# attention compressed branch rewritten: software-pipelined, inactive 32-key blocks skipped, softmax normalisation applied to O and importance after the sums (f32); K/V tile staging moved into the middl
# speedup vs baseline: 1.2661x; 1.0048x over previous
; #define LAS __attribute__((address_space(3)))
; #define MFMA32(a, b, c) __builtin_amdgcn_mfma_f32_32x32x16_bf16((a), (b), (c), 0, 0, 0)
; __device__ __forceinline__ void phase4_attn(const Args& a, LAS unsigned char* lds) {
;     ...
;                 const int lane = tid & 63, r = lane & 31, h = lane >> 5, ql = 32 * half + r, pos = 64 * t + ql, tok = b * 2048 + pos;
;                 comb[hkv][0] = zero16(); comb[hkv][1] = zero16();
;                 const float g0 = gates[(size_t)tok * 24 + head * 3 + 0], g1 = gates[(size_t)tok * 24 + head * 3 + 1], g2 = gates[(size_t)tok * 24 + head * 3 + 2];
;                 __syncthreads();
;                 {
;                     const bf16_t* kc = kcmp + (size_t)bh * 128 * 64; const bf16_t* vc = vcmpT + (size_t)bh * 64 * 128;
; #pragma unroll
;                     for (int i = 0; i < 2; ++i) { const int c = tid + 512 * i;
;                         const u32x4 kv = *(const u32x4*)(kc + (size_t)c * 8);
;                         *(LAS u32x4*)(lds + A_CMPK + (c >> 3) * A_KSTR + (c & 7) * 16) = kv;
;                         const u32x4 vv = *(const u32x4*)(vc + (size_t)c * 8);
;                         LAS unsigned char* vp = lds + A_CMPV + (c >> 4) * A_CVSTR + (c & 15) * 16;
;                         *(LAS u32x2*)vp = (u32x2){vv.x, vv.y}; *(LAS u32x2*)(vp + 8) = (u32x2){vv.z, vv.w}; }
;                 }
;                 bf16x8_t qf[4];
; #pragma unroll
;                 for (int ks = 0; ks < 4; ++ks) qf[ks] = __builtin_nontemporal_load((const bf16x8_t*)(qn + (size_t)tok * 512 + head * 64 + 16 * ks + 8 * h));
;                 __syncthreads();
;                 {
;                     f32x16 s4[4];
; #pragma unroll
;                     for (int mt = 0; mt < 4; ++mt) { s4[mt] = zero16();
; #pragma unroll
;                         for (int ks = 0; ks < 4; ++ks) { const bf16x8_t ka = *(const LAS bf16x8_t*)(lds + A_CMPK + (32 * mt + r) * A_KSTR + 32 * ks + 16 * h); s4[mt] = MFMA32(ka, qf[ks], s4[mt]); } }
;                     const int clim = (pos - 31 - 64 * h) >> 4;
.LBB0_715:
	s_and_b64 s[0:1], s[64:65], exec
	v_readlane_b32 s0, v254, 29
	v_readlane_b32 s1, v254, 30
	v_mov_b32_e32 v152, v184
	s_cselect_b32 s38, s0, s1
	s_lshl_b32 s24, s38, 6
	s_waitcnt vmcnt(0)
	v_and_b32_e32 v100, 31, v152
	v_or_b32_e32 v98, s79, v100
	v_or_b32_e32 v154, s24, v98
	v_or_b32_e32 v4, s39, v154
	v_mad_i64_i32 v[0:1], s[4:5], v4, s83, v[116:117]
	global_load_dwordx3 v[112:114], v[0:1], off
	v_lshlrev_b32_e32 v0, 4, v152
	v_ashrrev_i32_e32 v153, 31, v152
	v_readlane_b32 s6, v254, 39
	v_and_b32_e32 v1, 0x70, v0
	v_and_b32_e32 v0, 0xf0, v0
	v_lshlrev_b64 v[10:11], 4, v[152:153]
	v_readlane_b32 s7, v254, 40
	v_add_u32_e32 v6, s85, v1
	v_add_u32_e32 v8, s86, v0
	v_lshl_add_u64 v[0:1], s[6:7], 0, v[10:11]
	s_waitcnt lgkmcnt(0)
	s_barrier
	v_readlane_b32 s8, v254, 31
	v_readlane_b32 s9, v254, 32
	global_load_dwordx4 v[16:19], v[0:1], off
	v_add_u32_e32 v14, 0x200, v152
	v_ashrrev_i32_e32 v15, 31, v14
	v_lshlrev_b64 v[12:13], 4, v[14:15]
	v_lshl_add_u64 v[36:37], s[8:9], 0, v[10:11]
	global_load_dwordx4 v[20:23], v[36:37], off
	v_lshl_add_u64 v[36:37], s[6:7], 0, v[12:13]
	global_load_dwordx4 v[24:27], v[36:37], off
	v_lshl_add_u64 v[36:37], s[8:9], 0, v[12:13]
	global_load_dwordx4 v[28:31], v[36:37], off
	v_readlane_b32 s4, v254, 24
	v_readlane_b32 s5, v254, 25
	v_ashrrev_i32_e32 v5, 31, v4
	v_bfe_u32 v101, v152, 5, 1
	v_lshlrev_b64 v[72:73], 10, v[4:5]
	v_lshlrev_b32_e32 v118, 4, v101
	v_lshl_add_u64 v[0:1], s[4:5], 0, v[72:73]
	v_lshl_add_u64 v[4:5], v[0:1], 0, v[118:119]
	global_load_dwordx4 v[0:3], v[4:5], off nt
	global_load_dwordx4 v[74:77], v[4:5], off offset:32 nt
	global_load_dwordx4 v[68:71], v[4:5], off offset:64 nt
	global_load_dwordx4 v[64:67], v[4:5], off offset:96 nt
	v_ashrrev_i32_e32 v99, 3, v152
	v_ashrrev_i32_e32 v7, 4, v152
	v_mul_u32_u24_e32 v153, 0x90, v100
	v_add3_u32 v82, s85, v118, v153
	v_mad_u32_u24 v32, v99, s87, v6
	v_mad_u32_u24 v33, v7, s94, v8
	v_add_u32_e32 v35, 0x2100, v33
	s_cmp_gt_u32 s38, 15
	s_cselect_b64 s[0:1], -1, 0
	s_cmp_lt_u32 s38, 16
	s_mov_b64 s[2:3], -1
	s_cselect_b64 s[62:63], -1, 0
	s_waitcnt vmcnt(7)
	ds_write_b128 v32, v[16:19]
	s_waitcnt vmcnt(6)
	ds_write2_b64 v33, v[20:21], v[22:23] offset1:1
	s_waitcnt vmcnt(5)
	ds_write_b128 v32, v[24:27] offset:9216
	s_waitcnt vmcnt(4)
	ds_write2_b64 v35, v[28:29], v[30:31] offset1:1
	s_waitcnt lgkmcnt(0)
	s_barrier
	s_waitcnt vmcnt(0)
	v_mov_b32_e32 v84, v0
	v_mov_b32_e32 v85, v1
	v_mov_b32_e32 v86, v2
	v_mov_b32_e32 v87, v3
	v_lshlrev_b32_e32 v155, 2, v101
	v_lshlrev_b32_e32 v156, 3, v101
	v_mul_u32_u24_e32 v157, 0x108, v100
	v_add3_u32 v244, s86, v156, v157
	v_add_u32_e32 v245, 0x2000, v244
	v_lshlrev_b32_e32 v239, 4, v155
	v_sub_u32_e32 v236, v154, v239
	v_subrev_u32_e32 v236, 31, v236
	v_ashrrev_i32_e32 v236, 4, v236
	v_cmp_lt_i32_e32 vcc, v185, v188
	s_nop 1
	v_cndmask_b32_e32 v239, v115, v185, vcc
	v_lshlrev_b32_e32 v193, 2, v239
	v_mov_b32_e32 v0, 0
	v_mov_b32_e32 v1, 0
	v_mov_b32_e32 v2, 0
	v_mov_b32_e32 v3, 0
	v_mov_b32_e32 v4, 0
	v_mov_b32_e32 v5, 0
	v_mov_b32_e32 v6, 0
	v_mov_b32_e32 v7, 0
	v_mov_b32_e32 v8, 0
	v_mov_b32_e32 v9, 0
	v_mov_b32_e32 v10, 0
	v_mov_b32_e32 v11, 0
	v_mov_b32_e32 v12, 0
	v_mov_b32_e32 v13, 0
	v_mov_b32_e32 v14, 0
	v_mov_b32_e32 v15, 0
	v_mov_b32_e32 v16, 0
	v_mov_b32_e32 v17, 0
	v_mov_b32_e32 v18, 0
	v_mov_b32_e32 v19, 0
	v_mov_b32_e32 v20, 0
	v_mov_b32_e32 v21, 0
	v_mov_b32_e32 v22, 0
	v_mov_b32_e32 v23, 0
	v_mov_b32_e32 v24, 0
	v_mov_b32_e32 v25, 0
	v_mov_b32_e32 v26, 0
	v_mov_b32_e32 v27, 0
	v_mov_b32_e32 v28, 0
	v_mov_b32_e32 v29, 0
	v_mov_b32_e32 v30, 0
	v_mov_b32_e32 v31, 0
	v_mov_b32_e32 v160, 0
	v_mov_b32_e32 v161, 0
	v_mov_b32_e32 v162, 0
	v_mov_b32_e32 v163, 0
	v_mov_b32_e32 v164, 0
	v_mov_b32_e32 v165, 0
	v_mov_b32_e32 v166, 0
	v_mov_b32_e32 v167, 0
	v_mov_b32_e32 v168, 0
	v_mov_b32_e32 v169, 0
	v_mov_b32_e32 v170, 0
	v_mov_b32_e32 v171, 0
	v_mov_b32_e32 v172, 0
	v_mov_b32_e32 v173, 0
	v_mov_b32_e32 v174, 0
	v_mov_b32_e32 v175, 0
	v_mov_b32_e32 v176, 0
	v_mov_b32_e32 v177, 0
	v_mov_b32_e32 v178, 0
	v_mov_b32_e32 v179, 0
	v_mov_b32_e32 v180, 0
	v_mov_b32_e32 v181, 0
	v_mov_b32_e32 v182, 0
	v_mov_b32_e32 v183, 0
	v_mov_b32_e32 v246, 0
	v_mov_b32_e32 v247, 0
	v_mov_b32_e32 v248, 0
	v_mov_b32_e32 v249, 0
	v_mov_b32_e32 v250, 0
	v_mov_b32_e32 v251, 0
	v_mov_b32_e32 v252, 0
	v_mov_b32_e32 v253, 0
	v_readfirstlane_b32 s7, v152
	s_bfe_u32 s7, s7, 0x10006
	s_lshl_b32 s9, s38, 1
	s_add_i32 s7, s7, s9
	s_lshr_b32 s7, s7, 4
	s_cmp_eq_u32 s7, 0
	s_cbranch_scc1 .Lc0_n1
	s_cmp_eq_u32 s7, 1
	s_cbranch_scc1 .Lc0_n2
	s_cmp_eq_u32 s7, 2
	s_cbranch_scc1 .Lc0_n3
	s_branch .Lc0_n4
; #define LAS __attribute__((address_space(3)))
; __device__ __forceinline__ void phase4_attn(const Args& a, LAS unsigned char* lds) {
;     ...
;                     for (int mt = 0; mt < 4; ++mt) { s4[mt] = zero16();
; #pragma unroll
;                         for (int ks = 0; ks < 4; ++ks) { const bf16x8_t ka = *(const LAS bf16x8_t*)(lds + A_CMPK + (32 * mt + r) * A_KSTR + 32 * ks + 16 * h); s4[mt] = MFMA32(ka, qf[ks], s4[mt]); } }
;                     const int clim = (pos - 31 - 64 * h) >> 4;
;                     float ls = 0.f;
; #pragma unroll
;                     for (int mt = 0; mt < 4; ++mt)
; #pragma unroll
;                         for (int i = 0; i < 16; ++i) { const int ci = 32 * mt + (i & 3) + 8 * (i >> 2);
;                             const float p = (ci <= clim) ? ex2(s4[mt][i]) : 0.f; s4[mt][i] = p; ls += p; }
;                     ls += __shfl_xor(ls, 32);
;                     const float inv = 1.f / fmaxf(ls, 1e-20f);
; #pragma unroll
;                     for (int mt = 0; mt < 4; ++mt) s4[mt] *= inv;
;                     if (t >= 16) {
;                         float oprev = 0.f;
; #pragma unroll
;                         for (int idx = 0; idx < 16; ++idx) {
;                             const int mt = idx >> 2, ap = idx & 3;
;                             const float tail = 0.5f * s4[mt][4 * ap + 3];
;                             const float ot = __shfl_xor(tail, 32);
;                             const float inner = s4[mt][4 * ap] + s4[mt][4 * ap + 1] + s4[mt][4 * ap + 2] + tail;
;                             const float prev = h ? ot : oprev;
;                             oprev = ot;
;                             IMP[(g * 64 + ql) * A_IMPSTR + 8 * mt + 2 * ap + h] = inner + prev;
;                         }
;                     }
;                     f32x16 oc[2]; oc[0] = zero16(); oc[1] = zero16();
; #pragma unroll
;                     for (int mt = 0; mt < 4; ++mt)
; #pragma unroll
;                         for (int s = 0; s < 2; ++s) {
;                             const bf16x8_t pf = pack8(s4[mt], 8 * s);
; #pragma unroll
;                             for (int dt = 0; dt < 2; ++dt) {
;                                 const LAS unsigned char* vp = lds + A_CMPV + (32 * dt + r) * A_CVSTR + (32 * mt + 16 * s + 4 * h) * 2;
;                                 const s16x4_t lo = *(const LAS s16x4_t*)vp, hi = *(const LAS s16x4_t*)(vp + 16);
.Lc0_n1:
	ds_read_b128 v[200:203], v82 offset:0
	ds_read_b128 v[204:207], v82 offset:32
	ds_read_b128 v[208:211], v82 offset:64
	ds_read_b128 v[212:215], v82 offset:96
	ds_read2_b64 v[216:219], v244 offset0:0 offset1:2
	ds_read2_b64 v[220:223], v245 offset0:32 offset1:34
	ds_read2_b64 v[224:227], v244 offset0:4 offset1:6
	ds_read2_b64 v[228:231], v245 offset0:36 offset1:38
	v_subrev_u32_e32 v237, 0, v236
	s_waitcnt lgkmcnt(7)
	v_mfma_f32_32x32x16_bf16 v[32:47], v[200:203], v[84:87], 0
	s_waitcnt lgkmcnt(6)
	v_mfma_f32_32x32x16_bf16 v[32:47], v[204:207], v[74:77], v[32:47]
	s_waitcnt lgkmcnt(5)
	v_mfma_f32_32x32x16_bf16 v[32:47], v[208:211], v[68:71], v[32:47]
	s_waitcnt lgkmcnt(4)
	v_mfma_f32_32x32x16_bf16 v[32:47], v[212:215], v[64:67], v[32:47]
	s_nop 7
	s_nop 3
	v_cmp_le_i32_e64 s[10:11], 0, v237
	v_cmp_le_i32_e64 s[42:43], 1, v237
	v_exp_f32_e32 v32, v32
	v_exp_f32_e32 v33, v33
	v_cmp_le_i32_e64 s[44:45], 2, v237
	v_cmp_le_i32_e64 s[46:47], 3, v237
	v_exp_f32_e32 v34, v34
	v_exp_f32_e32 v35, v35
	v_cndmask_b32_e64 v32, 0, v32, s[10:11]
	v_cndmask_b32_e64 v33, 0, v33, s[42:43]
	v_mov_b32_e32 v232, v32
	v_mov_b32_e32 v233, v33
	v_cvt_pk_bf16_f32 v88, v32, v33
	v_cmp_le_i32_e64 s[10:11], 8, v237
	v_cmp_le_i32_e64 s[42:43], 9, v237
	v_exp_f32_e32 v36, v36
	v_exp_f32_e32 v37, v37
	v_cndmask_b32_e64 v34, 0, v34, s[44:45]
	v_cndmask_b32_e64 v35, 0, v35, s[46:47]
	v_add_f32_e32 v232, v232, v34
	v_add_f32_e32 v233, v233, v35
	v_cvt_pk_bf16_f32 v89, v34, v35
	v_cmp_le_i32_e64 s[44:45], 10, v237
	v_cmp_le_i32_e64 s[46:47], 11, v237
	v_exp_f32_e32 v38, v38
	v_exp_f32_e32 v39, v39
	v_cndmask_b32_e64 v36, 0, v36, s[10:11]
	v_cndmask_b32_e64 v37, 0, v37, s[42:43]
	v_add_f32_e32 v232, v232, v36
	v_add_f32_e32 v233, v233, v37
	v_cvt_pk_bf16_f32 v90, v36, v37
	v_cndmask_b32_e64 v38, 0, v38, s[44:45]
	v_cndmask_b32_e64 v39, 0, v39, s[46:47]
	v_add_f32_e32 v232, v232, v38
	v_add_f32_e32 v233, v233, v39
	v_cvt_pk_bf16_f32 v91, v38, v39
	v_cmp_le_i32_e64 s[10:11], 16, v237
	v_cmp_le_i32_e64 s[42:43], 17, v237
	v_exp_f32_e32 v40, v40
	v_exp_f32_e32 v41, v41
	v_cmp_le_i32_e64 s[44:45], 18, v237
	v_cmp_le_i32_e64 s[46:47], 19, v237
	v_exp_f32_e32 v42, v42
	v_exp_f32_e32 v43, v43
	v_cndmask_b32_e64 v40, 0, v40, s[10:11]
	v_cndmask_b32_e64 v41, 0, v41, s[42:43]
	v_add_f32_e32 v232, v232, v40
	v_add_f32_e32 v233, v233, v41
	v_cvt_pk_bf16_f32 v92, v40, v41
	s_waitcnt lgkmcnt(3)
	v_mfma_f32_32x32x16_bf16 v[0:15], v[216:219], v[88:91], v[0:15]
	v_cmp_le_i32_e64 s[10:11], 24, v237
	v_cmp_le_i32_e64 s[42:43], 25, v237
	v_exp_f32_e32 v44, v44
	v_exp_f32_e32 v45, v45
	v_cndmask_b32_e64 v42, 0, v42, s[44:45]
	v_cndmask_b32_e64 v43, 0, v43, s[46:47]
	v_add_f32_e32 v232, v232, v42
	v_add_f32_e32 v233, v233, v43
	v_cvt_pk_bf16_f32 v93, v42, v43
	s_waitcnt lgkmcnt(2)
	v_mfma_f32_32x32x16_bf16 v[16:31], v[220:223], v[88:91], v[16:31]
	v_cmp_le_i32_e64 s[44:45], 26, v237
	v_cmp_le_i32_e64 s[46:47], 27, v237
	v_exp_f32_e32 v46, v46
	v_exp_f32_e32 v47, v47
	v_cndmask_b32_e64 v44, 0, v44, s[10:11]
	v_cndmask_b32_e64 v45, 0, v45, s[42:43]
	v_add_f32_e32 v232, v232, v44
	v_add_f32_e32 v233, v233, v45
	v_cvt_pk_bf16_f32 v94, v44, v45
	v_cndmask_b32_e64 v46, 0, v46, s[44:45]
	v_cndmask_b32_e64 v47, 0, v47, s[46:47]
	v_add_f32_e32 v232, v232, v46
	v_add_f32_e32 v233, v233, v47
	v_cvt_pk_bf16_f32 v95, v46, v47
	s_nop 1
	s_waitcnt lgkmcnt(1)
	v_mfma_f32_32x32x16_bf16 v[0:15], v[224:227], v[92:95], v[0:15]
	s_waitcnt lgkmcnt(0)
	v_mfma_f32_32x32x16_bf16 v[16:31], v[228:231], v[92:95], v[16:31]
	s_branch .Lc0_fin
.Lc0_n2:
	ds_read_b128 v[200:203], v82 offset:0
	ds_read_b128 v[204:207], v82 offset:32
	ds_read_b128 v[208:211], v82 offset:64
	ds_read_b128 v[212:215], v82 offset:96
	ds_read2_b64 v[216:219], v244 offset0:0 offset1:2
	ds_read2_b64 v[220:223], v245 offset0:32 offset1:34
	ds_read2_b64 v[224:227], v244 offset0:4 offset1:6
	ds_read2_b64 v[228:231], v245 offset0:36 offset1:38
	v_subrev_u32_e32 v237, 0, v236
	v_subrev_u32_e32 v238, 32, v236
	s_waitcnt lgkmcnt(7)
	v_mfma_f32_32x32x16_bf16 v[32:47], v[200:203], v[84:87], 0
	ds_read_b128 v[200:203], v82 offset:4608
	s_waitcnt lgkmcnt(7)
	v_mfma_f32_32x32x16_bf16 v[32:47], v[204:207], v[74:77], v[32:47]
	ds_read_b128 v[204:207], v82 offset:4640
	s_waitcnt lgkmcnt(7)
	v_mfma_f32_32x32x16_bf16 v[32:47], v[208:211], v[68:71], v[32:47]
	ds_read_b128 v[208:211], v82 offset:4672
	s_waitcnt lgkmcnt(7)
	v_mfma_f32_32x32x16_bf16 v[32:47], v[212:215], v[64:67], v[32:47]
	ds_read_b128 v[212:215], v82 offset:4704
	s_nop 7
	s_nop 3
	s_waitcnt lgkmcnt(3)
	v_mfma_f32_32x32x16_bf16 v[48:63], v[200:203], v[84:87], 0
	v_cmp_le_i32_e64 s[10:11], 0, v237
	v_cmp_le_i32_e64 s[42:43], 1, v237
	v_exp_f32_e32 v32, v32
	v_exp_f32_e32 v33, v33
	s_waitcnt lgkmcnt(2)
	v_mfma_f32_32x32x16_bf16 v[48:63], v[204:207], v[74:77], v[48:63]
	v_cmp_le_i32_e64 s[44:45], 2, v237
	v_cmp_le_i32_e64 s[46:47], 3, v237
	v_exp_f32_e32 v34, v34
	v_exp_f32_e32 v35, v35
	v_cndmask_b32_e64 v32, 0, v32, s[10:11]
	v_cndmask_b32_e64 v33, 0, v33, s[42:43]
	v_mov_b32_e32 v232, v32
	v_mov_b32_e32 v233, v33
	v_cvt_pk_bf16_f32 v88, v32, v33
	v_cmp_le_i32_e64 s[10:11], 8, v237
	v_cmp_le_i32_e64 s[42:43], 9, v237
	v_exp_f32_e32 v36, v36
	v_exp_f32_e32 v37, v37
	v_cndmask_b32_e64 v34, 0, v34, s[44:45]
	v_cndmask_b32_e64 v35, 0, v35, s[46:47]
	v_add_f32_e32 v232, v232, v34
	v_add_f32_e32 v233, v233, v35
	v_cvt_pk_bf16_f32 v89, v34, v35
	v_cmp_le_i32_e64 s[44:45], 10, v237
	v_cmp_le_i32_e64 s[46:47], 11, v237
	v_exp_f32_e32 v38, v38
	v_exp_f32_e32 v39, v39
	v_cndmask_b32_e64 v36, 0, v36, s[10:11]
	v_cndmask_b32_e64 v37, 0, v37, s[42:43]
	v_add_f32_e32 v232, v232, v36
	v_add_f32_e32 v233, v233, v37
	v_cvt_pk_bf16_f32 v90, v36, v37
	v_cndmask_b32_e64 v38, 0, v38, s[44:45]
	v_cndmask_b32_e64 v39, 0, v39, s[46:47]
	v_add_f32_e32 v232, v232, v38
	v_add_f32_e32 v233, v233, v39
	v_cvt_pk_bf16_f32 v91, v38, v39
	s_waitcnt lgkmcnt(1)
; #define LAS __attribute__((address_space(3)))
; __device__ __forceinline__ void phase4_attn(const Args& a, LAS unsigned char* lds) {
;     ...
;                     for (int mt = 0; mt < 4; ++mt) { s4[mt] = zero16();
; #pragma unroll
;                         for (int ks = 0; ks < 4; ++ks) { const bf16x8_t ka = *(const LAS bf16x8_t*)(lds + A_CMPK + (32 * mt + r) * A_KSTR + 32 * ks + 16 * h); s4[mt] = MFMA32(ka, qf[ks], s4[mt]); } }
;                     const int clim = (pos - 31 - 64 * h) >> 4;
;                     float ls = 0.f;
; #pragma unroll
;                     for (int mt = 0; mt < 4; ++mt)
; #pragma unroll
;                         for (int i = 0; i < 16; ++i) { const int ci = 32 * mt + (i & 3) + 8 * (i >> 2);
;                             const float p = (ci <= clim) ? ex2(s4[mt][i]) : 0.f; s4[mt][i] = p; ls += p; }
;                     ls += __shfl_xor(ls, 32);
;                     const float inv = 1.f / fmaxf(ls, 1e-20f);
; #pragma unroll
;                     for (int mt = 0; mt < 4; ++mt) s4[mt] *= inv;
;                     if (t >= 16) {
;                         float oprev = 0.f;
; #pragma unroll
;                         for (int idx = 0; idx < 16; ++idx) {
;                             const int mt = idx >> 2, ap = idx & 3;
;                             const float tail = 0.5f * s4[mt][4 * ap + 3];
;                             const float ot = __shfl_xor(tail, 32);
;                             const float inner = s4[mt][4 * ap] + s4[mt][4 * ap + 1] + s4[mt][4 * ap + 2] + tail;
;                             const float prev = h ? ot : oprev;
;                             oprev = ot;
;                             IMP[(g * 64 + ql) * A_IMPSTR + 8 * mt + 2 * ap + h] = inner + prev;
;                         }
;                     }
;                     f32x16 oc[2]; oc[0] = zero16(); oc[1] = zero16();
; #pragma unroll
;                     for (int mt = 0; mt < 4; ++mt)
; #pragma unroll
;                         for (int s = 0; s < 2; ++s) {
;                             const bf16x8_t pf = pack8(s4[mt], 8 * s);
; #pragma unroll
;                             for (int dt = 0; dt < 2; ++dt) {
;                                 const LAS unsigned char* vp = lds + A_CMPV + (32 * dt + r) * A_CVSTR + (32 * mt + 16 * s + 4 * h) * 2;
;                                 const s16x4_t lo = *(const LAS s16x4_t*)vp, hi = *(const LAS s16x4_t*)(vp + 16);
	v_mfma_f32_32x32x16_bf16 v[48:63], v[208:211], v[68:71], v[48:63]
	v_cmp_le_i32_e64 s[10:11], 16, v237
	v_cmp_le_i32_e64 s[42:43], 17, v237
	v_exp_f32_e32 v40, v40
	v_exp_f32_e32 v41, v41
	s_waitcnt lgkmcnt(0)
	v_mfma_f32_32x32x16_bf16 v[48:63], v[212:215], v[64:67], v[48:63]
	v_cmp_le_i32_e64 s[44:45], 18, v237
	v_cmp_le_i32_e64 s[46:47], 19, v237
	v_exp_f32_e32 v42, v42
	v_exp_f32_e32 v43, v43
	v_cndmask_b32_e64 v40, 0, v40, s[10:11]
	v_cndmask_b32_e64 v41, 0, v41, s[42:43]
	v_add_f32_e32 v232, v232, v40
	v_add_f32_e32 v233, v233, v41
	v_cvt_pk_bf16_f32 v92, v40, v41
	v_mfma_f32_32x32x16_bf16 v[0:15], v[216:219], v[88:91], v[0:15]
	ds_read2_b64 v[216:219], v244 offset0:8 offset1:10
	v_cmp_le_i32_e64 s[10:11], 24, v237
	v_cmp_le_i32_e64 s[42:43], 25, v237
	v_exp_f32_e32 v44, v44
	v_exp_f32_e32 v45, v45
	v_cndmask_b32_e64 v42, 0, v42, s[44:45]
	v_cndmask_b32_e64 v43, 0, v43, s[46:47]
	v_add_f32_e32 v232, v232, v42
	v_add_f32_e32 v233, v233, v43
	v_cvt_pk_bf16_f32 v93, v42, v43
	v_mfma_f32_32x32x16_bf16 v[16:31], v[220:223], v[88:91], v[16:31]
	ds_read2_b64 v[220:223], v245 offset0:40 offset1:42
	v_cmp_le_i32_e64 s[44:45], 26, v237
	v_cmp_le_i32_e64 s[46:47], 27, v237
	v_exp_f32_e32 v46, v46
	v_exp_f32_e32 v47, v47
	v_cndmask_b32_e64 v44, 0, v44, s[10:11]
	v_cndmask_b32_e64 v45, 0, v45, s[42:43]
	v_add_f32_e32 v232, v232, v44
	v_add_f32_e32 v233, v233, v45
	v_cvt_pk_bf16_f32 v94, v44, v45
	v_cndmask_b32_e64 v46, 0, v46, s[44:45]
	v_cndmask_b32_e64 v47, 0, v47, s[46:47]
	v_add_f32_e32 v232, v232, v46
	v_add_f32_e32 v233, v233, v47
	v_cvt_pk_bf16_f32 v95, v46, v47
	v_cmp_le_i32_e64 s[10:11], 0, v238
	v_cmp_le_i32_e64 s[42:43], 1, v238
	v_exp_f32_e32 v48, v48
	v_exp_f32_e32 v49, v49
	v_cmp_le_i32_e64 s[44:45], 2, v238
	v_cmp_le_i32_e64 s[46:47], 3, v238
	v_exp_f32_e32 v50, v50
	v_exp_f32_e32 v51, v51
	v_cndmask_b32_e64 v48, 0, v48, s[10:11]
	v_cndmask_b32_e64 v49, 0, v49, s[42:43]
	v_add_f32_e32 v232, v232, v48
	v_add_f32_e32 v233, v233, v49
	v_cvt_pk_bf16_f32 v88, v48, v49
	v_mfma_f32_32x32x16_bf16 v[0:15], v[224:227], v[92:95], v[0:15]
	ds_read2_b64 v[224:227], v244 offset0:12 offset1:14
	v_cmp_le_i32_e64 s[10:11], 8, v238
	v_cmp_le_i32_e64 s[42:43], 9, v238
	v_exp_f32_e32 v52, v52
	v_exp_f32_e32 v53, v53
	v_cndmask_b32_e64 v50, 0, v50, s[44:45]
	v_cndmask_b32_e64 v51, 0, v51, s[46:47]
	v_add_f32_e32 v232, v232, v50
	v_add_f32_e32 v233, v233, v51
	v_cvt_pk_bf16_f32 v89, v50, v51
	v_mfma_f32_32x32x16_bf16 v[16:31], v[228:231], v[92:95], v[16:31]
	ds_read2_b64 v[228:231], v245 offset0:44 offset1:46
	v_cmp_le_i32_e64 s[44:45], 10, v238
	v_cmp_le_i32_e64 s[46:47], 11, v238
	v_exp_f32_e32 v54, v54
	v_exp_f32_e32 v55, v55
	v_cndmask_b32_e64 v52, 0, v52, s[10:11]
	v_cndmask_b32_e64 v53, 0, v53, s[42:43]
	v_add_f32_e32 v232, v232, v52
	v_add_f32_e32 v233, v233, v53
	v_cvt_pk_bf16_f32 v90, v52, v53
	v_cndmask_b32_e64 v54, 0, v54, s[44:45]
	v_cndmask_b32_e64 v55, 0, v55, s[46:47]
	v_add_f32_e32 v232, v232, v54
	v_add_f32_e32 v233, v233, v55
	v_cvt_pk_bf16_f32 v91, v54, v55
	v_cmp_le_i32_e64 s[10:11], 16, v238
	v_cmp_le_i32_e64 s[42:43], 17, v238
	v_exp_f32_e32 v56, v56
	v_exp_f32_e32 v57, v57
	v_cmp_le_i32_e64 s[44:45], 18, v238
	v_cmp_le_i32_e64 s[46:47], 19, v238
	v_exp_f32_e32 v58, v58
	v_exp_f32_e32 v59, v59
	v_cndmask_b32_e64 v56, 0, v56, s[10:11]
	v_cndmask_b32_e64 v57, 0, v57, s[42:43]
	v_add_f32_e32 v232, v232, v56
	v_add_f32_e32 v233, v233, v57
	v_cvt_pk_bf16_f32 v92, v56, v57
	s_waitcnt lgkmcnt(3)
	v_mfma_f32_32x32x16_bf16 v[0:15], v[216:219], v[88:91], v[0:15]
	v_cmp_le_i32_e64 s[10:11], 24, v238
	v_cmp_le_i32_e64 s[42:43], 25, v238
	v_exp_f32_e32 v60, v60
	v_exp_f32_e32 v61, v61
	v_cndmask_b32_e64 v58, 0, v58, s[44:45]
	v_cndmask_b32_e64 v59, 0, v59, s[46:47]
	v_add_f32_e32 v232, v232, v58
	v_add_f32_e32 v233, v233, v59
	v_cvt_pk_bf16_f32 v93, v58, v59
	s_waitcnt lgkmcnt(2)
	v_mfma_f32_32x32x16_bf16 v[16:31], v[220:223], v[88:91], v[16:31]
	v_cmp_le_i32_e64 s[44:45], 26, v238
	v_cmp_le_i32_e64 s[46:47], 27, v238
	v_exp_f32_e32 v62, v62
	v_exp_f32_e32 v63, v63
	v_cndmask_b32_e64 v60, 0, v60, s[10:11]
	v_cndmask_b32_e64 v61, 0, v61, s[42:43]
	v_add_f32_e32 v232, v232, v60
	v_add_f32_e32 v233, v233, v61
	v_cvt_pk_bf16_f32 v94, v60, v61
	v_cndmask_b32_e64 v62, 0, v62, s[44:45]
	v_cndmask_b32_e64 v63, 0, v63, s[46:47]
	v_add_f32_e32 v232, v232, v62
	v_add_f32_e32 v233, v233, v63
	v_cvt_pk_bf16_f32 v95, v62, v63
	s_nop 1
	s_waitcnt lgkmcnt(1)
	v_mfma_f32_32x32x16_bf16 v[0:15], v[224:227], v[92:95], v[0:15]
	s_waitcnt lgkmcnt(0)
	v_mfma_f32_32x32x16_bf16 v[16:31], v[228:231], v[92:95], v[16:31]
	s_branch .Lc0_fin
; #define LAS __attribute__((address_space(3)))
; __device__ __forceinline__ void phase4_attn(const Args& a, LAS unsigned char* lds) {
;     ...
;                     for (int mt = 0; mt < 4; ++mt) { s4[mt] = zero16();
; #pragma unroll
;                         for (int ks = 0; ks < 4; ++ks) { const bf16x8_t ka = *(const LAS bf16x8_t*)(lds + A_CMPK + (32 * mt + r) * A_KSTR + 32 * ks + 16 * h); s4[mt] = MFMA32(ka, qf[ks], s4[mt]); } }
;                     const int clim = (pos - 31 - 64 * h) >> 4;
;                     float ls = 0.f;
; #pragma unroll
;                     for (int mt = 0; mt < 4; ++mt)
; #pragma unroll
;                         for (int i = 0; i < 16; ++i) { const int ci = 32 * mt + (i & 3) + 8 * (i >> 2);
;                             const float p = (ci <= clim) ? ex2(s4[mt][i]) : 0.f; s4[mt][i] = p; ls += p; }
;                     ls += __shfl_xor(ls, 32);
;                     const float inv = 1.f / fmaxf(ls, 1e-20f);
; #pragma unroll
;                     for (int mt = 0; mt < 4; ++mt) s4[mt] *= inv;
;                     if (t >= 16) {
;                         float oprev = 0.f;
; #pragma unroll
;                         for (int idx = 0; idx < 16; ++idx) {
;                             const int mt = idx >> 2, ap = idx & 3;
;                             const float tail = 0.5f * s4[mt][4 * ap + 3];
;                             const float ot = __shfl_xor(tail, 32);
;                             const float inner = s4[mt][4 * ap] + s4[mt][4 * ap + 1] + s4[mt][4 * ap + 2] + tail;
;                             const float prev = h ? ot : oprev;
;                             oprev = ot;
;                             IMP[(g * 64 + ql) * A_IMPSTR + 8 * mt + 2 * ap + h] = inner + prev;
;                         }
;                     }
;                     f32x16 oc[2]; oc[0] = zero16(); oc[1] = zero16();
; #pragma unroll
;                     for (int mt = 0; mt < 4; ++mt)
; #pragma unroll
;                         for (int s = 0; s < 2; ++s) {
;                             const bf16x8_t pf = pack8(s4[mt], 8 * s);
; #pragma unroll
;                             for (int dt = 0; dt < 2; ++dt) {
;                                 const LAS unsigned char* vp = lds + A_CMPV + (32 * dt + r) * A_CVSTR + (32 * mt + 16 * s + 4 * h) * 2;
;                                 const s16x4_t lo = *(const LAS s16x4_t*)vp, hi = *(const LAS s16x4_t*)(vp + 16);
.Lc0_n3:
	ds_read_b128 v[200:203], v82 offset:0
	ds_read_b128 v[204:207], v82 offset:32
	ds_read_b128 v[208:211], v82 offset:64
	ds_read_b128 v[212:215], v82 offset:96
	ds_read2_b64 v[216:219], v244 offset0:0 offset1:2
	ds_read2_b64 v[220:223], v245 offset0:32 offset1:34
	ds_read2_b64 v[224:227], v244 offset0:4 offset1:6
	ds_read2_b64 v[228:231], v245 offset0:36 offset1:38
	v_subrev_u32_e32 v237, 32, v236
	v_subrev_u32_e32 v238, 64, v236
	s_waitcnt lgkmcnt(7)
	v_mfma_f32_32x32x16_bf16 v[32:47], v[200:203], v[84:87], 0
	ds_read_b128 v[200:203], v82 offset:4608
	s_waitcnt lgkmcnt(7)
	v_mfma_f32_32x32x16_bf16 v[32:47], v[204:207], v[74:77], v[32:47]
	ds_read_b128 v[204:207], v82 offset:4640
	s_waitcnt lgkmcnt(7)
	v_mfma_f32_32x32x16_bf16 v[32:47], v[208:211], v[68:71], v[32:47]
	ds_read_b128 v[208:211], v82 offset:4672
	s_waitcnt lgkmcnt(7)
	v_mfma_f32_32x32x16_bf16 v[32:47], v[212:215], v[64:67], v[32:47]
	ds_read_b128 v[212:215], v82 offset:4704
	s_nop 7
	s_nop 3
	s_waitcnt lgkmcnt(3)
	v_mfma_f32_32x32x16_bf16 v[48:63], v[200:203], v[84:87], 0
	ds_read_b128 v[200:203], v82 offset:9216
	v_exp_f32_e32 v32, v32
	v_exp_f32_e32 v33, v33
	s_waitcnt lgkmcnt(3)
	v_mfma_f32_32x32x16_bf16 v[48:63], v[204:207], v[74:77], v[48:63]
	ds_read_b128 v[204:207], v82 offset:9248
	v_exp_f32_e32 v34, v34
	v_exp_f32_e32 v35, v35
	v_mov_b32_e32 v232, v32
	v_mov_b32_e32 v233, v33
	v_cvt_pk_bf16_f32 v88, v32, v33
	v_exp_f32_e32 v36, v36
	v_exp_f32_e32 v37, v37
	v_add_f32_e32 v232, v232, v34
	v_add_f32_e32 v233, v233, v35
	v_cvt_pk_bf16_f32 v89, v34, v35
	v_mul_f32_e32 v176, 0.5, v35
	v_add_f32_e32 v160, v32, v33
	v_add_f32_e32 v160, v160, v34
	v_add_f32_e32 v160, v160, v176
	v_exp_f32_e32 v38, v38
	v_exp_f32_e32 v39, v39
	v_add_f32_e32 v232, v232, v36
	v_add_f32_e32 v233, v233, v37
	v_cvt_pk_bf16_f32 v90, v36, v37
	v_add_f32_e32 v232, v232, v38
	v_add_f32_e32 v233, v233, v39
	v_cvt_pk_bf16_f32 v91, v38, v39
	v_mul_f32_e32 v177, 0.5, v39
	v_add_f32_e32 v161, v36, v37
	v_add_f32_e32 v161, v161, v38
	v_add_f32_e32 v161, v161, v177
	s_waitcnt lgkmcnt(3)
	v_mfma_f32_32x32x16_bf16 v[48:63], v[208:211], v[68:71], v[48:63]
	ds_read_b128 v[208:211], v82 offset:9280
	v_exp_f32_e32 v40, v40
	v_exp_f32_e32 v41, v41
	s_waitcnt lgkmcnt(3)
	v_mfma_f32_32x32x16_bf16 v[48:63], v[212:215], v[64:67], v[48:63]
	ds_read_b128 v[212:215], v82 offset:9312
	v_exp_f32_e32 v42, v42
	v_exp_f32_e32 v43, v43
	v_add_f32_e32 v232, v232, v40
	v_add_f32_e32 v233, v233, v41
	v_cvt_pk_bf16_f32 v92, v40, v41
	v_mfma_f32_32x32x16_bf16 v[0:15], v[216:219], v[88:91], v[0:15]
	ds_read2_b64 v[216:219], v244 offset0:8 offset1:10
	v_exp_f32_e32 v44, v44
	v_exp_f32_e32 v45, v45
	v_add_f32_e32 v232, v232, v42
	v_add_f32_e32 v233, v233, v43
	v_cvt_pk_bf16_f32 v93, v42, v43
	v_mul_f32_e32 v178, 0.5, v43
	v_add_f32_e32 v162, v40, v41
	v_add_f32_e32 v162, v162, v42
	v_add_f32_e32 v162, v162, v178
	v_mfma_f32_32x32x16_bf16 v[16:31], v[220:223], v[88:91], v[16:31]
	ds_read2_b64 v[220:223], v245 offset0:40 offset1:42
	v_exp_f32_e32 v46, v46
	v_exp_f32_e32 v47, v47
	v_add_f32_e32 v232, v232, v44
	v_add_f32_e32 v233, v233, v45
	v_cvt_pk_bf16_f32 v94, v44, v45
	v_add_f32_e32 v232, v232, v46
	v_add_f32_e32 v233, v233, v47
	v_cvt_pk_bf16_f32 v95, v46, v47
	v_mul_f32_e32 v179, 0.5, v47
	v_add_f32_e32 v163, v44, v45
	v_add_f32_e32 v163, v163, v46
	v_add_f32_e32 v163, v163, v179
	s_waitcnt lgkmcnt(5)
	v_mfma_f32_32x32x16_bf16 v[32:47], v[200:203], v[84:87], 0
	v_cmp_le_i32_e64 s[10:11], 0, v237
	v_cmp_le_i32_e64 s[42:43], 1, v237
	v_exp_f32_e32 v48, v48
	v_exp_f32_e32 v49, v49
	s_waitcnt lgkmcnt(4)
	v_mfma_f32_32x32x16_bf16 v[32:47], v[204:207], v[74:77], v[32:47]
	v_cmp_le_i32_e64 s[44:45], 2, v237
	v_cmp_le_i32_e64 s[46:47], 3, v237
	v_exp_f32_e32 v50, v50
	v_exp_f32_e32 v51, v51
	v_cndmask_b32_e64 v48, 0, v48, s[10:11]
	v_cndmask_b32_e64 v49, 0, v49, s[42:43]
	v_add_f32_e32 v232, v232, v48
	v_add_f32_e32 v233, v233, v49
	v_cvt_pk_bf16_f32 v88, v48, v49
	v_mfma_f32_32x32x16_bf16 v[0:15], v[224:227], v[92:95], v[0:15]
	ds_read2_b64 v[224:227], v244 offset0:12 offset1:14
	v_cmp_le_i32_e64 s[10:11], 8, v237
	v_cmp_le_i32_e64 s[42:43], 9, v237
	v_exp_f32_e32 v52, v52
	v_exp_f32_e32 v53, v53
	v_cndmask_b32_e64 v50, 0, v50, s[44:45]
	v_cndmask_b32_e64 v51, 0, v51, s[46:47]
	v_add_f32_e32 v232, v232, v50
	v_add_f32_e32 v233, v233, v51
	v_cvt_pk_bf16_f32 v89, v50, v51
	v_mul_f32_e32 v180, 0.5, v51
	v_add_f32_e32 v164, v48, v49
	v_add_f32_e32 v164, v164, v50
	v_add_f32_e32 v164, v164, v180
	v_mfma_f32_32x32x16_bf16 v[16:31], v[228:231], v[92:95], v[16:31]
	ds_read2_b64 v[228:231], v245 offset0:44 offset1:46
	v_cmp_le_i32_e64 s[44:45], 10, v237
	v_cmp_le_i32_e64 s[46:47], 11, v237
	v_exp_f32_e32 v54, v54
	v_exp_f32_e32 v55, v55
	v_cndmask_b32_e64 v52, 0, v52, s[10:11]
	v_cndmask_b32_e64 v53, 0, v53, s[42:43]
	v_add_f32_e32 v232, v232, v52
	v_add_f32_e32 v233, v233, v53
	v_cvt_pk_bf16_f32 v90, v52, v53
	v_cndmask_b32_e64 v54, 0, v54, s[44:45]
	v_cndmask_b32_e64 v55, 0, v55, s[46:47]
	v_add_f32_e32 v232, v232, v54
	v_add_f32_e32 v233, v233, v55
	v_cvt_pk_bf16_f32 v91, v54, v55
	v_mul_f32_e32 v181, 0.5, v55
	v_add_f32_e32 v165, v52, v53
	v_add_f32_e32 v165, v165, v54
	v_add_f32_e32 v165, v165, v181
	s_waitcnt lgkmcnt(5)
	v_mfma_f32_32x32x16_bf16 v[32:47], v[208:211], v[68:71], v[32:47]
	v_cmp_le_i32_e64 s[10:11], 16, v237
	v_cmp_le_i32_e64 s[42:43], 17, v237
	v_exp_f32_e32 v56, v56
	v_exp_f32_e32 v57, v57
	s_waitcnt lgkmcnt(4)
	v_mfma_f32_32x32x16_bf16 v[32:47], v[212:215], v[64:67], v[32:47]
	v_cmp_le_i32_e64 s[44:45], 18, v237
	v_cmp_le_i32_e64 s[46:47], 19, v237
	v_exp_f32_e32 v58, v58
	v_exp_f32_e32 v59, v59
	v_cndmask_b32_e64 v56, 0, v56, s[10:11]
	v_cndmask_b32_e64 v57, 0, v57, s[42:43]
	v_add_f32_e32 v232, v232, v56
	v_add_f32_e32 v233, v233, v57
	v_cvt_pk_bf16_f32 v92, v56, v57
	s_waitcnt lgkmcnt(3)
; #define LAS __attribute__((address_space(3)))
; __device__ __forceinline__ void phase4_attn(const Args& a, LAS unsigned char* lds) {
;     ...
;                     for (int mt = 0; mt < 4; ++mt) { s4[mt] = zero16();
; #pragma unroll
;                         for (int ks = 0; ks < 4; ++ks) { const bf16x8_t ka = *(const LAS bf16x8_t*)(lds + A_CMPK + (32 * mt + r) * A_KSTR + 32 * ks + 16 * h); s4[mt] = MFMA32(ka, qf[ks], s4[mt]); } }
;                     const int clim = (pos - 31 - 64 * h) >> 4;
;                     float ls = 0.f;
; #pragma unroll
;                     for (int mt = 0; mt < 4; ++mt)
; #pragma unroll
;                         for (int i = 0; i < 16; ++i) { const int ci = 32 * mt + (i & 3) + 8 * (i >> 2);
;                             const float p = (ci <= clim) ? ex2(s4[mt][i]) : 0.f; s4[mt][i] = p; ls += p; }
;                     ls += __shfl_xor(ls, 32);
;                     const float inv = 1.f / fmaxf(ls, 1e-20f);
; #pragma unroll
;                     for (int mt = 0; mt < 4; ++mt) s4[mt] *= inv;
;                     if (t >= 16) {
;                         float oprev = 0.f;
; #pragma unroll
;                         for (int idx = 0; idx < 16; ++idx) {
;                             const int mt = idx >> 2, ap = idx & 3;
;                             const float tail = 0.5f * s4[mt][4 * ap + 3];
;                             const float ot = __shfl_xor(tail, 32);
;                             const float inner = s4[mt][4 * ap] + s4[mt][4 * ap + 1] + s4[mt][4 * ap + 2] + tail;
;                             const float prev = h ? ot : oprev;
;                             oprev = ot;
;                             IMP[(g * 64 + ql) * A_IMPSTR + 8 * mt + 2 * ap + h] = inner + prev;
;                         }
;                     }
;                     f32x16 oc[2]; oc[0] = zero16(); oc[1] = zero16();
; #pragma unroll
;                     for (int mt = 0; mt < 4; ++mt)
; #pragma unroll
;                         for (int s = 0; s < 2; ++s) {
;                             const bf16x8_t pf = pack8(s4[mt], 8 * s);
; #pragma unroll
;                             for (int dt = 0; dt < 2; ++dt) {
;                                 const LAS unsigned char* vp = lds + A_CMPV + (32 * dt + r) * A_CVSTR + (32 * mt + 16 * s + 4 * h) * 2;
;                                 const s16x4_t lo = *(const LAS s16x4_t*)vp, hi = *(const LAS s16x4_t*)(vp + 16);
	v_mfma_f32_32x32x16_bf16 v[0:15], v[216:219], v[88:91], v[0:15]
	ds_read2_b64 v[216:219], v244 offset0:16 offset1:18
	v_cmp_le_i32_e64 s[10:11], 24, v237
	v_cmp_le_i32_e64 s[42:43], 25, v237
	v_exp_f32_e32 v60, v60
	v_exp_f32_e32 v61, v61
	v_cndmask_b32_e64 v58, 0, v58, s[44:45]
	v_cndmask_b32_e64 v59, 0, v59, s[46:47]
	v_add_f32_e32 v232, v232, v58
	v_add_f32_e32 v233, v233, v59
	v_cvt_pk_bf16_f32 v93, v58, v59
	v_mul_f32_e32 v182, 0.5, v59
	v_add_f32_e32 v166, v56, v57
	v_add_f32_e32 v166, v166, v58
	v_add_f32_e32 v166, v166, v182
	s_waitcnt lgkmcnt(3)
	v_mfma_f32_32x32x16_bf16 v[16:31], v[220:223], v[88:91], v[16:31]
	ds_read2_b64 v[220:223], v245 offset0:48 offset1:50
	v_cmp_le_i32_e64 s[44:45], 26, v237
	v_cmp_le_i32_e64 s[46:47], 27, v237
	v_exp_f32_e32 v62, v62
	v_exp_f32_e32 v63, v63
	v_cndmask_b32_e64 v60, 0, v60, s[10:11]
	v_cndmask_b32_e64 v61, 0, v61, s[42:43]
	v_add_f32_e32 v232, v232, v60
	v_add_f32_e32 v233, v233, v61
	v_cvt_pk_bf16_f32 v94, v60, v61
	v_cndmask_b32_e64 v62, 0, v62, s[44:45]
	v_cndmask_b32_e64 v63, 0, v63, s[46:47]
	v_add_f32_e32 v232, v232, v62
	v_add_f32_e32 v233, v233, v63
	v_cvt_pk_bf16_f32 v95, v62, v63
	v_mul_f32_e32 v183, 0.5, v63
	v_add_f32_e32 v167, v60, v61
	v_add_f32_e32 v167, v167, v62
	v_add_f32_e32 v167, v167, v183
	v_cmp_le_i32_e64 s[10:11], 0, v238
	v_cmp_le_i32_e64 s[42:43], 1, v238
	v_exp_f32_e32 v32, v32
	v_exp_f32_e32 v33, v33
	v_cmp_le_i32_e64 s[44:45], 2, v238
	v_cmp_le_i32_e64 s[46:47], 3, v238
	v_exp_f32_e32 v34, v34
	v_exp_f32_e32 v35, v35
	v_cndmask_b32_e64 v32, 0, v32, s[10:11]
	v_cndmask_b32_e64 v33, 0, v33, s[42:43]
	v_add_f32_e32 v232, v232, v32
	v_add_f32_e32 v233, v233, v33
	v_cvt_pk_bf16_f32 v88, v32, v33
	s_waitcnt lgkmcnt(3)
	v_mfma_f32_32x32x16_bf16 v[0:15], v[224:227], v[92:95], v[0:15]
	ds_read2_b64 v[224:227], v244 offset0:20 offset1:22
	v_cmp_le_i32_e64 s[10:11], 8, v238
	v_cmp_le_i32_e64 s[42:43], 9, v238
	v_exp_f32_e32 v36, v36
	v_exp_f32_e32 v37, v37
	v_cndmask_b32_e64 v34, 0, v34, s[44:45]
	v_cndmask_b32_e64 v35, 0, v35, s[46:47]
	v_add_f32_e32 v232, v232, v34
	v_add_f32_e32 v233, v233, v35
	v_cvt_pk_bf16_f32 v89, v34, v35
	v_mul_f32_e32 v246, 0.5, v35
	v_add_f32_e32 v168, v32, v33
	v_add_f32_e32 v168, v168, v34
	v_add_f32_e32 v168, v168, v246
	s_waitcnt lgkmcnt(3)
	v_mfma_f32_32x32x16_bf16 v[16:31], v[228:231], v[92:95], v[16:31]
	ds_read2_b64 v[228:231], v245 offset0:52 offset1:54
	v_cmp_le_i32_e64 s[44:45], 10, v238
	v_cmp_le_i32_e64 s[46:47], 11, v238
	v_exp_f32_e32 v38, v38
	v_exp_f32_e32 v39, v39
	v_cndmask_b32_e64 v36, 0, v36, s[10:11]
	v_cndmask_b32_e64 v37, 0, v37, s[42:43]
	v_add_f32_e32 v232, v232, v36
	v_add_f32_e32 v233, v233, v37
	v_cvt_pk_bf16_f32 v90, v36, v37
	v_cndmask_b32_e64 v38, 0, v38, s[44:45]
	v_cndmask_b32_e64 v39, 0, v39, s[46:47]
	v_add_f32_e32 v232, v232, v38
	v_add_f32_e32 v233, v233, v39
	v_cvt_pk_bf16_f32 v91, v38, v39
	v_mul_f32_e32 v247, 0.5, v39
	v_add_f32_e32 v169, v36, v37
	v_add_f32_e32 v169, v169, v38
	v_add_f32_e32 v169, v169, v247
	v_cmp_le_i32_e64 s[10:11], 16, v238
	v_cmp_le_i32_e64 s[42:43], 17, v238
	v_exp_f32_e32 v40, v40
	v_exp_f32_e32 v41, v41
	v_cmp_le_i32_e64 s[44:45], 18, v238
	v_cmp_le_i32_e64 s[46:47], 19, v238
	v_exp_f32_e32 v42, v42
	v_exp_f32_e32 v43, v43
	v_cndmask_b32_e64 v40, 0, v40, s[10:11]
	v_cndmask_b32_e64 v41, 0, v41, s[42:43]
	v_add_f32_e32 v232, v232, v40
	v_add_f32_e32 v233, v233, v41
	v_cvt_pk_bf16_f32 v92, v40, v41
	s_waitcnt lgkmcnt(3)
	v_mfma_f32_32x32x16_bf16 v[0:15], v[216:219], v[88:91], v[0:15]
	v_cmp_le_i32_e64 s[10:11], 24, v238
	v_cmp_le_i32_e64 s[42:43], 25, v238
	v_exp_f32_e32 v44, v44
	v_exp_f32_e32 v45, v45
	v_cndmask_b32_e64 v42, 0, v42, s[44:45]
	v_cndmask_b32_e64 v43, 0, v43, s[46:47]
	v_add_f32_e32 v232, v232, v42
	v_add_f32_e32 v233, v233, v43
	v_cvt_pk_bf16_f32 v93, v42, v43
	v_mul_f32_e32 v248, 0.5, v43
	v_add_f32_e32 v170, v40, v41
	v_add_f32_e32 v170, v170, v42
	v_add_f32_e32 v170, v170, v248
	s_waitcnt lgkmcnt(2)
	v_mfma_f32_32x32x16_bf16 v[16:31], v[220:223], v[88:91], v[16:31]
	v_cmp_le_i32_e64 s[44:45], 26, v238
	v_cmp_le_i32_e64 s[46:47], 27, v238
	v_exp_f32_e32 v46, v46
	v_exp_f32_e32 v47, v47
	v_cndmask_b32_e64 v44, 0, v44, s[10:11]
	v_cndmask_b32_e64 v45, 0, v45, s[42:43]
	v_add_f32_e32 v232, v232, v44
	v_add_f32_e32 v233, v233, v45
	v_cvt_pk_bf16_f32 v94, v44, v45
	v_cndmask_b32_e64 v46, 0, v46, s[44:45]
	v_cndmask_b32_e64 v47, 0, v47, s[46:47]
	v_add_f32_e32 v232, v232, v46
	v_add_f32_e32 v233, v233, v47
	v_cvt_pk_bf16_f32 v95, v46, v47
	v_mul_f32_e32 v249, 0.5, v47
	v_add_f32_e32 v171, v44, v45
	v_add_f32_e32 v171, v171, v46
	v_add_f32_e32 v171, v171, v249
	s_nop 1
	s_waitcnt lgkmcnt(1)
	v_mfma_f32_32x32x16_bf16 v[0:15], v[224:227], v[92:95], v[0:15]
	s_waitcnt lgkmcnt(0)
	v_mfma_f32_32x32x16_bf16 v[16:31], v[228:231], v[92:95], v[16:31]
	s_branch .Lc0_fin
; #define LAS __attribute__((address_space(3)))
; __device__ __forceinline__ void phase4_attn(const Args& a, LAS unsigned char* lds) {
;     ...
;                     for (int mt = 0; mt < 4; ++mt) { s4[mt] = zero16();
; #pragma unroll
;                         for (int ks = 0; ks < 4; ++ks) { const bf16x8_t ka = *(const LAS bf16x8_t*)(lds + A_CMPK + (32 * mt + r) * A_KSTR + 32 * ks + 16 * h); s4[mt] = MFMA32(ka, qf[ks], s4[mt]); } }
;                     const int clim = (pos - 31 - 64 * h) >> 4;
;                     float ls = 0.f;
; #pragma unroll
;                     for (int mt = 0; mt < 4; ++mt)
; #pragma unroll
;                         for (int i = 0; i < 16; ++i) { const int ci = 32 * mt + (i & 3) + 8 * (i >> 2);
;                             const float p = (ci <= clim) ? ex2(s4[mt][i]) : 0.f; s4[mt][i] = p; ls += p; }
;                     ls += __shfl_xor(ls, 32);
;                     const float inv = 1.f / fmaxf(ls, 1e-20f);
; #pragma unroll
;                     for (int mt = 0; mt < 4; ++mt) s4[mt] *= inv;
;                     if (t >= 16) {
;                         float oprev = 0.f;
; #pragma unroll
;                         for (int idx = 0; idx < 16; ++idx) {
;                             const int mt = idx >> 2, ap = idx & 3;
;                             const float tail = 0.5f * s4[mt][4 * ap + 3];
;                             const float ot = __shfl_xor(tail, 32);
;                             const float inner = s4[mt][4 * ap] + s4[mt][4 * ap + 1] + s4[mt][4 * ap + 2] + tail;
;                             const float prev = h ? ot : oprev;
;                             oprev = ot;
;                             IMP[(g * 64 + ql) * A_IMPSTR + 8 * mt + 2 * ap + h] = inner + prev;
;                         }
;                     }
;                     f32x16 oc[2]; oc[0] = zero16(); oc[1] = zero16();
; #pragma unroll
;                     for (int mt = 0; mt < 4; ++mt)
; #pragma unroll
;                         for (int s = 0; s < 2; ++s) {
;                             const bf16x8_t pf = pack8(s4[mt], 8 * s);
; #pragma unroll
;                             for (int dt = 0; dt < 2; ++dt) {
;                                 const LAS unsigned char* vp = lds + A_CMPV + (32 * dt + r) * A_CVSTR + (32 * mt + 16 * s + 4 * h) * 2;
;                                 const s16x4_t lo = *(const LAS s16x4_t*)vp, hi = *(const LAS s16x4_t*)(vp + 16);
.Lc0_n4:
	ds_read_b128 v[200:203], v82 offset:0
	ds_read_b128 v[204:207], v82 offset:32
	ds_read_b128 v[208:211], v82 offset:64
	ds_read_b128 v[212:215], v82 offset:96
	ds_read2_b64 v[216:219], v244 offset0:0 offset1:2
	ds_read2_b64 v[220:223], v245 offset0:32 offset1:34
	ds_read2_b64 v[224:227], v244 offset0:4 offset1:6
	ds_read2_b64 v[228:231], v245 offset0:36 offset1:38
	v_subrev_u32_e32 v237, 64, v236
	v_subrev_u32_e32 v238, 96, v236
	s_waitcnt lgkmcnt(7)
	v_mfma_f32_32x32x16_bf16 v[32:47], v[200:203], v[84:87], 0
	ds_read_b128 v[200:203], v82 offset:4608
	s_waitcnt lgkmcnt(7)
	v_mfma_f32_32x32x16_bf16 v[32:47], v[204:207], v[74:77], v[32:47]
	ds_read_b128 v[204:207], v82 offset:4640
	s_waitcnt lgkmcnt(7)
	v_mfma_f32_32x32x16_bf16 v[32:47], v[208:211], v[68:71], v[32:47]
	ds_read_b128 v[208:211], v82 offset:4672
	s_waitcnt lgkmcnt(7)
	v_mfma_f32_32x32x16_bf16 v[32:47], v[212:215], v[64:67], v[32:47]
	ds_read_b128 v[212:215], v82 offset:4704
	s_nop 7
	s_nop 3
	s_waitcnt lgkmcnt(3)
	v_mfma_f32_32x32x16_bf16 v[48:63], v[200:203], v[84:87], 0
	ds_read_b128 v[200:203], v82 offset:9216
	v_exp_f32_e32 v32, v32
	v_exp_f32_e32 v33, v33
	s_waitcnt lgkmcnt(3)
	v_mfma_f32_32x32x16_bf16 v[48:63], v[204:207], v[74:77], v[48:63]
	ds_read_b128 v[204:207], v82 offset:9248
	v_exp_f32_e32 v34, v34
	v_exp_f32_e32 v35, v35
	v_mov_b32_e32 v232, v32
	v_mov_b32_e32 v233, v33
	v_cvt_pk_bf16_f32 v88, v32, v33
	v_exp_f32_e32 v36, v36
	v_exp_f32_e32 v37, v37
	v_add_f32_e32 v232, v232, v34
	v_add_f32_e32 v233, v233, v35
	v_cvt_pk_bf16_f32 v89, v34, v35
	v_mul_f32_e32 v176, 0.5, v35
	v_add_f32_e32 v160, v32, v33
	v_add_f32_e32 v160, v160, v34
	v_add_f32_e32 v160, v160, v176
	v_exp_f32_e32 v38, v38
	v_exp_f32_e32 v39, v39
	v_add_f32_e32 v232, v232, v36
	v_add_f32_e32 v233, v233, v37
	v_cvt_pk_bf16_f32 v90, v36, v37
	v_add_f32_e32 v232, v232, v38
	v_add_f32_e32 v233, v233, v39
	v_cvt_pk_bf16_f32 v91, v38, v39
	v_mul_f32_e32 v177, 0.5, v39
	v_add_f32_e32 v161, v36, v37
	v_add_f32_e32 v161, v161, v38
	v_add_f32_e32 v161, v161, v177
	s_waitcnt lgkmcnt(3)
	v_mfma_f32_32x32x16_bf16 v[48:63], v[208:211], v[68:71], v[48:63]
	ds_read_b128 v[208:211], v82 offset:9280
	v_exp_f32_e32 v40, v40
	v_exp_f32_e32 v41, v41
	s_waitcnt lgkmcnt(3)
	v_mfma_f32_32x32x16_bf16 v[48:63], v[212:215], v[64:67], v[48:63]
	ds_read_b128 v[212:215], v82 offset:9312
	v_exp_f32_e32 v42, v42
	v_exp_f32_e32 v43, v43
	v_add_f32_e32 v232, v232, v40
	v_add_f32_e32 v233, v233, v41
	v_cvt_pk_bf16_f32 v92, v40, v41
	v_mfma_f32_32x32x16_bf16 v[0:15], v[216:219], v[88:91], v[0:15]
	ds_read2_b64 v[216:219], v244 offset0:8 offset1:10
	v_exp_f32_e32 v44, v44
	v_exp_f32_e32 v45, v45
	v_add_f32_e32 v232, v232, v42
	v_add_f32_e32 v233, v233, v43
	v_cvt_pk_bf16_f32 v93, v42, v43
	v_mul_f32_e32 v178, 0.5, v43
	v_add_f32_e32 v162, v40, v41
	v_add_f32_e32 v162, v162, v42
	v_add_f32_e32 v162, v162, v178
	v_mfma_f32_32x32x16_bf16 v[16:31], v[220:223], v[88:91], v[16:31]
	ds_read2_b64 v[220:223], v245 offset0:40 offset1:42
	v_exp_f32_e32 v46, v46
	v_exp_f32_e32 v47, v47
	v_add_f32_e32 v232, v232, v44
	v_add_f32_e32 v233, v233, v45
	v_cvt_pk_bf16_f32 v94, v44, v45
	v_add_f32_e32 v232, v232, v46
	v_add_f32_e32 v233, v233, v47
	v_cvt_pk_bf16_f32 v95, v46, v47
	v_mul_f32_e32 v179, 0.5, v47
	v_add_f32_e32 v163, v44, v45
	v_add_f32_e32 v163, v163, v46
	v_add_f32_e32 v163, v163, v179
	s_waitcnt lgkmcnt(5)
	v_mfma_f32_32x32x16_bf16 v[32:47], v[200:203], v[84:87], 0
	ds_read_b128 v[200:203], v82 offset:13824
	v_exp_f32_e32 v48, v48
	v_exp_f32_e32 v49, v49
	s_waitcnt lgkmcnt(5)
	v_mfma_f32_32x32x16_bf16 v[32:47], v[204:207], v[74:77], v[32:47]
	ds_read_b128 v[204:207], v82 offset:13856
	v_exp_f32_e32 v50, v50
	v_exp_f32_e32 v51, v51
	v_add_f32_e32 v232, v232, v48
	v_add_f32_e32 v233, v233, v49
	v_cvt_pk_bf16_f32 v88, v48, v49
	v_mfma_f32_32x32x16_bf16 v[0:15], v[224:227], v[92:95], v[0:15]
	ds_read2_b64 v[224:227], v244 offset0:12 offset1:14
	v_exp_f32_e32 v52, v52
	v_exp_f32_e32 v53, v53
	v_add_f32_e32 v232, v232, v50
	v_add_f32_e32 v233, v233, v51
	v_cvt_pk_bf16_f32 v89, v50, v51
	v_mul_f32_e32 v180, 0.5, v51
	v_add_f32_e32 v164, v48, v49
	v_add_f32_e32 v164, v164, v50
	v_add_f32_e32 v164, v164, v180
	v_mfma_f32_32x32x16_bf16 v[16:31], v[228:231], v[92:95], v[16:31]
	ds_read2_b64 v[228:231], v245 offset0:44 offset1:46
	v_exp_f32_e32 v54, v54
	v_exp_f32_e32 v55, v55
	v_add_f32_e32 v232, v232, v52
	v_add_f32_e32 v233, v233, v53
	v_cvt_pk_bf16_f32 v90, v52, v53
	v_add_f32_e32 v232, v232, v54
	v_add_f32_e32 v233, v233, v55
	v_cvt_pk_bf16_f32 v91, v54, v55
	v_mul_f32_e32 v181, 0.5, v55
	v_add_f32_e32 v165, v52, v53
	v_add_f32_e32 v165, v165, v54
	v_add_f32_e32 v165, v165, v181
	s_waitcnt lgkmcnt(7)
	v_mfma_f32_32x32x16_bf16 v[32:47], v[208:211], v[68:71], v[32:47]
	ds_read_b128 v[208:211], v82 offset:13888
	v_exp_f32_e32 v56, v56
	v_exp_f32_e32 v57, v57
	s_waitcnt lgkmcnt(7)
	v_mfma_f32_32x32x16_bf16 v[32:47], v[212:215], v[64:67], v[32:47]
	ds_read_b128 v[212:215], v82 offset:13920
	v_exp_f32_e32 v58, v58
	v_exp_f32_e32 v59, v59
	v_add_f32_e32 v232, v232, v56
	v_add_f32_e32 v233, v233, v57
	v_cvt_pk_bf16_f32 v92, v56, v57
	s_waitcnt lgkmcnt(7)
	v_mfma_f32_32x32x16_bf16 v[0:15], v[216:219], v[88:91], v[0:15]
	ds_read2_b64 v[216:219], v244 offset0:16 offset1:18
	v_exp_f32_e32 v60, v60
	v_exp_f32_e32 v61, v61
	v_add_f32_e32 v232, v232, v58
	v_add_f32_e32 v233, v233, v59
	v_cvt_pk_bf16_f32 v93, v58, v59
	v_mul_f32_e32 v182, 0.5, v59
	v_add_f32_e32 v166, v56, v57
	v_add_f32_e32 v166, v166, v58
	v_add_f32_e32 v166, v166, v182
	s_waitcnt lgkmcnt(7)
; #define LAS __attribute__((address_space(3)))
; __device__ __forceinline__ void phase4_attn(const Args& a, LAS unsigned char* lds) {
;     ...
;                     for (int mt = 0; mt < 4; ++mt) { s4[mt] = zero16();
; #pragma unroll
;                         for (int ks = 0; ks < 4; ++ks) { const bf16x8_t ka = *(const LAS bf16x8_t*)(lds + A_CMPK + (32 * mt + r) * A_KSTR + 32 * ks + 16 * h); s4[mt] = MFMA32(ka, qf[ks], s4[mt]); } }
;                     const int clim = (pos - 31 - 64 * h) >> 4;
;                     float ls = 0.f;
; #pragma unroll
;                     for (int mt = 0; mt < 4; ++mt)
; #pragma unroll
;                         for (int i = 0; i < 16; ++i) { const int ci = 32 * mt + (i & 3) + 8 * (i >> 2);
;                             const float p = (ci <= clim) ? ex2(s4[mt][i]) : 0.f; s4[mt][i] = p; ls += p; }
;                     ls += __shfl_xor(ls, 32);
;                     const float inv = 1.f / fmaxf(ls, 1e-20f);
; #pragma unroll
;                     for (int mt = 0; mt < 4; ++mt) s4[mt] *= inv;
;                     if (t >= 16) {
;                         float oprev = 0.f;
; #pragma unroll
;                         for (int idx = 0; idx < 16; ++idx) {
;                             const int mt = idx >> 2, ap = idx & 3;
;                             const float tail = 0.5f * s4[mt][4 * ap + 3];
;                             const float ot = __shfl_xor(tail, 32);
;                             const float inner = s4[mt][4 * ap] + s4[mt][4 * ap + 1] + s4[mt][4 * ap + 2] + tail;
;                             const float prev = h ? ot : oprev;
;                             oprev = ot;
;                             IMP[(g * 64 + ql) * A_IMPSTR + 8 * mt + 2 * ap + h] = inner + prev;
;                         }
;                     }
;                     f32x16 oc[2]; oc[0] = zero16(); oc[1] = zero16();
; #pragma unroll
;                     for (int mt = 0; mt < 4; ++mt)
; #pragma unroll
;                         for (int s = 0; s < 2; ++s) {
;                             const bf16x8_t pf = pack8(s4[mt], 8 * s);
; #pragma unroll
;                             for (int dt = 0; dt < 2; ++dt) {
;                                 const LAS unsigned char* vp = lds + A_CMPV + (32 * dt + r) * A_CVSTR + (32 * mt + 16 * s + 4 * h) * 2;
;                                 const s16x4_t lo = *(const LAS s16x4_t*)vp, hi = *(const LAS s16x4_t*)(vp + 16);
	v_mfma_f32_32x32x16_bf16 v[16:31], v[220:223], v[88:91], v[16:31]
	ds_read2_b64 v[220:223], v245 offset0:48 offset1:50
	v_exp_f32_e32 v62, v62
	v_exp_f32_e32 v63, v63
	v_add_f32_e32 v232, v232, v60
	v_add_f32_e32 v233, v233, v61
	v_cvt_pk_bf16_f32 v94, v60, v61
	v_add_f32_e32 v232, v232, v62
	v_add_f32_e32 v233, v233, v63
	v_cvt_pk_bf16_f32 v95, v62, v63
	v_mul_f32_e32 v183, 0.5, v63
	v_add_f32_e32 v167, v60, v61
	v_add_f32_e32 v167, v167, v62
	v_add_f32_e32 v167, v167, v183
	s_waitcnt lgkmcnt(7)
	v_mfma_f32_32x32x16_bf16 v[48:63], v[200:203], v[84:87], 0
	v_cmp_le_i32_e64 s[10:11], 0, v237
	v_cmp_le_i32_e64 s[42:43], 1, v237
	v_exp_f32_e32 v32, v32
	v_exp_f32_e32 v33, v33
	s_waitcnt lgkmcnt(6)
	v_mfma_f32_32x32x16_bf16 v[48:63], v[204:207], v[74:77], v[48:63]
	v_cmp_le_i32_e64 s[44:45], 2, v237
	v_cmp_le_i32_e64 s[46:47], 3, v237
	v_exp_f32_e32 v34, v34
	v_exp_f32_e32 v35, v35
	v_cndmask_b32_e64 v32, 0, v32, s[10:11]
	v_cndmask_b32_e64 v33, 0, v33, s[42:43]
	v_add_f32_e32 v232, v232, v32
	v_add_f32_e32 v233, v233, v33
	v_cvt_pk_bf16_f32 v88, v32, v33
	s_waitcnt lgkmcnt(5)
	v_mfma_f32_32x32x16_bf16 v[0:15], v[224:227], v[92:95], v[0:15]
	ds_read2_b64 v[224:227], v244 offset0:20 offset1:22
	v_cmp_le_i32_e64 s[10:11], 8, v237
	v_cmp_le_i32_e64 s[42:43], 9, v237
	v_exp_f32_e32 v36, v36
	v_exp_f32_e32 v37, v37
	v_cndmask_b32_e64 v34, 0, v34, s[44:45]
	v_cndmask_b32_e64 v35, 0, v35, s[46:47]
	v_add_f32_e32 v232, v232, v34
	v_add_f32_e32 v233, v233, v35
	v_cvt_pk_bf16_f32 v89, v34, v35
	v_mul_f32_e32 v246, 0.5, v35
	v_add_f32_e32 v168, v32, v33
	v_add_f32_e32 v168, v168, v34
	v_add_f32_e32 v168, v168, v246
	s_waitcnt lgkmcnt(5)
	v_mfma_f32_32x32x16_bf16 v[16:31], v[228:231], v[92:95], v[16:31]
	ds_read2_b64 v[228:231], v245 offset0:52 offset1:54
	v_cmp_le_i32_e64 s[44:45], 10, v237
	v_cmp_le_i32_e64 s[46:47], 11, v237
	v_exp_f32_e32 v38, v38
	v_exp_f32_e32 v39, v39
	v_cndmask_b32_e64 v36, 0, v36, s[10:11]
	v_cndmask_b32_e64 v37, 0, v37, s[42:43]
	v_add_f32_e32 v232, v232, v36
	v_add_f32_e32 v233, v233, v37
	v_cvt_pk_bf16_f32 v90, v36, v37
	v_cndmask_b32_e64 v38, 0, v38, s[44:45]
	v_cndmask_b32_e64 v39, 0, v39, s[46:47]
	v_add_f32_e32 v232, v232, v38
	v_add_f32_e32 v233, v233, v39
	v_cvt_pk_bf16_f32 v91, v38, v39
	v_mul_f32_e32 v247, 0.5, v39
	v_add_f32_e32 v169, v36, v37
	v_add_f32_e32 v169, v169, v38
	v_add_f32_e32 v169, v169, v247
	s_waitcnt lgkmcnt(5)
	v_mfma_f32_32x32x16_bf16 v[48:63], v[208:211], v[68:71], v[48:63]
	v_cmp_le_i32_e64 s[10:11], 16, v237
	v_cmp_le_i32_e64 s[42:43], 17, v237
	v_exp_f32_e32 v40, v40
	v_exp_f32_e32 v41, v41
	s_waitcnt lgkmcnt(4)
	v_mfma_f32_32x32x16_bf16 v[48:63], v[212:215], v[64:67], v[48:63]
	v_cmp_le_i32_e64 s[44:45], 18, v237
	v_cmp_le_i32_e64 s[46:47], 19, v237
	v_exp_f32_e32 v42, v42
	v_exp_f32_e32 v43, v43
	v_cndmask_b32_e64 v40, 0, v40, s[10:11]
	v_cndmask_b32_e64 v41, 0, v41, s[42:43]
	v_add_f32_e32 v232, v232, v40
	v_add_f32_e32 v233, v233, v41
	v_cvt_pk_bf16_f32 v92, v40, v41
	s_waitcnt lgkmcnt(3)
	v_mfma_f32_32x32x16_bf16 v[0:15], v[216:219], v[88:91], v[0:15]
	ds_read2_b64 v[216:219], v244 offset0:24 offset1:26
	v_cmp_le_i32_e64 s[10:11], 24, v237
	v_cmp_le_i32_e64 s[42:43], 25, v237
	v_exp_f32_e32 v44, v44
	v_exp_f32_e32 v45, v45
	v_cndmask_b32_e64 v42, 0, v42, s[44:45]
	v_cndmask_b32_e64 v43, 0, v43, s[46:47]
	v_add_f32_e32 v232, v232, v42
	v_add_f32_e32 v233, v233, v43
	v_cvt_pk_bf16_f32 v93, v42, v43
	v_mul_f32_e32 v248, 0.5, v43
	v_add_f32_e32 v170, v40, v41
	v_add_f32_e32 v170, v170, v42
	v_add_f32_e32 v170, v170, v248
	s_waitcnt lgkmcnt(3)
	v_mfma_f32_32x32x16_bf16 v[16:31], v[220:223], v[88:91], v[16:31]
	ds_read2_b64 v[220:223], v245 offset0:56 offset1:58
	v_cmp_le_i32_e64 s[44:45], 26, v237
	v_cmp_le_i32_e64 s[46:47], 27, v237
	v_exp_f32_e32 v46, v46
	v_exp_f32_e32 v47, v47
	v_cndmask_b32_e64 v44, 0, v44, s[10:11]
	v_cndmask_b32_e64 v45, 0, v45, s[42:43]
	v_add_f32_e32 v232, v232, v44
	v_add_f32_e32 v233, v233, v45
	v_cvt_pk_bf16_f32 v94, v44, v45
	v_cndmask_b32_e64 v46, 0, v46, s[44:45]
	v_cndmask_b32_e64 v47, 0, v47, s[46:47]
	v_add_f32_e32 v232, v232, v46
	v_add_f32_e32 v233, v233, v47
	v_cvt_pk_bf16_f32 v95, v46, v47
	v_mul_f32_e32 v249, 0.5, v47
	v_add_f32_e32 v171, v44, v45
	v_add_f32_e32 v171, v171, v46
	v_add_f32_e32 v171, v171, v249
	v_cmp_le_i32_e64 s[10:11], 0, v238
	v_cmp_le_i32_e64 s[42:43], 1, v238
	v_exp_f32_e32 v48, v48
	v_exp_f32_e32 v49, v49
	v_cmp_le_i32_e64 s[44:45], 2, v238
	v_cmp_le_i32_e64 s[46:47], 3, v238
	v_exp_f32_e32 v50, v50
	v_exp_f32_e32 v51, v51
	v_cndmask_b32_e64 v48, 0, v48, s[10:11]
	v_cndmask_b32_e64 v49, 0, v49, s[42:43]
	v_add_f32_e32 v232, v232, v48
	v_add_f32_e32 v233, v233, v49
	v_cvt_pk_bf16_f32 v88, v48, v49
	s_waitcnt lgkmcnt(3)
	v_mfma_f32_32x32x16_bf16 v[0:15], v[224:227], v[92:95], v[0:15]
	ds_read2_b64 v[224:227], v244 offset0:28 offset1:30
	v_cmp_le_i32_e64 s[10:11], 8, v238
	v_cmp_le_i32_e64 s[42:43], 9, v238
	v_exp_f32_e32 v52, v52
	v_exp_f32_e32 v53, v53
	v_cndmask_b32_e64 v50, 0, v50, s[44:45]
	v_cndmask_b32_e64 v51, 0, v51, s[46:47]
	v_add_f32_e32 v232, v232, v50
	v_add_f32_e32 v233, v233, v51
	v_cvt_pk_bf16_f32 v89, v50, v51
	v_mul_f32_e32 v250, 0.5, v51
	v_add_f32_e32 v172, v48, v49
	v_add_f32_e32 v172, v172, v50
	v_add_f32_e32 v172, v172, v250
	s_waitcnt lgkmcnt(3)
; __device__ __forceinline__ void phase4_attn(const Args& a, LAS unsigned char* lds) {
;     ...
;                     ls += __shfl_xor(ls, 32);
;                     const float inv = 1.f / fmaxf(ls, 1e-20f);
; #pragma unroll
;                     for (int mt = 0; mt < 4; ++mt) s4[mt] *= inv;
;                     if (t >= 16) {
;                         float oprev = 0.f;
; #pragma unroll
;                         for (int idx = 0; idx < 16; ++idx) {
;                             const int mt = idx >> 2, ap = idx & 3;
;                             const float tail = 0.5f * s4[mt][4 * ap + 3];
;                             const float ot = __shfl_xor(tail, 32);
;                             const float inner = s4[mt][4 * ap] + s4[mt][4 * ap + 1] + s4[mt][4 * ap + 2] + tail;
;                             const float prev = h ? ot : oprev;
;                             oprev = ot;
;                             IMP[(g * 64 + ql) * A_IMPSTR + 8 * mt + 2 * ap + h] = inner + prev;
;                         }
;                     }
	v_mfma_f32_32x32x16_bf16 v[16:31], v[228:231], v[92:95], v[16:31]
	ds_read2_b64 v[228:231], v245 offset0:60 offset1:62
	v_cmp_le_i32_e64 s[44:45], 10, v238
	v_cmp_le_i32_e64 s[46:47], 11, v238
	v_exp_f32_e32 v54, v54
	v_exp_f32_e32 v55, v55
	v_cndmask_b32_e64 v52, 0, v52, s[10:11]
	v_cndmask_b32_e64 v53, 0, v53, s[42:43]
	v_add_f32_e32 v232, v232, v52
	v_add_f32_e32 v233, v233, v53
	v_cvt_pk_bf16_f32 v90, v52, v53
	v_cndmask_b32_e64 v54, 0, v54, s[44:45]
	v_cndmask_b32_e64 v55, 0, v55, s[46:47]
	v_add_f32_e32 v232, v232, v54
	v_add_f32_e32 v233, v233, v55
	v_cvt_pk_bf16_f32 v91, v54, v55
	v_mul_f32_e32 v251, 0.5, v55
	v_add_f32_e32 v173, v52, v53
	v_add_f32_e32 v173, v173, v54
	v_add_f32_e32 v173, v173, v251
	v_cmp_le_i32_e64 s[10:11], 16, v238
	v_cmp_le_i32_e64 s[42:43], 17, v238
	v_exp_f32_e32 v56, v56
	v_exp_f32_e32 v57, v57
	v_cmp_le_i32_e64 s[44:45], 18, v238
	v_cmp_le_i32_e64 s[46:47], 19, v238
	v_exp_f32_e32 v58, v58
	v_exp_f32_e32 v59, v59
	v_cndmask_b32_e64 v56, 0, v56, s[10:11]
	v_cndmask_b32_e64 v57, 0, v57, s[42:43]
	v_add_f32_e32 v232, v232, v56
	v_add_f32_e32 v233, v233, v57
	v_cvt_pk_bf16_f32 v92, v56, v57
	s_waitcnt lgkmcnt(3)
	v_mfma_f32_32x32x16_bf16 v[0:15], v[216:219], v[88:91], v[0:15]
	v_cmp_le_i32_e64 s[10:11], 24, v238
	v_cmp_le_i32_e64 s[42:43], 25, v238
	v_exp_f32_e32 v60, v60
	v_exp_f32_e32 v61, v61
	v_cndmask_b32_e64 v58, 0, v58, s[44:45]
	v_cndmask_b32_e64 v59, 0, v59, s[46:47]
	v_add_f32_e32 v232, v232, v58
	v_add_f32_e32 v233, v233, v59
	v_cvt_pk_bf16_f32 v93, v58, v59
	v_mul_f32_e32 v252, 0.5, v59
	v_add_f32_e32 v174, v56, v57
	v_add_f32_e32 v174, v174, v58
	v_add_f32_e32 v174, v174, v252
	s_waitcnt lgkmcnt(2)
	v_mfma_f32_32x32x16_bf16 v[16:31], v[220:223], v[88:91], v[16:31]
	v_cmp_le_i32_e64 s[44:45], 26, v238
	v_cmp_le_i32_e64 s[46:47], 27, v238
	v_exp_f32_e32 v62, v62
	v_exp_f32_e32 v63, v63
	v_cndmask_b32_e64 v60, 0, v60, s[10:11]
	v_cndmask_b32_e64 v61, 0, v61, s[42:43]
	v_add_f32_e32 v232, v232, v60
	v_add_f32_e32 v233, v233, v61
	v_cvt_pk_bf16_f32 v94, v60, v61
	v_cndmask_b32_e64 v62, 0, v62, s[44:45]
	v_cndmask_b32_e64 v63, 0, v63, s[46:47]
	v_add_f32_e32 v232, v232, v62
	v_add_f32_e32 v233, v233, v63
	v_cvt_pk_bf16_f32 v95, v62, v63
	v_mul_f32_e32 v253, 0.5, v63
	v_add_f32_e32 v175, v60, v61
	v_add_f32_e32 v175, v175, v62
	v_add_f32_e32 v175, v175, v253
	s_nop 1
	s_waitcnt lgkmcnt(1)
	v_mfma_f32_32x32x16_bf16 v[0:15], v[224:227], v[92:95], v[0:15]
	s_waitcnt lgkmcnt(0)
	v_mfma_f32_32x32x16_bf16 v[16:31], v[228:231], v[92:95], v[16:31]
	s_branch .Lc0_fin
.Lc0_fin:
	v_add_f32_e32 v232, v232, v233
	ds_bpermute_b32 v239, v193, v232
	s_waitcnt lgkmcnt(0)
	v_add_f32_e32 v239, v232, v239
	v_max_f32_e32 v239, 0x1e3ce508, v239
	v_div_scale_f32 v240, s[44:45], v239, v239, 1.0
	v_rcp_f32_e32 v241, v240
	v_div_scale_f32 v242, vcc, 1.0, v239, 1.0
	s_nop 0
	v_fma_f32 v243, -v240, v241, 1.0
	v_fmac_f32_e32 v241, v243, v241
	v_mul_f32_e32 v243, v242, v241
	v_fma_f32 v96, -v240, v243, v242
	v_fmac_f32_e32 v243, v96, v241
	v_fma_f32 v240, -v240, v243, v242
	v_div_fmas_f32 v240, v240, v241, v243
	v_div_fixup_f32 v97, v240, v239, 1.0
	v_mul_f32_e32 v0, v0, v97
	v_mul_f32_e32 v1, v1, v97
	v_mul_f32_e32 v2, v2, v97
	v_mul_f32_e32 v3, v3, v97
	v_mul_f32_e32 v4, v4, v97
	v_mul_f32_e32 v5, v5, v97
	v_mul_f32_e32 v6, v6, v97
	v_mul_f32_e32 v7, v7, v97
	v_mul_f32_e32 v8, v8, v97
	v_mul_f32_e32 v9, v9, v97
	v_mul_f32_e32 v10, v10, v97
	v_mul_f32_e32 v11, v11, v97
	v_mul_f32_e32 v12, v12, v97
	v_mul_f32_e32 v13, v13, v97
	v_mul_f32_e32 v14, v14, v97
	v_mul_f32_e32 v15, v15, v97
	v_mul_f32_e32 v16, v16, v97
	v_mul_f32_e32 v17, v17, v97
	v_mul_f32_e32 v18, v18, v97
	v_mul_f32_e32 v19, v19, v97
	v_mul_f32_e32 v20, v20, v97
	v_mul_f32_e32 v21, v21, v97
	v_mul_f32_e32 v22, v22, v97
	v_mul_f32_e32 v23, v23, v97
	v_mul_f32_e32 v24, v24, v97
	v_mul_f32_e32 v25, v25, v97
	v_mul_f32_e32 v26, v26, v97
	v_mul_f32_e32 v27, v27, v97
	v_mul_f32_e32 v28, v28, v97
	v_mul_f32_e32 v29, v29, v97
	v_mul_f32_e32 v30, v30, v97
	v_mul_f32_e32 v31, v31, v97
	s_cmp_gt_u32 s38, 15
	s_cbranch_scc0 .Lc0_noimp
	v_cmp_ne_u32_e64 s[46:47], 0, v101
	ds_bpermute_b32 v32, v193, v176
	ds_bpermute_b32 v33, v193, v177
	ds_bpermute_b32 v34, v193, v178
	ds_bpermute_b32 v35, v193, v179
	ds_bpermute_b32 v36, v193, v180
	ds_bpermute_b32 v37, v193, v181
	ds_bpermute_b32 v38, v193, v182
	ds_bpermute_b32 v39, v193, v183
	ds_bpermute_b32 v40, v193, v246
	ds_bpermute_b32 v41, v193, v247
	ds_bpermute_b32 v42, v193, v248
	ds_bpermute_b32 v43, v193, v249
	ds_bpermute_b32 v44, v193, v250
	ds_bpermute_b32 v45, v193, v251
	ds_bpermute_b32 v46, v193, v252
	ds_bpermute_b32 v47, v193, v253
	v_lshrrev_b32_e32 v48, 7, v152
	v_lshl_or_b32 v48, v48, 6, v98
	v_mul_u32_u24_e32 v48, 0x84, v48
	v_add_u32_e32 v48, v48, v155
	v_add_u32_e32 v48, 0x19e00, v48
	s_waitcnt lgkmcnt(0)
	v_cndmask_b32_e64 v49, 0, v32, s[46:47]
	v_add_f32_e32 v49, v160, v49
	v_mul_f32_e32 v49, v49, v97
	ds_write_b32 v48, v49 offset:0
	v_cndmask_b32_e64 v50, v32, v33, s[46:47]
	v_add_f32_e32 v50, v161, v50
	v_mul_f32_e32 v50, v50, v97
	ds_write_b32 v48, v50 offset:8
	v_cndmask_b32_e64 v49, v33, v34, s[46:47]
	v_add_f32_e32 v49, v162, v49
	v_mul_f32_e32 v49, v49, v97
	ds_write_b32 v48, v49 offset:16
	v_cndmask_b32_e64 v50, v34, v35, s[46:47]
	v_add_f32_e32 v50, v163, v50
	v_mul_f32_e32 v50, v50, v97
	ds_write_b32 v48, v50 offset:24
	v_cndmask_b32_e64 v49, v35, v36, s[46:47]
	v_add_f32_e32 v49, v164, v49
	v_mul_f32_e32 v49, v49, v97
	ds_write_b32 v48, v49 offset:32
	v_cndmask_b32_e64 v50, v36, v37, s[46:47]
	v_add_f32_e32 v50, v165, v50
	v_mul_f32_e32 v50, v50, v97
	ds_write_b32 v48, v50 offset:40
	v_cndmask_b32_e64 v49, v37, v38, s[46:47]
	v_add_f32_e32 v49, v166, v49
	v_mul_f32_e32 v49, v49, v97
	ds_write_b32 v48, v49 offset:48
	v_cndmask_b32_e64 v50, v38, v39, s[46:47]
	v_add_f32_e32 v50, v167, v50
	v_mul_f32_e32 v50, v50, v97
	ds_write_b32 v48, v50 offset:56
	v_cndmask_b32_e64 v49, v39, v40, s[46:47]
	v_add_f32_e32 v49, v168, v49
	v_mul_f32_e32 v49, v49, v97
	ds_write_b32 v48, v49 offset:64
	v_cndmask_b32_e64 v50, v40, v41, s[46:47]
	v_add_f32_e32 v50, v169, v50
	v_mul_f32_e32 v50, v50, v97
	ds_write_b32 v48, v50 offset:72
	v_cndmask_b32_e64 v49, v41, v42, s[46:47]
	v_add_f32_e32 v49, v170, v49
	v_mul_f32_e32 v49, v49, v97
	ds_write_b32 v48, v49 offset:80
	v_cndmask_b32_e64 v50, v42, v43, s[46:47]
	v_add_f32_e32 v50, v171, v50
	v_mul_f32_e32 v50, v50, v97
	ds_write_b32 v48, v50 offset:88
	v_cndmask_b32_e64 v49, v43, v44, s[46:47]
	v_add_f32_e32 v49, v172, v49
	v_mul_f32_e32 v49, v49, v97
	ds_write_b32 v48, v49 offset:96
	v_cndmask_b32_e64 v50, v44, v45, s[46:47]
	v_add_f32_e32 v50, v173, v50
	v_mul_f32_e32 v50, v50, v97
	ds_write_b32 v48, v50 offset:104
	v_cndmask_b32_e64 v49, v45, v46, s[46:47]
	v_add_f32_e32 v49, v174, v49
	v_mul_f32_e32 v49, v49, v97
	ds_write_b32 v48, v49 offset:112
	v_cndmask_b32_e64 v50, v46, v47, s[46:47]
	v_add_f32_e32 v50, v175, v50
	v_mul_f32_e32 v50, v50, v97
	ds_write_b32 v48, v50 offset:120
; #define LAS __attribute__((address_space(3)))
; __device__ __forceinline__ void phase4_attn(const Args& a, LAS unsigned char* lds) {
;     ...
;                 if (t >= 16) {
;                     __syncthreads();
;                     const int qloc = tid >> 3, jg = tid & 7;
;                     unsigned bits = 0u;
;                     float xe[4]; int cnt[4];
; #pragma unroll
;                     for (int e = 0; e < 4; ++e) { const int j = 4 * jg + e; const LAS float* ip = IMP + qloc * A_IMPSTR + j;
;                         float x = (ip[0] + ip[64 * A_IMPSTR]) + (ip[128 * A_IMPSTR] + ip[192 * A_IMPSTR]);
;                         if (j == 0 || j == t || j == t - 1) x = 1e9f;
;                         if (j > t) x = -INFINITY;
;                         xe[e] = x; cnt[e] = 0; }
; #pragma unroll 4
;                     for (int i = 0; i < 32; ++i) { const LAS float* ip = IMP + qloc * A_IMPSTR + i;
;                         float vi = (ip[0] + ip[64 * A_IMPSTR]) + (ip[128 * A_IMPSTR] + ip[192 * A_IMPSTR]);
;                         if (i == 0 || i == t || i == t - 1) vi = 1e9f;
;                         if (i > t) vi = -INFINITY;
; #pragma unroll
;                         for (int e = 0; e < 4; ++e) cnt[e] += (vi > xe[e] || (vi == xe[e] && i < 4 * jg + e)) ? 1 : 0; }
; #pragma unroll
;                     for (int e = 0; e < 4; ++e) if (cnt[e] < 16 && xe[e] > -INFINITY) bits |= 1u << (4 * jg + e);
.Lc0_noimp:
	s_waitcnt lgkmcnt(0)
	s_lshl_b32 s30, 2, s38
	s_add_i32 s30, s30, -1
	s_add_i32 s80, s38, -1
	v_mov_b32_e32 v158, s30
	s_cmp_gt_u32 s38, 15
	s_cselect_b64 s[2:3], 0, -1
	s_andn2_b64 vcc, exec, s[0:1]
	s_cbranch_vccnz .LBB0_725
	s_movk_i32 s0, 0x84
	v_mul_lo_u32 v50, v99, s0
	v_readlane_b32 s0, v254, 28
	v_and_b32_e32 v33, 7, v152
	s_nop 0
	v_add_u32_e32 v46, s0, v50
	v_lshl_add_u32 v32, v33, 4, v46
	v_add_u32_e32 v40, 0x2100, v32
	v_add_u32_e32 v36, 0x4200, v32
	v_add_u32_e32 v38, 0x6300, v32
	s_barrier
	ds_read2_b32 v[34:35], v32 offset1:1
	ds_read2_b32 v[36:37], v36 offset1:1
	ds_read2_b32 v[38:39], v38 offset1:1
	ds_read2_b32 v[40:41], v40 offset1:1
	v_lshlrev_b32_e32 v32, 2, v33
	s_waitcnt lgkmcnt(3)
	v_mov_b32_e32 v42, v34
	s_waitcnt lgkmcnt(2)
	v_mov_b32_e32 v43, v36
	s_waitcnt lgkmcnt(1)
	v_mov_b32_e32 v45, v38
	s_waitcnt lgkmcnt(0)
	v_mov_b32_e32 v44, v40
	v_cmp_eq_u32_e32 vcc, 0, v33
	v_cmp_eq_u32_e64 s[0:1], s38, v32
	v_pk_add_f32 v[42:43], v[42:43], v[44:45]
	s_or_b64 s[4:5], vcc, s[0:1]
	v_cmp_eq_u32_e64 s[0:1], s80, v32
	v_add_f32_e32 v34, v42, v43
	s_or_b64 s[0:1], s[4:5], s[0:1]
	v_cndmask_b32_e64 v33, v34, v190, s[0:1]
	v_cmp_ge_u32_e64 s[0:1], s38, v32
	v_mov_b32_e32 v36, v35
	v_mov_b32_e32 v38, v41
	v_cndmask_b32_e64 v34, v191, v33, s[0:1]
	v_or_b32_e32 v33, 1, v32
	v_pk_add_f32 v[36:37], v[36:37], v[38:39]
	v_cmp_eq_u32_e64 s[0:1], s38, v33
	v_cmp_eq_u32_e64 s[4:5], s80, v33
	v_add_f32_e32 v35, v36, v37
	s_or_b64 s[0:1], s[0:1], s[4:5]
	v_or_b32_e32 v38, 2, v32
	v_cndmask_b32_e64 v33, v35, v190, s[0:1]
	v_lshl_add_u32 v35, v38, 2, v46
	v_add_u32_e32 v36, 0x2100, v35
	v_add_u32_e32 v37, 0x4200, v35
	v_add_u32_e32 v39, 0x6300, v35
	ds_read2_b32 v[40:41], v35 offset1:1
	ds_read2_b32 v[44:45], v36 offset1:1
	ds_read2_b32 v[46:47], v37 offset1:1
	ds_read2_b32 v[48:49], v39 offset1:1
	v_cmp_gt_u32_e64 s[0:1], s38, v32
	v_or_b32_e32 v42, 3, v32
	s_waitcnt lgkmcnt(2)
	v_pk_add_f32 v[40:41], v[40:41], v[44:45]
	v_cndmask_b32_e64 v36, v191, v33, s[0:1]
	s_waitcnt lgkmcnt(0)
	v_pk_add_f32 v[44:45], v[46:47], v[48:49]
	v_cmp_eq_u32_e64 s[0:1], s38, v38
	v_cmp_eq_u32_e64 s[6:7], s80, v38
	v_pk_add_f32 v[40:41], v[40:41], v[44:45]
	v_cmp_eq_u32_e64 s[4:5], s38, v42
	v_cmp_eq_u32_e64 s[8:9], s80, v42
	s_or_b64 s[0:1], s[0:1], s[6:7]
	v_cndmask_b32_e64 v37, v40, v190, s[0:1]
	s_or_b64 s[0:1], s[4:5], s[8:9]
	v_cndmask_b32_e64 v33, v41, v190, s[0:1]
	v_cmp_ge_u32_e64 s[0:1], s38, v42
	s_mov_b32 s31, 0
	s_mov_b32 s42, 1
	v_cndmask_b32_e64 v33, v191, v33, s[0:1]
	v_cmp_ge_u32_e64 s[0:1], s38, v38
	v_mov_b32_e32 v35, v32
	s_mov_b32 s43, s38
	v_cndmask_b32_e64 v40, v191, v37, s[0:1]
	s_mov_b32 s44, s80
	v_mov_b32_e32 v37, v34
	v_mov_b32_e32 v39, v36
	v_mov_b32_e32 v41, v38
	v_mov_b32_e32 v44, v40
	v_mov_b32_e32 v43, v40
	v_mov_b32_e32 v45, v42
	v_mov_b32_e32 v46, v33
	v_mov_b32_e32 v47, v33
	v_add_u32_e32 v48, 0, v50
	v_mov_b32_e32 v49, 0
	v_mov_b32_e32 v50, 0
	v_mov_b32_e32 v51, 0
	v_mov_b32_e32 v52, 0
	v_mov_b32_e32 v53, 0
	v_mov_b32_e32 v54, 0
	v_mov_b32_e32 v55, 0
	v_mov_b32_e32 v56, 0
	s_mov_b32 s45, 0

; #define LAS __attribute__((address_space(3)))
; __device__ __forceinline__ void phase4_attn(const Args& a, LAS unsigned char* lds) {
;     ...
;                 for (int i = 0; i < n_all; ++i) {
;                     const int bufo = i & 1;
;                     if (i + 1 < n_all) A_ISSUE(i + 1);
;                     const LAS unsigned char* Kb = lds + A_KBUF + bufo * A_KT; const LAS unsigned char* Vb = lds + A_VBUF + bufo * A_VT;
;     ...
;                     if (i + 1 < n_all) A_STAGE(bufo ^ 1);
.Lt1_noissue:
	s_and_b32 s46, s44, 1
	s_mul_i32 s0, s46, 0x4800
	s_mul_i32 s1, s46, 0x4200
	v_add_u32_e32 v72, s0, v244
	v_add_u32_e32 v73, s1, v245
	v_add_u32_e32 v74, 0x2000, v73
	s_xor_b32 s0, s46, 1
	s_mul_i32 s1, s0, 0x4800
	s_mul_i32 s0, s0, 0x4200
	v_add_u32_e32 v251, s1, v246
	v_add_u32_e32 v252, s0, v247
	s_mov_b32 s47, 0

; #define LAS __attribute__((address_space(3)))
; #define MFMA32(a, b, c) __builtin_amdgcn_mfma_f32_32x32x16_bf16((a), (b), (c), 0, 0, 0)
; __device__ __forceinline__ float ex2(float x) { return __builtin_amdgcn_exp2f(x); }
; template <int MODE>
; __device__ __forceinline__ void attn_tile(const LAS unsigned char* Kb, const LAS unsigned char* Vb, const bf16x8_t (&qf)[4], f32x16 (&oacc)[2], float& l_run,
;                                           int r, int h, int dlt0, int dlt1, bool hiw) {
;     const unsigned ulim = (MODE == 0) ? 0x80000000u : 512u;
;     float ls = 0.f;
; #pragma unroll
;     for (int mt = 0; mt < 4; ++mt) {
;         if (mt == 0) { if (hiw) __builtin_amdgcn_s_setprio(1); else __builtin_amdgcn_s_setprio(0); }
;         if (mt == 2) { if (hiw) __builtin_amdgcn_s_setprio(0); else __builtin_amdgcn_s_setprio(1); }
;         const int dl = mt < 2 ? dlt0 : dlt1;
;         f32x16 sacc = zero16();
; #pragma unroll
;         for (int ks = 0; ks < 4; ++ks) { const bf16x8_t ka = *(const LAS bf16x8_t*)(Kb + (32 * mt + r) * A_KSTR + 32 * ks + 16 * h); sacc = MFMA32(ka, qf[ks], sacc); }
; #pragma unroll
;         for (int i = 0; i < 16; ++i) {
;             float p;
;             if (MODE == 2) p = ex2(sacc[i]);
;             else if (MODE == 3) p = ex2(sacc[i] + __int_as_float(dl));
;             else { const int ci = 32 * mt + (i & 3) + 8 * (i >> 2); p = ((unsigned)(dl - ci) < ulim) ? ex2(sacc[i]) : 0.f; }
;             sacc[i] = p; ls += p;
;         }
; #pragma unroll
;         for (int s = 0; s < 2; ++s) {
;             const bf16x8_t pf = pack8(sacc, 8 * s);
; #pragma unroll
;             for (int dt = 0; dt < 2; ++dt) {
;                 const LAS unsigned char* vp = Vb + (32 * dt + r) * A_CVSTR + (32 * mt + 16 * s + 4 * h) * 2;
;                 const s16x4_t lo = *(const LAS s16x4_t*)vp, hi = *(const LAS s16x4_t*)(vp + 16);
;                 oacc[dt] = MFMA32(__builtin_shufflevector(lo, hi, 0, 1, 2, 3, 4, 5, 6, 7), pf, oacc[dt]);
;             }
;         }
;     }
;     l_run += ls;
.Lt1_full:
	ds_read_b128 v[200:203], v72 offset:0
	ds_read_b128 v[204:207], v72 offset:32
	ds_read_b128 v[208:211], v72 offset:64
	ds_read_b128 v[212:215], v72 offset:96
	ds_read2_b64 v[216:219], v73 offset0:0 offset1:2
	ds_read2_b64 v[220:223], v74 offset0:32 offset1:34
	ds_read2_b64 v[224:227], v73 offset0:4 offset1:6
	ds_read2_b64 v[228:231], v74 offset0:36 offset1:38
	s_waitcnt lgkmcnt(7)
	v_mfma_f32_32x32x16_bf16 v[32:47], v[200:203], v[80:83], 0
	ds_read_b128 v[200:203], v72 offset:4608
	s_waitcnt lgkmcnt(7)
	v_mfma_f32_32x32x16_bf16 v[32:47], v[204:207], v[84:87], v[32:47]
	ds_read_b128 v[204:207], v72 offset:4640
	s_waitcnt lgkmcnt(7)
	v_mfma_f32_32x32x16_bf16 v[32:47], v[208:211], v[88:91], v[32:47]
	ds_read_b128 v[208:211], v72 offset:4672
	s_waitcnt lgkmcnt(7)
	v_mfma_f32_32x32x16_bf16 v[32:47], v[212:215], v[92:95], v[32:47]
	ds_read_b128 v[212:215], v72 offset:4704
	s_nop 7
	s_nop 3
	s_waitcnt lgkmcnt(3)
	v_mfma_f32_32x32x16_bf16 v[48:63], v[200:203], v[80:83], 0
	ds_read_b128 v[200:203], v72 offset:9216
	v_exp_f32_e32 v32, v32
	v_exp_f32_e32 v33, v33
	s_waitcnt lgkmcnt(3)
	v_mfma_f32_32x32x16_bf16 v[48:63], v[204:207], v[84:87], v[48:63]
	ds_read_b128 v[204:207], v72 offset:9248
	v_exp_f32_e32 v34, v34
	v_exp_f32_e32 v35, v35
	v_mov_b32_e32 v232, v32
	v_mov_b32_e32 v233, v33
	v_cvt_pk_bf16_f32 v64, v32, v33
	v_exp_f32_e32 v36, v36
	v_exp_f32_e32 v37, v37
	v_add_f32_e32 v232, v232, v34
	v_add_f32_e32 v233, v233, v35
	v_cvt_pk_bf16_f32 v65, v34, v35
	v_exp_f32_e32 v38, v38
	v_exp_f32_e32 v39, v39
	v_add_f32_e32 v232, v232, v36
	v_add_f32_e32 v233, v233, v37
	v_cvt_pk_bf16_f32 v66, v36, v37
	v_add_f32_e32 v232, v232, v38
	v_add_f32_e32 v233, v233, v39
	v_cvt_pk_bf16_f32 v67, v38, v39
	s_waitcnt lgkmcnt(3)
	v_mfma_f32_32x32x16_bf16 v[48:63], v[208:211], v[88:91], v[48:63]
	ds_read_b128 v[208:211], v72 offset:9280
	v_exp_f32_e32 v40, v40
	v_exp_f32_e32 v41, v41
	s_waitcnt lgkmcnt(3)
	v_mfma_f32_32x32x16_bf16 v[48:63], v[212:215], v[92:95], v[48:63]
	ds_read_b128 v[212:215], v72 offset:9312
	v_exp_f32_e32 v42, v42
	v_exp_f32_e32 v43, v43
	v_add_f32_e32 v232, v232, v40
	v_add_f32_e32 v233, v233, v41
	v_cvt_pk_bf16_f32 v68, v40, v41
	v_mfma_f32_32x32x16_bf16 v[0:15], v[216:219], v[64:67], v[0:15]
	ds_read2_b64 v[216:219], v73 offset0:8 offset1:10
	v_exp_f32_e32 v44, v44
	v_exp_f32_e32 v45, v45
	v_add_f32_e32 v232, v232, v42
	v_add_f32_e32 v233, v233, v43
	v_cvt_pk_bf16_f32 v69, v42, v43
	v_mfma_f32_32x32x16_bf16 v[16:31], v[220:223], v[64:67], v[16:31]
	ds_read2_b64 v[220:223], v74 offset0:40 offset1:42
	v_exp_f32_e32 v46, v46
	v_exp_f32_e32 v47, v47
	v_add_f32_e32 v232, v232, v44
	v_add_f32_e32 v233, v233, v45
	v_cvt_pk_bf16_f32 v70, v44, v45
	v_add_f32_e32 v232, v232, v46
	v_add_f32_e32 v233, v233, v47
	v_cvt_pk_bf16_f32 v71, v46, v47
	s_waitcnt lgkmcnt(5)
	v_mfma_f32_32x32x16_bf16 v[32:47], v[200:203], v[80:83], 0
	ds_read_b128 v[200:203], v72 offset:13824
	v_exp_f32_e32 v48, v48
	v_exp_f32_e32 v49, v49
	s_waitcnt lgkmcnt(5)
	v_mfma_f32_32x32x16_bf16 v[32:47], v[204:207], v[84:87], v[32:47]
	ds_read_b128 v[204:207], v72 offset:13856
	v_exp_f32_e32 v50, v50
	v_exp_f32_e32 v51, v51
	v_add_f32_e32 v232, v232, v48
	v_add_f32_e32 v233, v233, v49
	v_cvt_pk_bf16_f32 v64, v48, v49
	v_mfma_f32_32x32x16_bf16 v[0:15], v[224:227], v[68:71], v[0:15]
	ds_read2_b64 v[224:227], v73 offset0:12 offset1:14
	v_exp_f32_e32 v52, v52
	v_exp_f32_e32 v53, v53
	v_add_f32_e32 v232, v232, v50
	v_add_f32_e32 v233, v233, v51
	v_cvt_pk_bf16_f32 v65, v50, v51
	v_mfma_f32_32x32x16_bf16 v[16:31], v[228:231], v[68:71], v[16:31]
	ds_read2_b64 v[228:231], v74 offset0:44 offset1:46
	v_exp_f32_e32 v54, v54
	v_exp_f32_e32 v55, v55
	v_add_f32_e32 v232, v232, v52
	v_add_f32_e32 v233, v233, v53
	v_cvt_pk_bf16_f32 v66, v52, v53
	v_add_f32_e32 v232, v232, v54
	v_add_f32_e32 v233, v233, v55
	v_cvt_pk_bf16_f32 v67, v54, v55
	s_waitcnt lgkmcnt(7)
	v_mfma_f32_32x32x16_bf16 v[32:47], v[208:211], v[88:91], v[32:47]
	ds_read_b128 v[208:211], v72 offset:13888
	v_exp_f32_e32 v56, v56
	v_exp_f32_e32 v57, v57
	s_waitcnt lgkmcnt(7)
	v_mfma_f32_32x32x16_bf16 v[32:47], v[212:215], v[92:95], v[32:47]
	ds_read_b128 v[212:215], v72 offset:13920
	v_exp_f32_e32 v58, v58
	v_exp_f32_e32 v59, v59
	v_add_f32_e32 v232, v232, v56
	v_add_f32_e32 v233, v233, v57
	v_cvt_pk_bf16_f32 v68, v56, v57
	s_waitcnt lgkmcnt(7)
	v_mfma_f32_32x32x16_bf16 v[0:15], v[216:219], v[64:67], v[0:15]
	ds_read2_b64 v[216:219], v73 offset0:16 offset1:18
	v_exp_f32_e32 v60, v60
	v_exp_f32_e32 v61, v61
	v_add_f32_e32 v232, v232, v58
	v_add_f32_e32 v233, v233, v59
	v_cvt_pk_bf16_f32 v69, v58, v59
	s_waitcnt lgkmcnt(7)
	v_mfma_f32_32x32x16_bf16 v[16:31], v[220:223], v[64:67], v[16:31]
	ds_read2_b64 v[220:223], v74 offset0:48 offset1:50
	v_exp_f32_e32 v62, v62
	v_exp_f32_e32 v63, v63
	v_add_f32_e32 v232, v232, v60
	v_add_f32_e32 v233, v233, v61
	v_cvt_pk_bf16_f32 v70, v60, v61
	v_add_f32_e32 v232, v232, v62
	v_add_f32_e32 v233, v233, v63
	v_cvt_pk_bf16_f32 v71, v62, v63
	s_waitcnt lgkmcnt(7)
	v_mfma_f32_32x32x16_bf16 v[48:63], v[200:203], v[80:83], 0
	v_exp_f32_e32 v32, v32
	v_exp_f32_e32 v33, v33
	s_waitcnt lgkmcnt(6)
	v_mfma_f32_32x32x16_bf16 v[48:63], v[204:207], v[84:87], v[48:63]
	v_exp_f32_e32 v34, v34
	v_exp_f32_e32 v35, v35
	v_add_f32_e32 v232, v232, v32
	v_add_f32_e32 v233, v233, v33
	v_cvt_pk_bf16_f32 v64, v32, v33
	s_waitcnt lgkmcnt(5)
	v_mfma_f32_32x32x16_bf16 v[0:15], v[224:227], v[68:71], v[0:15]
	ds_read2_b64 v[224:227], v73 offset0:20 offset1:22
	v_exp_f32_e32 v36, v36
	v_exp_f32_e32 v37, v37
	v_add_f32_e32 v232, v232, v34
	v_add_f32_e32 v233, v233, v35
	v_cvt_pk_bf16_f32 v65, v34, v35
	s_waitcnt lgkmcnt(5)
	v_mfma_f32_32x32x16_bf16 v[16:31], v[228:231], v[68:71], v[16:31]
	ds_read2_b64 v[228:231], v74 offset0:52 offset1:54
	v_exp_f32_e32 v38, v38
	v_exp_f32_e32 v39, v39
	v_add_f32_e32 v232, v232, v36
	v_add_f32_e32 v233, v233, v37
	v_cvt_pk_bf16_f32 v66, v36, v37
	s_cmp_eq_u32 s45, 0
	s_cbranch_scc1 .Lt1_full_nostage
	s_waitcnt vmcnt(3)
	ds_write_b128 v251, v[96:99]
	s_waitcnt vmcnt(2)
	ds_write_b128 v251, v[100:103] offset:9216
	s_waitcnt vmcnt(1)
	ds_write2_b64 v252, v[104:105], v[106:107] offset1:1
	s_waitcnt vmcnt(0)
	ds_write2_b64 v252, v[108:109], v[110:111] offset0:16 offset1:17
	s_mov_b32 s47, 1
; #define LAS __attribute__((address_space(3)))
; #define MFMA32(a, b, c) __builtin_amdgcn_mfma_f32_32x32x16_bf16((a), (b), (c), 0, 0, 0)
; __device__ __forceinline__ float ex2(float x) { return __builtin_amdgcn_exp2f(x); }
; template <int MODE>
; __device__ __forceinline__ void attn_tile(const LAS unsigned char* Kb, const LAS unsigned char* Vb, const bf16x8_t (&qf)[4], f32x16 (&oacc)[2], float& l_run,
;                                           int r, int h, int dlt0, int dlt1, bool hiw) {
;     const unsigned ulim = (MODE == 0) ? 0x80000000u : 512u;
;     float ls = 0.f;
; #pragma unroll
;     for (int mt = 0; mt < 4; ++mt) {
;         if (mt == 0) { if (hiw) __builtin_amdgcn_s_setprio(1); else __builtin_amdgcn_s_setprio(0); }
;         if (mt == 2) { if (hiw) __builtin_amdgcn_s_setprio(0); else __builtin_amdgcn_s_setprio(1); }
;         const int dl = mt < 2 ? dlt0 : dlt1;
;         f32x16 sacc = zero16();
; #pragma unroll
;         for (int ks = 0; ks < 4; ++ks) { const bf16x8_t ka = *(const LAS bf16x8_t*)(Kb + (32 * mt + r) * A_KSTR + 32 * ks + 16 * h); sacc = MFMA32(ka, qf[ks], sacc); }
; #pragma unroll
;         for (int i = 0; i < 16; ++i) {
;             float p;
;             if (MODE == 2) p = ex2(sacc[i]);
;             else if (MODE == 3) p = ex2(sacc[i] + __int_as_float(dl));
;             else { const int ci = 32 * mt + (i & 3) + 8 * (i >> 2); p = ((unsigned)(dl - ci) < ulim) ? ex2(sacc[i]) : 0.f; }
;             sacc[i] = p; ls += p;
;         }
; #pragma unroll
;         for (int s = 0; s < 2; ++s) {
;             const bf16x8_t pf = pack8(sacc, 8 * s);
; #pragma unroll
;             for (int dt = 0; dt < 2; ++dt) {
;                 const LAS unsigned char* vp = Vb + (32 * dt + r) * A_CVSTR + (32 * mt + 16 * s + 4 * h) * 2;
;                 const s16x4_t lo = *(const LAS s16x4_t*)vp, hi = *(const LAS s16x4_t*)(vp + 16);
;                 oacc[dt] = MFMA32(__builtin_shufflevector(lo, hi, 0, 1, 2, 3, 4, 5, 6, 7), pf, oacc[dt]);
;             }
;         }
;     }
;     l_run += ls;
; }
.Lt1_full_nostage:
	v_add_f32_e32 v232, v232, v38
	v_add_f32_e32 v233, v233, v39
	v_cvt_pk_bf16_f32 v67, v38, v39
	s_waitcnt lgkmcnt(5)
	v_mfma_f32_32x32x16_bf16 v[48:63], v[208:211], v[88:91], v[48:63]
	v_exp_f32_e32 v40, v40
	v_exp_f32_e32 v41, v41
	s_waitcnt lgkmcnt(4)
	v_mfma_f32_32x32x16_bf16 v[48:63], v[212:215], v[92:95], v[48:63]
	v_exp_f32_e32 v42, v42
	v_exp_f32_e32 v43, v43
	v_add_f32_e32 v232, v232, v40
	v_add_f32_e32 v233, v233, v41
	v_cvt_pk_bf16_f32 v68, v40, v41
	s_waitcnt lgkmcnt(3)
	v_mfma_f32_32x32x16_bf16 v[0:15], v[216:219], v[64:67], v[0:15]
	ds_read2_b64 v[216:219], v73 offset0:24 offset1:26
	v_exp_f32_e32 v44, v44
	v_exp_f32_e32 v45, v45
	v_add_f32_e32 v232, v232, v42
	v_add_f32_e32 v233, v233, v43
	v_cvt_pk_bf16_f32 v69, v42, v43
	s_waitcnt lgkmcnt(3)
	v_mfma_f32_32x32x16_bf16 v[16:31], v[220:223], v[64:67], v[16:31]
	ds_read2_b64 v[220:223], v74 offset0:56 offset1:58
	v_exp_f32_e32 v46, v46
	v_exp_f32_e32 v47, v47
	v_add_f32_e32 v232, v232, v44
	v_add_f32_e32 v233, v233, v45
	v_cvt_pk_bf16_f32 v70, v44, v45
	v_add_f32_e32 v232, v232, v46
	v_add_f32_e32 v233, v233, v47
	v_cvt_pk_bf16_f32 v71, v46, v47
	v_exp_f32_e32 v48, v48
	v_exp_f32_e32 v49, v49
	v_exp_f32_e32 v50, v50
	v_exp_f32_e32 v51, v51
	v_add_f32_e32 v232, v232, v48
	v_add_f32_e32 v233, v233, v49
	v_cvt_pk_bf16_f32 v64, v48, v49
	s_waitcnt lgkmcnt(3)
	v_mfma_f32_32x32x16_bf16 v[0:15], v[224:227], v[68:71], v[0:15]
	ds_read2_b64 v[224:227], v73 offset0:28 offset1:30
	v_exp_f32_e32 v52, v52
	v_exp_f32_e32 v53, v53
	v_add_f32_e32 v232, v232, v50
	v_add_f32_e32 v233, v233, v51
	v_cvt_pk_bf16_f32 v65, v50, v51
	s_waitcnt lgkmcnt(3)
	v_mfma_f32_32x32x16_bf16 v[16:31], v[228:231], v[68:71], v[16:31]
	ds_read2_b64 v[228:231], v74 offset0:60 offset1:62
	v_exp_f32_e32 v54, v54
	v_exp_f32_e32 v55, v55
	v_add_f32_e32 v232, v232, v52
	v_add_f32_e32 v233, v233, v53
	v_cvt_pk_bf16_f32 v66, v52, v53
	v_add_f32_e32 v232, v232, v54
	v_add_f32_e32 v233, v233, v55
	v_cvt_pk_bf16_f32 v67, v54, v55
	v_exp_f32_e32 v56, v56
	v_exp_f32_e32 v57, v57
	v_exp_f32_e32 v58, v58
	v_exp_f32_e32 v59, v59
	v_add_f32_e32 v232, v232, v56
	v_add_f32_e32 v233, v233, v57
	v_cvt_pk_bf16_f32 v68, v56, v57
	s_waitcnt lgkmcnt(3)
	v_mfma_f32_32x32x16_bf16 v[0:15], v[216:219], v[64:67], v[0:15]
	v_exp_f32_e32 v60, v60
	v_exp_f32_e32 v61, v61
	v_add_f32_e32 v232, v232, v58
	v_add_f32_e32 v233, v233, v59
	v_cvt_pk_bf16_f32 v69, v58, v59
	s_waitcnt lgkmcnt(2)
	v_mfma_f32_32x32x16_bf16 v[16:31], v[220:223], v[64:67], v[16:31]
	v_exp_f32_e32 v62, v62
	v_exp_f32_e32 v63, v63
	v_add_f32_e32 v232, v232, v60
	v_add_f32_e32 v233, v233, v61
	v_cvt_pk_bf16_f32 v70, v60, v61
	v_add_f32_e32 v232, v232, v62
	v_add_f32_e32 v233, v233, v63
	v_cvt_pk_bf16_f32 v71, v62, v63
	s_nop 1
	s_waitcnt lgkmcnt(1)
	v_mfma_f32_32x32x16_bf16 v[0:15], v[224:227], v[68:71], v[0:15]
	s_waitcnt lgkmcnt(0)
	v_mfma_f32_32x32x16_bf16 v[16:31], v[228:231], v[68:71], v[16:31]
	v_add_f32_e32 v232, v232, v233
	v_add_f32_e32 v112, v112, v232
	s_branch .Lt1_join
.Lt1_bias:
	ds_read_b128 v[200:203], v72 offset:0
	ds_read_b128 v[204:207], v72 offset:32
	ds_read_b128 v[208:211], v72 offset:64
	ds_read_b128 v[212:215], v72 offset:96
	ds_read2_b64 v[216:219], v73 offset0:0 offset1:2
	ds_read2_b64 v[220:223], v74 offset0:32 offset1:34
	ds_read2_b64 v[224:227], v73 offset0:4 offset1:6
	ds_read2_b64 v[228:231], v74 offset0:36 offset1:38
	v_bfe_i32 v236, v158, s49, 1
	s_add_i32 s49, s49, 1
	v_bfe_i32 v237, v158, s49, 1
	s_waitcnt lgkmcnt(7)
	v_mfma_f32_32x32x16_bf16 v[32:47], v[200:203], v[80:83], 0
	ds_read_b128 v[200:203], v72 offset:4608
	s_waitcnt lgkmcnt(7)
	v_mfma_f32_32x32x16_bf16 v[32:47], v[204:207], v[84:87], v[32:47]
	ds_read_b128 v[204:207], v72 offset:4640
	s_waitcnt lgkmcnt(7)
	v_mfma_f32_32x32x16_bf16 v[32:47], v[208:211], v[88:91], v[32:47]
	ds_read_b128 v[208:211], v72 offset:4672
	s_waitcnt lgkmcnt(7)
	v_mfma_f32_32x32x16_bf16 v[32:47], v[212:215], v[92:95], v[32:47]
	ds_read_b128 v[212:215], v72 offset:4704
	s_nop 7
	s_nop 3
	s_waitcnt lgkmcnt(3)
	v_mfma_f32_32x32x16_bf16 v[48:63], v[200:203], v[80:83], 0
	ds_read_b128 v[200:203], v72 offset:9216
	v_exp_f32_e32 v32, v32
	v_exp_f32_e32 v33, v33
	s_waitcnt lgkmcnt(3)
	v_mfma_f32_32x32x16_bf16 v[48:63], v[204:207], v[84:87], v[48:63]
	ds_read_b128 v[204:207], v72 offset:9248
	v_exp_f32_e32 v34, v34
	v_exp_f32_e32 v35, v35
	v_mov_b32_e32 v232, v32
	v_mov_b32_e32 v233, v33
	v_cvt_pk_bf16_f32 v64, v32, v33
	v_and_b32_e32 v64, v236, v64
	v_exp_f32_e32 v36, v36
	v_exp_f32_e32 v37, v37
	v_add_f32_e32 v232, v232, v34
	v_add_f32_e32 v233, v233, v35
	v_cvt_pk_bf16_f32 v65, v34, v35
	v_and_b32_e32 v65, v236, v65
	v_exp_f32_e32 v38, v38
	v_exp_f32_e32 v39, v39
	v_add_f32_e32 v232, v232, v36
	v_add_f32_e32 v233, v233, v37
	v_cvt_pk_bf16_f32 v66, v36, v37
	v_and_b32_e32 v66, v236, v66
	v_add_f32_e32 v232, v232, v38
	v_add_f32_e32 v233, v233, v39
	v_cvt_pk_bf16_f32 v67, v38, v39
	v_and_b32_e32 v67, v236, v67
	s_waitcnt lgkmcnt(3)
	v_mfma_f32_32x32x16_bf16 v[48:63], v[208:211], v[88:91], v[48:63]
	ds_read_b128 v[208:211], v72 offset:9280
	v_exp_f32_e32 v40, v40
	v_exp_f32_e32 v41, v41
	s_waitcnt lgkmcnt(3)
; #define LAS __attribute__((address_space(3)))
; #define MFMA32(a, b, c) __builtin_amdgcn_mfma_f32_32x32x16_bf16((a), (b), (c), 0, 0, 0)
; __device__ __forceinline__ float ex2(float x) { return __builtin_amdgcn_exp2f(x); }
; template <int MODE>
; __device__ __forceinline__ void attn_tile(const LAS unsigned char* Kb, const LAS unsigned char* Vb, const bf16x8_t (&qf)[4], f32x16 (&oacc)[2], float& l_run,
;                                           int r, int h, int dlt0, int dlt1, bool hiw) {
;     const unsigned ulim = (MODE == 0) ? 0x80000000u : 512u;
;     float ls = 0.f;
; #pragma unroll
;     for (int mt = 0; mt < 4; ++mt) {
;         if (mt == 0) { if (hiw) __builtin_amdgcn_s_setprio(1); else __builtin_amdgcn_s_setprio(0); }
;         if (mt == 2) { if (hiw) __builtin_amdgcn_s_setprio(0); else __builtin_amdgcn_s_setprio(1); }
;         const int dl = mt < 2 ? dlt0 : dlt1;
;         f32x16 sacc = zero16();
; #pragma unroll
;         for (int ks = 0; ks < 4; ++ks) { const bf16x8_t ka = *(const LAS bf16x8_t*)(Kb + (32 * mt + r) * A_KSTR + 32 * ks + 16 * h); sacc = MFMA32(ka, qf[ks], sacc); }
; #pragma unroll
;         for (int i = 0; i < 16; ++i) {
;             float p;
;             if (MODE == 2) p = ex2(sacc[i]);
;             else if (MODE == 3) p = ex2(sacc[i] + __int_as_float(dl));
;             else { const int ci = 32 * mt + (i & 3) + 8 * (i >> 2); p = ((unsigned)(dl - ci) < ulim) ? ex2(sacc[i]) : 0.f; }
;             sacc[i] = p; ls += p;
;         }
; #pragma unroll
;         for (int s = 0; s < 2; ++s) {
;             const bf16x8_t pf = pack8(sacc, 8 * s);
; #pragma unroll
;             for (int dt = 0; dt < 2; ++dt) {
;                 const LAS unsigned char* vp = Vb + (32 * dt + r) * A_CVSTR + (32 * mt + 16 * s + 4 * h) * 2;
;                 const s16x4_t lo = *(const LAS s16x4_t*)vp, hi = *(const LAS s16x4_t*)(vp + 16);
;                 oacc[dt] = MFMA32(__builtin_shufflevector(lo, hi, 0, 1, 2, 3, 4, 5, 6, 7), pf, oacc[dt]);
;             }
;         }
;     }
;     l_run += ls;
	v_mfma_f32_32x32x16_bf16 v[48:63], v[212:215], v[92:95], v[48:63]
	ds_read_b128 v[212:215], v72 offset:9312
	v_exp_f32_e32 v42, v42
	v_exp_f32_e32 v43, v43
	v_add_f32_e32 v232, v232, v40
	v_add_f32_e32 v233, v233, v41
	v_cvt_pk_bf16_f32 v68, v40, v41
	v_and_b32_e32 v68, v236, v68
	v_mfma_f32_32x32x16_bf16 v[0:15], v[216:219], v[64:67], v[0:15]
	ds_read2_b64 v[216:219], v73 offset0:8 offset1:10
	v_exp_f32_e32 v44, v44
	v_exp_f32_e32 v45, v45
	v_add_f32_e32 v232, v232, v42
	v_add_f32_e32 v233, v233, v43
	v_cvt_pk_bf16_f32 v69, v42, v43
	v_and_b32_e32 v69, v236, v69
	v_mfma_f32_32x32x16_bf16 v[16:31], v[220:223], v[64:67], v[16:31]
	ds_read2_b64 v[220:223], v74 offset0:40 offset1:42
	v_exp_f32_e32 v46, v46
	v_exp_f32_e32 v47, v47
	v_add_f32_e32 v232, v232, v44
	v_add_f32_e32 v233, v233, v45
	v_cvt_pk_bf16_f32 v70, v44, v45
	v_and_b32_e32 v70, v236, v70
	v_add_f32_e32 v232, v232, v46
	v_add_f32_e32 v233, v233, v47
	v_cvt_pk_bf16_f32 v71, v46, v47
	v_and_b32_e32 v71, v236, v71
	s_waitcnt lgkmcnt(5)
	v_mfma_f32_32x32x16_bf16 v[32:47], v[200:203], v[80:83], 0
	ds_read_b128 v[200:203], v72 offset:13824
	v_exp_f32_e32 v48, v48
	v_exp_f32_e32 v49, v49
	s_waitcnt lgkmcnt(5)
	v_mfma_f32_32x32x16_bf16 v[32:47], v[204:207], v[84:87], v[32:47]
	ds_read_b128 v[204:207], v72 offset:13856
	v_exp_f32_e32 v50, v50
	v_exp_f32_e32 v51, v51
	v_add_f32_e32 v232, v232, v48
	v_add_f32_e32 v233, v233, v49
	v_cvt_pk_bf16_f32 v64, v48, v49
	v_and_b32_e32 v64, v236, v64
	v_mfma_f32_32x32x16_bf16 v[0:15], v[224:227], v[68:71], v[0:15]
	ds_read2_b64 v[224:227], v73 offset0:12 offset1:14
	v_exp_f32_e32 v52, v52
	v_exp_f32_e32 v53, v53
	v_add_f32_e32 v232, v232, v50
	v_add_f32_e32 v233, v233, v51
	v_cvt_pk_bf16_f32 v65, v50, v51
	v_and_b32_e32 v65, v236, v65
	v_mfma_f32_32x32x16_bf16 v[16:31], v[228:231], v[68:71], v[16:31]
	ds_read2_b64 v[228:231], v74 offset0:44 offset1:46
	v_exp_f32_e32 v54, v54
	v_exp_f32_e32 v55, v55
	v_add_f32_e32 v232, v232, v52
	v_add_f32_e32 v233, v233, v53
	v_cvt_pk_bf16_f32 v66, v52, v53
	v_and_b32_e32 v66, v236, v66
	v_add_f32_e32 v232, v232, v54
	v_add_f32_e32 v233, v233, v55
	v_cvt_pk_bf16_f32 v67, v54, v55
	v_and_b32_e32 v67, v236, v67
	s_waitcnt lgkmcnt(7)
	v_mfma_f32_32x32x16_bf16 v[32:47], v[208:211], v[88:91], v[32:47]
	ds_read_b128 v[208:211], v72 offset:13888
	v_exp_f32_e32 v56, v56
	v_exp_f32_e32 v57, v57
	s_waitcnt lgkmcnt(7)
	v_mfma_f32_32x32x16_bf16 v[32:47], v[212:215], v[92:95], v[32:47]
	ds_read_b128 v[212:215], v72 offset:13920
	v_exp_f32_e32 v58, v58
	v_exp_f32_e32 v59, v59
	v_add_f32_e32 v232, v232, v56
	v_add_f32_e32 v233, v233, v57
	v_cvt_pk_bf16_f32 v68, v56, v57
	v_and_b32_e32 v68, v236, v68
	s_waitcnt lgkmcnt(7)
	v_mfma_f32_32x32x16_bf16 v[0:15], v[216:219], v[64:67], v[0:15]
	ds_read2_b64 v[216:219], v73 offset0:16 offset1:18
	v_exp_f32_e32 v60, v60
	v_exp_f32_e32 v61, v61
	v_add_f32_e32 v232, v232, v58
	v_add_f32_e32 v233, v233, v59
	v_cvt_pk_bf16_f32 v69, v58, v59
	v_and_b32_e32 v69, v236, v69
	s_waitcnt lgkmcnt(7)
	v_mfma_f32_32x32x16_bf16 v[16:31], v[220:223], v[64:67], v[16:31]
	ds_read2_b64 v[220:223], v74 offset0:48 offset1:50
	v_exp_f32_e32 v62, v62
	v_exp_f32_e32 v63, v63
	v_add_f32_e32 v232, v232, v60
	v_add_f32_e32 v233, v233, v61
	v_cvt_pk_bf16_f32 v70, v60, v61
	v_and_b32_e32 v70, v236, v70
	v_add_f32_e32 v232, v232, v62
	v_add_f32_e32 v233, v233, v63
	v_cvt_pk_bf16_f32 v71, v62, v63
	v_and_b32_e32 v71, v236, v71
	s_waitcnt lgkmcnt(7)
	v_mfma_f32_32x32x16_bf16 v[48:63], v[200:203], v[80:83], 0
	v_exp_f32_e32 v32, v32
	v_exp_f32_e32 v33, v33
	s_waitcnt lgkmcnt(6)
	v_mfma_f32_32x32x16_bf16 v[48:63], v[204:207], v[84:87], v[48:63]
	v_exp_f32_e32 v34, v34
	v_exp_f32_e32 v35, v35
	v_mov_b32_e32 v234, v32
	v_mov_b32_e32 v235, v33
	v_cvt_pk_bf16_f32 v64, v32, v33
	v_and_b32_e32 v64, v237, v64
	s_waitcnt lgkmcnt(5)
	v_mfma_f32_32x32x16_bf16 v[0:15], v[224:227], v[68:71], v[0:15]
	ds_read2_b64 v[224:227], v73 offset0:20 offset1:22
	v_exp_f32_e32 v36, v36
	v_exp_f32_e32 v37, v37
	v_add_f32_e32 v234, v234, v34
	v_add_f32_e32 v235, v235, v35
	v_cvt_pk_bf16_f32 v65, v34, v35
	v_and_b32_e32 v65, v237, v65
	s_waitcnt lgkmcnt(5)
	v_mfma_f32_32x32x16_bf16 v[16:31], v[228:231], v[68:71], v[16:31]
	ds_read2_b64 v[228:231], v74 offset0:52 offset1:54
	v_exp_f32_e32 v38, v38
	v_exp_f32_e32 v39, v39
	v_add_f32_e32 v234, v234, v36
	v_add_f32_e32 v235, v235, v37
	v_cvt_pk_bf16_f32 v66, v36, v37
	v_and_b32_e32 v66, v237, v66
	s_cmp_eq_u32 s45, 0
	s_cbranch_scc1 .Lt1_bias_nostage
	s_waitcnt vmcnt(3)
	ds_write_b128 v251, v[96:99]
	s_waitcnt vmcnt(2)
	ds_write_b128 v251, v[100:103] offset:9216
	s_waitcnt vmcnt(1)
	ds_write2_b64 v252, v[104:105], v[106:107] offset1:1
	s_waitcnt vmcnt(0)
	ds_write2_b64 v252, v[108:109], v[110:111] offset0:16 offset1:17
	s_mov_b32 s47, 1
; #define LAS __attribute__((address_space(3)))
; #define MFMA32(a, b, c) __builtin_amdgcn_mfma_f32_32x32x16_bf16((a), (b), (c), 0, 0, 0)
; __device__ __forceinline__ float ex2(float x) { return __builtin_amdgcn_exp2f(x); }
; template <int MODE>
; __device__ __forceinline__ void attn_tile(const LAS unsigned char* Kb, const LAS unsigned char* Vb, const bf16x8_t (&qf)[4], f32x16 (&oacc)[2], float& l_run,
;                                           int r, int h, int dlt0, int dlt1, bool hiw) {
;     const unsigned ulim = (MODE == 0) ? 0x80000000u : 512u;
;     float ls = 0.f;
; #pragma unroll
;     for (int mt = 0; mt < 4; ++mt) {
;         if (mt == 0) { if (hiw) __builtin_amdgcn_s_setprio(1); else __builtin_amdgcn_s_setprio(0); }
;         if (mt == 2) { if (hiw) __builtin_amdgcn_s_setprio(0); else __builtin_amdgcn_s_setprio(1); }
;         const int dl = mt < 2 ? dlt0 : dlt1;
;         f32x16 sacc = zero16();
; #pragma unroll
;         for (int ks = 0; ks < 4; ++ks) { const bf16x8_t ka = *(const LAS bf16x8_t*)(Kb + (32 * mt + r) * A_KSTR + 32 * ks + 16 * h); sacc = MFMA32(ka, qf[ks], sacc); }
; #pragma unroll
;         for (int i = 0; i < 16; ++i) {
;             float p;
;             if (MODE == 2) p = ex2(sacc[i]);
;             else if (MODE == 3) p = ex2(sacc[i] + __int_as_float(dl));
;             else { const int ci = 32 * mt + (i & 3) + 8 * (i >> 2); p = ((unsigned)(dl - ci) < ulim) ? ex2(sacc[i]) : 0.f; }
;             sacc[i] = p; ls += p;
;         }
; #pragma unroll
;         for (int s = 0; s < 2; ++s) {
;             const bf16x8_t pf = pack8(sacc, 8 * s);
; #pragma unroll
;             for (int dt = 0; dt < 2; ++dt) {
;                 const LAS unsigned char* vp = Vb + (32 * dt + r) * A_CVSTR + (32 * mt + 16 * s + 4 * h) * 2;
;                 const s16x4_t lo = *(const LAS s16x4_t*)vp, hi = *(const LAS s16x4_t*)(vp + 16);
;                 oacc[dt] = MFMA32(__builtin_shufflevector(lo, hi, 0, 1, 2, 3, 4, 5, 6, 7), pf, oacc[dt]);
;             }
;         }
;     }
;     l_run += ls;
; }
.Lt1_bias_nostage:
	v_add_f32_e32 v234, v234, v38
	v_add_f32_e32 v235, v235, v39
	v_cvt_pk_bf16_f32 v67, v38, v39
	v_and_b32_e32 v67, v237, v67
	s_waitcnt lgkmcnt(5)
	v_mfma_f32_32x32x16_bf16 v[48:63], v[208:211], v[88:91], v[48:63]
	v_exp_f32_e32 v40, v40
	v_exp_f32_e32 v41, v41
	s_waitcnt lgkmcnt(4)
	v_mfma_f32_32x32x16_bf16 v[48:63], v[212:215], v[92:95], v[48:63]
	v_exp_f32_e32 v42, v42
	v_exp_f32_e32 v43, v43
	v_add_f32_e32 v234, v234, v40
	v_add_f32_e32 v235, v235, v41
	v_cvt_pk_bf16_f32 v68, v40, v41
	v_and_b32_e32 v68, v237, v68
	s_waitcnt lgkmcnt(3)
	v_mfma_f32_32x32x16_bf16 v[0:15], v[216:219], v[64:67], v[0:15]
	ds_read2_b64 v[216:219], v73 offset0:24 offset1:26
	v_exp_f32_e32 v44, v44
	v_exp_f32_e32 v45, v45
	v_add_f32_e32 v234, v234, v42
	v_add_f32_e32 v235, v235, v43
	v_cvt_pk_bf16_f32 v69, v42, v43
	v_and_b32_e32 v69, v237, v69
	s_waitcnt lgkmcnt(3)
	v_mfma_f32_32x32x16_bf16 v[16:31], v[220:223], v[64:67], v[16:31]
	ds_read2_b64 v[220:223], v74 offset0:56 offset1:58
	v_exp_f32_e32 v46, v46
	v_exp_f32_e32 v47, v47
	v_add_f32_e32 v234, v234, v44
	v_add_f32_e32 v235, v235, v45
	v_cvt_pk_bf16_f32 v70, v44, v45
	v_and_b32_e32 v70, v237, v70
	v_add_f32_e32 v234, v234, v46
	v_add_f32_e32 v235, v235, v47
	v_cvt_pk_bf16_f32 v71, v46, v47
	v_and_b32_e32 v71, v237, v71
	v_exp_f32_e32 v48, v48
	v_exp_f32_e32 v49, v49
	v_exp_f32_e32 v50, v50
	v_exp_f32_e32 v51, v51
	v_add_f32_e32 v234, v234, v48
	v_add_f32_e32 v235, v235, v49
	v_cvt_pk_bf16_f32 v64, v48, v49
	v_and_b32_e32 v64, v237, v64
	s_waitcnt lgkmcnt(3)
	v_mfma_f32_32x32x16_bf16 v[0:15], v[224:227], v[68:71], v[0:15]
	ds_read2_b64 v[224:227], v73 offset0:28 offset1:30
	v_exp_f32_e32 v52, v52
	v_exp_f32_e32 v53, v53
	v_add_f32_e32 v234, v234, v50
	v_add_f32_e32 v235, v235, v51
	v_cvt_pk_bf16_f32 v65, v50, v51
	v_and_b32_e32 v65, v237, v65
	s_waitcnt lgkmcnt(3)
	v_mfma_f32_32x32x16_bf16 v[16:31], v[228:231], v[68:71], v[16:31]
	ds_read2_b64 v[228:231], v74 offset0:60 offset1:62
	v_exp_f32_e32 v54, v54
	v_exp_f32_e32 v55, v55
	v_add_f32_e32 v234, v234, v52
	v_add_f32_e32 v235, v235, v53
	v_cvt_pk_bf16_f32 v66, v52, v53
	v_and_b32_e32 v66, v237, v66
	v_add_f32_e32 v234, v234, v54
	v_add_f32_e32 v235, v235, v55
	v_cvt_pk_bf16_f32 v67, v54, v55
	v_and_b32_e32 v67, v237, v67
	v_exp_f32_e32 v56, v56
	v_exp_f32_e32 v57, v57
	v_exp_f32_e32 v58, v58
	v_exp_f32_e32 v59, v59
	v_add_f32_e32 v234, v234, v56
	v_add_f32_e32 v235, v235, v57
	v_cvt_pk_bf16_f32 v68, v56, v57
	v_and_b32_e32 v68, v237, v68
	s_waitcnt lgkmcnt(3)
	v_mfma_f32_32x32x16_bf16 v[0:15], v[216:219], v[64:67], v[0:15]
	v_exp_f32_e32 v60, v60
	v_exp_f32_e32 v61, v61
	v_add_f32_e32 v234, v234, v58
	v_add_f32_e32 v235, v235, v59
	v_cvt_pk_bf16_f32 v69, v58, v59
	v_and_b32_e32 v69, v237, v69
	s_waitcnt lgkmcnt(2)
	v_mfma_f32_32x32x16_bf16 v[16:31], v[220:223], v[64:67], v[16:31]
	v_exp_f32_e32 v62, v62
	v_exp_f32_e32 v63, v63
	v_add_f32_e32 v234, v234, v60
	v_add_f32_e32 v235, v235, v61
	v_cvt_pk_bf16_f32 v70, v60, v61
	v_and_b32_e32 v70, v237, v70
	v_add_f32_e32 v234, v234, v62
	v_add_f32_e32 v235, v235, v63
	v_cvt_pk_bf16_f32 v71, v62, v63
	v_and_b32_e32 v71, v237, v71
	s_nop 1
	s_waitcnt lgkmcnt(1)
	v_mfma_f32_32x32x16_bf16 v[0:15], v[224:227], v[68:71], v[0:15]
	s_waitcnt lgkmcnt(0)
	v_mfma_f32_32x32x16_bf16 v[16:31], v[228:231], v[68:71], v[16:31]
	v_add_f32_e32 v232, v232, v233
	v_add_f32_e32 v234, v234, v235
	v_and_b32_e32 v239, 1.0, v236
	v_and_b32_e32 v240, 1.0, v237
	v_fmac_f32_e32 v112, v232, v239
	v_fmac_f32_e32 v112, v234, v240
	s_branch .Lt1_join

; #define LAS __attribute__((address_space(3)))
; #define MFMA32(a, b, c) __builtin_amdgcn_mfma_f32_32x32x16_bf16((a), (b), (c), 0, 0, 0)
; __device__ __forceinline__ float ex2(float x) { return __builtin_amdgcn_exp2f(x); }
; template <int MODE>
; __device__ __forceinline__ void attn_tile(const LAS unsigned char* Kb, const LAS unsigned char* Vb, const bf16x8_t (&qf)[4], f32x16 (&oacc)[2], float& l_run,
;                                           int r, int h, int dlt0, int dlt1, bool hiw) {
;     const unsigned ulim = (MODE == 0) ? 0x80000000u : 512u;
;     float ls = 0.f;
; #pragma unroll
;     for (int mt = 0; mt < 4; ++mt) {
;         if (mt == 0) { if (hiw) __builtin_amdgcn_s_setprio(1); else __builtin_amdgcn_s_setprio(0); }
;         if (mt == 2) { if (hiw) __builtin_amdgcn_s_setprio(0); else __builtin_amdgcn_s_setprio(1); }
;         const int dl = mt < 2 ? dlt0 : dlt1;
;         f32x16 sacc = zero16();
; #pragma unroll
;         for (int ks = 0; ks < 4; ++ks) { const bf16x8_t ka = *(const LAS bf16x8_t*)(Kb + (32 * mt + r) * A_KSTR + 32 * ks + 16 * h); sacc = MFMA32(ka, qf[ks], sacc); }
; #pragma unroll
;         for (int i = 0; i < 16; ++i) {
;             float p;
;             if (MODE == 2) p = ex2(sacc[i]);
;             else if (MODE == 3) p = ex2(sacc[i] + __int_as_float(dl));
;             else { const int ci = 32 * mt + (i & 3) + 8 * (i >> 2); p = ((unsigned)(dl - ci) < ulim) ? ex2(sacc[i]) : 0.f; }
;             sacc[i] = p; ls += p;
;         }
; #pragma unroll
;         for (int s = 0; s < 2; ++s) {
;             const bf16x8_t pf = pack8(sacc, 8 * s);
; #pragma unroll
;             for (int dt = 0; dt < 2; ++dt) {
;                 const LAS unsigned char* vp = Vb + (32 * dt + r) * A_CVSTR + (32 * mt + 16 * s + 4 * h) * 2;
;                 const s16x4_t lo = *(const LAS s16x4_t*)vp, hi = *(const LAS s16x4_t*)(vp + 16);
;                 oacc[dt] = MFMA32(__builtin_shufflevector(lo, hi, 0, 1, 2, 3, 4, 5, 6, 7), pf, oacc[dt]);
;             }
;         }
;     }
;     l_run += ls;
.Lt1_d1:
	ds_read_b128 v[200:203], v72 offset:0
	ds_read_b128 v[204:207], v72 offset:32
	ds_read_b128 v[208:211], v72 offset:64
	ds_read_b128 v[212:215], v72 offset:96
	ds_read2_b64 v[216:219], v73 offset0:0 offset1:2
	ds_read2_b64 v[220:223], v74 offset0:32 offset1:34
	ds_read2_b64 v[224:227], v73 offset0:4 offset1:6
	ds_read2_b64 v[228:231], v74 offset0:36 offset1:38
	s_waitcnt lgkmcnt(7)
	v_mfma_f32_32x32x16_bf16 v[32:47], v[200:203], v[80:83], 0
	ds_read_b128 v[200:203], v72 offset:4608
	s_waitcnt lgkmcnt(7)
	v_mfma_f32_32x32x16_bf16 v[32:47], v[204:207], v[84:87], v[32:47]
	ds_read_b128 v[204:207], v72 offset:4640
	s_waitcnt lgkmcnt(7)
	v_mfma_f32_32x32x16_bf16 v[32:47], v[208:211], v[88:91], v[32:47]
	ds_read_b128 v[208:211], v72 offset:4672
	s_waitcnt lgkmcnt(7)
	v_mfma_f32_32x32x16_bf16 v[32:47], v[212:215], v[92:95], v[32:47]
	ds_read_b128 v[212:215], v72 offset:4704
	s_nop 7
	s_nop 3
	s_waitcnt lgkmcnt(3)
	v_mfma_f32_32x32x16_bf16 v[48:63], v[200:203], v[80:83], 0
	v_exp_f32_e32 v32, v32
	v_exp_f32_e32 v33, v33
	s_waitcnt lgkmcnt(2)
	v_mfma_f32_32x32x16_bf16 v[48:63], v[204:207], v[84:87], v[48:63]
	v_exp_f32_e32 v34, v34
	v_exp_f32_e32 v35, v35
	v_mov_b32_e32 v232, v32
	v_mov_b32_e32 v233, v33
	v_cvt_pk_bf16_f32 v64, v32, v33
	v_exp_f32_e32 v36, v36
	v_exp_f32_e32 v37, v37
	v_add_f32_e32 v232, v232, v34
	v_add_f32_e32 v233, v233, v35
	v_cvt_pk_bf16_f32 v65, v34, v35
	v_exp_f32_e32 v38, v38
	v_exp_f32_e32 v39, v39
	v_add_f32_e32 v232, v232, v36
	v_add_f32_e32 v233, v233, v37
	v_cvt_pk_bf16_f32 v66, v36, v37
	s_cmp_eq_u32 s45, 0
	s_cbranch_scc1 .Lt1_d1_nostage
	s_waitcnt vmcnt(3)
	ds_write_b128 v251, v[96:99]
	s_waitcnt vmcnt(2)
	ds_write_b128 v251, v[100:103] offset:9216
	s_waitcnt vmcnt(1)
	ds_write2_b64 v252, v[104:105], v[106:107] offset1:1
	s_waitcnt vmcnt(0)
	ds_write2_b64 v252, v[108:109], v[110:111] offset0:16 offset1:17
	s_mov_b32 s47, 1
.Lt1_d1_nostage:
	v_add_f32_e32 v232, v232, v38
	v_add_f32_e32 v233, v233, v39
	v_cvt_pk_bf16_f32 v67, v38, v39
	s_waitcnt lgkmcnt(1)
	v_mfma_f32_32x32x16_bf16 v[48:63], v[208:211], v[88:91], v[48:63]
	v_exp_f32_e32 v40, v40
	v_exp_f32_e32 v41, v41
	s_waitcnt lgkmcnt(0)
	v_mfma_f32_32x32x16_bf16 v[48:63], v[212:215], v[92:95], v[48:63]
	v_exp_f32_e32 v42, v42
	v_exp_f32_e32 v43, v43
	v_add_f32_e32 v232, v232, v40
	v_add_f32_e32 v233, v233, v41
	v_cvt_pk_bf16_f32 v68, v40, v41
	v_mfma_f32_32x32x16_bf16 v[0:15], v[216:219], v[64:67], v[0:15]
	ds_read2_b64 v[216:219], v73 offset0:8 offset1:10
	v_exp_f32_e32 v44, v44
	v_exp_f32_e32 v45, v45
	v_add_f32_e32 v232, v232, v42
	v_add_f32_e32 v233, v233, v43
	v_cvt_pk_bf16_f32 v69, v42, v43
	v_mfma_f32_32x32x16_bf16 v[16:31], v[220:223], v[64:67], v[16:31]
	ds_read2_b64 v[220:223], v74 offset0:40 offset1:42
	v_exp_f32_e32 v46, v46
	v_exp_f32_e32 v47, v47
	v_add_f32_e32 v232, v232, v44
	v_add_f32_e32 v233, v233, v45
	v_cvt_pk_bf16_f32 v70, v44, v45
	v_add_f32_e32 v232, v232, v46
	v_add_f32_e32 v233, v233, v47
	v_cvt_pk_bf16_f32 v71, v46, v47
	v_cmp_le_i32_e64 s[0:1], 0, v250
	v_cmp_le_i32_e64 s[4:5], 1, v250
	v_exp_f32_e32 v48, v48
	v_exp_f32_e32 v49, v49
	v_cmp_le_i32_e64 s[6:7], 2, v250
	v_cmp_le_i32_e64 s[48:49], 3, v250
	v_exp_f32_e32 v50, v50
	v_exp_f32_e32 v51, v51
	v_cndmask_b32_e64 v48, 0, v48, s[0:1]
	v_cndmask_b32_e64 v49, 0, v49, s[4:5]
	v_add_f32_e32 v232, v232, v48
	v_add_f32_e32 v233, v233, v49
	v_cvt_pk_bf16_f32 v64, v48, v49
	v_mfma_f32_32x32x16_bf16 v[0:15], v[224:227], v[68:71], v[0:15]
	ds_read2_b64 v[224:227], v73 offset0:12 offset1:14
	v_cmp_le_i32_e64 s[0:1], 8, v250
	v_cmp_le_i32_e64 s[4:5], 9, v250
	v_exp_f32_e32 v52, v52
	v_exp_f32_e32 v53, v53
	v_cndmask_b32_e64 v50, 0, v50, s[6:7]
	v_cndmask_b32_e64 v51, 0, v51, s[48:49]
	v_add_f32_e32 v232, v232, v50
	v_add_f32_e32 v233, v233, v51
	v_cvt_pk_bf16_f32 v65, v50, v51
	v_mfma_f32_32x32x16_bf16 v[16:31], v[228:231], v[68:71], v[16:31]
	ds_read2_b64 v[228:231], v74 offset0:44 offset1:46
	v_cmp_le_i32_e64 s[6:7], 10, v250
	v_cmp_le_i32_e64 s[48:49], 11, v250
	v_exp_f32_e32 v54, v54
	v_exp_f32_e32 v55, v55
	v_cndmask_b32_e64 v52, 0, v52, s[0:1]
	v_cndmask_b32_e64 v53, 0, v53, s[4:5]
	v_add_f32_e32 v232, v232, v52
	v_add_f32_e32 v233, v233, v53
	v_cvt_pk_bf16_f32 v66, v52, v53
	v_cndmask_b32_e64 v54, 0, v54, s[6:7]
	v_cndmask_b32_e64 v55, 0, v55, s[48:49]
	v_add_f32_e32 v232, v232, v54
	v_add_f32_e32 v233, v233, v55
	v_cvt_pk_bf16_f32 v67, v54, v55
	v_cmp_le_i32_e64 s[0:1], 16, v250
	v_cmp_le_i32_e64 s[4:5], 17, v250
	v_exp_f32_e32 v56, v56
	v_exp_f32_e32 v57, v57
	v_cmp_le_i32_e64 s[6:7], 18, v250
	v_cmp_le_i32_e64 s[48:49], 19, v250
	v_exp_f32_e32 v58, v58
	v_exp_f32_e32 v59, v59
	v_cndmask_b32_e64 v56, 0, v56, s[0:1]
	v_cndmask_b32_e64 v57, 0, v57, s[4:5]
	v_add_f32_e32 v232, v232, v56
	v_add_f32_e32 v233, v233, v57
	v_cvt_pk_bf16_f32 v68, v56, v57
	s_waitcnt lgkmcnt(3)
	v_mfma_f32_32x32x16_bf16 v[0:15], v[216:219], v[64:67], v[0:15]
	v_cmp_le_i32_e64 s[0:1], 24, v250
	v_cmp_le_i32_e64 s[4:5], 25, v250
	v_exp_f32_e32 v60, v60
	v_exp_f32_e32 v61, v61
	v_cndmask_b32_e64 v58, 0, v58, s[6:7]
	v_cndmask_b32_e64 v59, 0, v59, s[48:49]
	v_add_f32_e32 v232, v232, v58
	v_add_f32_e32 v233, v233, v59
	v_cvt_pk_bf16_f32 v69, v58, v59
	s_waitcnt lgkmcnt(2)
	v_mfma_f32_32x32x16_bf16 v[16:31], v[220:223], v[64:67], v[16:31]
	v_cmp_le_i32_e64 s[6:7], 26, v250
	v_cmp_le_i32_e64 s[48:49], 27, v250
	v_exp_f32_e32 v62, v62
	v_exp_f32_e32 v63, v63
	v_cndmask_b32_e64 v60, 0, v60, s[0:1]
	v_cndmask_b32_e64 v61, 0, v61, s[4:5]
	v_add_f32_e32 v232, v232, v60
	v_add_f32_e32 v233, v233, v61
	v_cvt_pk_bf16_f32 v70, v60, v61
	v_cndmask_b32_e64 v62, 0, v62, s[6:7]
	v_cndmask_b32_e64 v63, 0, v63, s[48:49]
	v_add_f32_e32 v232, v232, v62
	v_add_f32_e32 v233, v233, v63
	v_cvt_pk_bf16_f32 v71, v62, v63
	s_nop 1
	s_waitcnt lgkmcnt(1)
	v_mfma_f32_32x32x16_bf16 v[0:15], v[224:227], v[68:71], v[0:15]
	s_waitcnt lgkmcnt(0)
	v_mfma_f32_32x32x16_bf16 v[16:31], v[228:231], v[68:71], v[16:31]
	v_add_f32_e32 v232, v232, v233
	v_add_f32_e32 v112, v112, v232
	s_branch .Lt1_join
; #define LAS __attribute__((address_space(3)))
; #define MFMA32(a, b, c) __builtin_amdgcn_mfma_f32_32x32x16_bf16((a), (b), (c), 0, 0, 0)
; __device__ __forceinline__ float ex2(float x) { return __builtin_amdgcn_exp2f(x); }
; template <int MODE>
; __device__ __forceinline__ void attn_tile(const LAS unsigned char* Kb, const LAS unsigned char* Vb, const bf16x8_t (&qf)[4], f32x16 (&oacc)[2], float& l_run,
;                                           int r, int h, int dlt0, int dlt1, bool hiw) {
;     const unsigned ulim = (MODE == 0) ? 0x80000000u : 512u;
;     float ls = 0.f;
; #pragma unroll
;     for (int mt = 0; mt < 4; ++mt) {
;         if (mt == 0) { if (hiw) __builtin_amdgcn_s_setprio(1); else __builtin_amdgcn_s_setprio(0); }
;         if (mt == 2) { if (hiw) __builtin_amdgcn_s_setprio(0); else __builtin_amdgcn_s_setprio(1); }
;         const int dl = mt < 2 ? dlt0 : dlt1;
;         f32x16 sacc = zero16();
; #pragma unroll
;         for (int ks = 0; ks < 4; ++ks) { const bf16x8_t ka = *(const LAS bf16x8_t*)(Kb + (32 * mt + r) * A_KSTR + 32 * ks + 16 * h); sacc = MFMA32(ka, qf[ks], sacc); }
; #pragma unroll
;         for (int i = 0; i < 16; ++i) {
;             float p;
;             if (MODE == 2) p = ex2(sacc[i]);
;             else if (MODE == 3) p = ex2(sacc[i] + __int_as_float(dl));
;             else { const int ci = 32 * mt + (i & 3) + 8 * (i >> 2); p = ((unsigned)(dl - ci) < ulim) ? ex2(sacc[i]) : 0.f; }
;             sacc[i] = p; ls += p;
;         }
; #pragma unroll
;         for (int s = 0; s < 2; ++s) {
;             const bf16x8_t pf = pack8(sacc, 8 * s);
; #pragma unroll
;             for (int dt = 0; dt < 2; ++dt) {
;                 const LAS unsigned char* vp = Vb + (32 * dt + r) * A_CVSTR + (32 * mt + 16 * s + 4 * h) * 2;
;                 const s16x4_t lo = *(const LAS s16x4_t*)vp, hi = *(const LAS s16x4_t*)(vp + 16);
;                 oacc[dt] = MFMA32(__builtin_shufflevector(lo, hi, 0, 1, 2, 3, 4, 5, 6, 7), pf, oacc[dt]);
;             }
;         }
;     }
;     l_run += ls;
.Lt1_d2:
	ds_read_b128 v[200:203], v72 offset:0
	ds_read_b128 v[204:207], v72 offset:32
	ds_read_b128 v[208:211], v72 offset:64
	ds_read_b128 v[212:215], v72 offset:96
	ds_read2_b64 v[216:219], v73 offset0:0 offset1:2
	ds_read2_b64 v[220:223], v74 offset0:32 offset1:34
	ds_read2_b64 v[224:227], v73 offset0:4 offset1:6
	ds_read2_b64 v[228:231], v74 offset0:36 offset1:38
	s_waitcnt lgkmcnt(7)
	v_mfma_f32_32x32x16_bf16 v[32:47], v[200:203], v[80:83], 0
	ds_read_b128 v[200:203], v72 offset:4608
	s_waitcnt lgkmcnt(7)
	v_mfma_f32_32x32x16_bf16 v[32:47], v[204:207], v[84:87], v[32:47]
	ds_read_b128 v[204:207], v72 offset:4640
	s_waitcnt lgkmcnt(7)
	v_mfma_f32_32x32x16_bf16 v[32:47], v[208:211], v[88:91], v[32:47]
	ds_read_b128 v[208:211], v72 offset:4672
	s_waitcnt lgkmcnt(7)
	v_mfma_f32_32x32x16_bf16 v[32:47], v[212:215], v[92:95], v[32:47]
	ds_read_b128 v[212:215], v72 offset:4704
	s_nop 7
	s_nop 3
	s_waitcnt lgkmcnt(3)
	v_mfma_f32_32x32x16_bf16 v[48:63], v[200:203], v[80:83], 0
	ds_read_b128 v[200:203], v72 offset:9216
	v_exp_f32_e32 v32, v32
	v_exp_f32_e32 v33, v33
	s_waitcnt lgkmcnt(3)
	v_mfma_f32_32x32x16_bf16 v[48:63], v[204:207], v[84:87], v[48:63]
	ds_read_b128 v[204:207], v72 offset:9248
	v_exp_f32_e32 v34, v34
	v_exp_f32_e32 v35, v35
	v_mov_b32_e32 v232, v32
	v_mov_b32_e32 v233, v33
	v_cvt_pk_bf16_f32 v64, v32, v33
	v_exp_f32_e32 v36, v36
	v_exp_f32_e32 v37, v37
	v_add_f32_e32 v232, v232, v34
	v_add_f32_e32 v233, v233, v35
	v_cvt_pk_bf16_f32 v65, v34, v35
	v_exp_f32_e32 v38, v38
	v_exp_f32_e32 v39, v39
	v_add_f32_e32 v232, v232, v36
	v_add_f32_e32 v233, v233, v37
	v_cvt_pk_bf16_f32 v66, v36, v37
	v_add_f32_e32 v232, v232, v38
	v_add_f32_e32 v233, v233, v39
	v_cvt_pk_bf16_f32 v67, v38, v39
	s_waitcnt lgkmcnt(3)
	v_mfma_f32_32x32x16_bf16 v[48:63], v[208:211], v[88:91], v[48:63]
	ds_read_b128 v[208:211], v72 offset:9280
	v_exp_f32_e32 v40, v40
	v_exp_f32_e32 v41, v41
	s_waitcnt lgkmcnt(3)
	v_mfma_f32_32x32x16_bf16 v[48:63], v[212:215], v[92:95], v[48:63]
	ds_read_b128 v[212:215], v72 offset:9312
	v_exp_f32_e32 v42, v42
	v_exp_f32_e32 v43, v43
	v_add_f32_e32 v232, v232, v40
	v_add_f32_e32 v233, v233, v41
	v_cvt_pk_bf16_f32 v68, v40, v41
	v_mfma_f32_32x32x16_bf16 v[0:15], v[216:219], v[64:67], v[0:15]
	ds_read2_b64 v[216:219], v73 offset0:8 offset1:10
	v_exp_f32_e32 v44, v44
	v_exp_f32_e32 v45, v45
	v_add_f32_e32 v232, v232, v42
	v_add_f32_e32 v233, v233, v43
	v_cvt_pk_bf16_f32 v69, v42, v43
	v_mfma_f32_32x32x16_bf16 v[16:31], v[220:223], v[64:67], v[16:31]
	ds_read2_b64 v[220:223], v74 offset0:40 offset1:42
	v_exp_f32_e32 v46, v46
	v_exp_f32_e32 v47, v47
	v_add_f32_e32 v232, v232, v44
	v_add_f32_e32 v233, v233, v45
	v_cvt_pk_bf16_f32 v70, v44, v45
	v_add_f32_e32 v232, v232, v46
	v_add_f32_e32 v233, v233, v47
	v_cvt_pk_bf16_f32 v71, v46, v47
	s_waitcnt lgkmcnt(5)
	v_mfma_f32_32x32x16_bf16 v[32:47], v[200:203], v[80:83], 0
	v_exp_f32_e32 v48, v48
	v_exp_f32_e32 v49, v49
	s_waitcnt lgkmcnt(4)
	v_mfma_f32_32x32x16_bf16 v[32:47], v[204:207], v[84:87], v[32:47]
	v_exp_f32_e32 v50, v50
	v_exp_f32_e32 v51, v51
	v_add_f32_e32 v232, v232, v48
	v_add_f32_e32 v233, v233, v49
	v_cvt_pk_bf16_f32 v64, v48, v49
	v_mfma_f32_32x32x16_bf16 v[0:15], v[224:227], v[68:71], v[0:15]
	ds_read2_b64 v[224:227], v73 offset0:12 offset1:14
	v_exp_f32_e32 v52, v52
	v_exp_f32_e32 v53, v53
	v_add_f32_e32 v232, v232, v50
	v_add_f32_e32 v233, v233, v51
	v_cvt_pk_bf16_f32 v65, v50, v51
	v_mfma_f32_32x32x16_bf16 v[16:31], v[228:231], v[68:71], v[16:31]
	ds_read2_b64 v[228:231], v74 offset0:44 offset1:46
	v_exp_f32_e32 v54, v54
	v_exp_f32_e32 v55, v55
	v_add_f32_e32 v232, v232, v52
	v_add_f32_e32 v233, v233, v53
	v_cvt_pk_bf16_f32 v66, v52, v53
	s_cmp_eq_u32 s45, 0
	s_cbranch_scc1 .Lt1_d2_nostage
	s_waitcnt vmcnt(3)
	ds_write_b128 v251, v[96:99]
	s_waitcnt vmcnt(2)
	ds_write_b128 v251, v[100:103] offset:9216
	s_waitcnt vmcnt(1)
	ds_write2_b64 v252, v[104:105], v[106:107] offset1:1
	s_waitcnt vmcnt(0)
	ds_write2_b64 v252, v[108:109], v[110:111] offset0:16 offset1:17
	s_mov_b32 s47, 1
; #define LAS __attribute__((address_space(3)))
; #define MFMA32(a, b, c) __builtin_amdgcn_mfma_f32_32x32x16_bf16((a), (b), (c), 0, 0, 0)
; __device__ __forceinline__ float ex2(float x) { return __builtin_amdgcn_exp2f(x); }
; template <int MODE>
; __device__ __forceinline__ void attn_tile(const LAS unsigned char* Kb, const LAS unsigned char* Vb, const bf16x8_t (&qf)[4], f32x16 (&oacc)[2], float& l_run,
;                                           int r, int h, int dlt0, int dlt1, bool hiw) {
;     const unsigned ulim = (MODE == 0) ? 0x80000000u : 512u;
;     float ls = 0.f;
; #pragma unroll
;     for (int mt = 0; mt < 4; ++mt) {
;         if (mt == 0) { if (hiw) __builtin_amdgcn_s_setprio(1); else __builtin_amdgcn_s_setprio(0); }
;         if (mt == 2) { if (hiw) __builtin_amdgcn_s_setprio(0); else __builtin_amdgcn_s_setprio(1); }
;         const int dl = mt < 2 ? dlt0 : dlt1;
;         f32x16 sacc = zero16();
; #pragma unroll
;         for (int ks = 0; ks < 4; ++ks) { const bf16x8_t ka = *(const LAS bf16x8_t*)(Kb + (32 * mt + r) * A_KSTR + 32 * ks + 16 * h); sacc = MFMA32(ka, qf[ks], sacc); }
; #pragma unroll
;         for (int i = 0; i < 16; ++i) {
;             float p;
;             if (MODE == 2) p = ex2(sacc[i]);
;             else if (MODE == 3) p = ex2(sacc[i] + __int_as_float(dl));
;             else { const int ci = 32 * mt + (i & 3) + 8 * (i >> 2); p = ((unsigned)(dl - ci) < ulim) ? ex2(sacc[i]) : 0.f; }
;             sacc[i] = p; ls += p;
;         }
; #pragma unroll
;         for (int s = 0; s < 2; ++s) {
;             const bf16x8_t pf = pack8(sacc, 8 * s);
; #pragma unroll
;             for (int dt = 0; dt < 2; ++dt) {
;                 const LAS unsigned char* vp = Vb + (32 * dt + r) * A_CVSTR + (32 * mt + 16 * s + 4 * h) * 2;
;                 const s16x4_t lo = *(const LAS s16x4_t*)vp, hi = *(const LAS s16x4_t*)(vp + 16);
;                 oacc[dt] = MFMA32(__builtin_shufflevector(lo, hi, 0, 1, 2, 3, 4, 5, 6, 7), pf, oacc[dt]);
;             }
;         }
;     }
;     l_run += ls;
; }
.Lt1_d2_nostage:
	v_add_f32_e32 v232, v232, v54
	v_add_f32_e32 v233, v233, v55
	v_cvt_pk_bf16_f32 v67, v54, v55
	s_waitcnt lgkmcnt(5)
	v_mfma_f32_32x32x16_bf16 v[32:47], v[208:211], v[88:91], v[32:47]
	v_exp_f32_e32 v56, v56
	v_exp_f32_e32 v57, v57
	s_waitcnt lgkmcnt(4)
	v_mfma_f32_32x32x16_bf16 v[32:47], v[212:215], v[92:95], v[32:47]
	v_exp_f32_e32 v58, v58
	v_exp_f32_e32 v59, v59
	v_add_f32_e32 v232, v232, v56
	v_add_f32_e32 v233, v233, v57
	v_cvt_pk_bf16_f32 v68, v56, v57
	s_waitcnt lgkmcnt(3)
	v_mfma_f32_32x32x16_bf16 v[0:15], v[216:219], v[64:67], v[0:15]
	ds_read2_b64 v[216:219], v73 offset0:16 offset1:18
	v_exp_f32_e32 v60, v60
	v_exp_f32_e32 v61, v61
	v_add_f32_e32 v232, v232, v58
	v_add_f32_e32 v233, v233, v59
	v_cvt_pk_bf16_f32 v69, v58, v59
	s_waitcnt lgkmcnt(3)
	v_mfma_f32_32x32x16_bf16 v[16:31], v[220:223], v[64:67], v[16:31]
	ds_read2_b64 v[220:223], v74 offset0:48 offset1:50
	v_exp_f32_e32 v62, v62
	v_exp_f32_e32 v63, v63
	v_add_f32_e32 v232, v232, v60
	v_add_f32_e32 v233, v233, v61
	v_cvt_pk_bf16_f32 v70, v60, v61
	v_add_f32_e32 v232, v232, v62
	v_add_f32_e32 v233, v233, v63
	v_cvt_pk_bf16_f32 v71, v62, v63
	v_cmp_le_i32_e64 s[0:1], 0, v250
	v_cmp_le_i32_e64 s[4:5], 1, v250
	v_exp_f32_e32 v32, v32
	v_exp_f32_e32 v33, v33
	v_cmp_le_i32_e64 s[6:7], 2, v250
	v_cmp_le_i32_e64 s[48:49], 3, v250
	v_exp_f32_e32 v34, v34
	v_exp_f32_e32 v35, v35
	v_cndmask_b32_e64 v32, 0, v32, s[0:1]
	v_cndmask_b32_e64 v33, 0, v33, s[4:5]
	v_add_f32_e32 v232, v232, v32
	v_add_f32_e32 v233, v233, v33
	v_cvt_pk_bf16_f32 v64, v32, v33
	s_waitcnt lgkmcnt(3)
	v_mfma_f32_32x32x16_bf16 v[0:15], v[224:227], v[68:71], v[0:15]
	ds_read2_b64 v[224:227], v73 offset0:20 offset1:22
	v_cmp_le_i32_e64 s[0:1], 8, v250
	v_cmp_le_i32_e64 s[4:5], 9, v250
	v_exp_f32_e32 v36, v36
	v_exp_f32_e32 v37, v37
	v_cndmask_b32_e64 v34, 0, v34, s[6:7]
	v_cndmask_b32_e64 v35, 0, v35, s[48:49]
	v_add_f32_e32 v232, v232, v34
	v_add_f32_e32 v233, v233, v35
	v_cvt_pk_bf16_f32 v65, v34, v35
	s_waitcnt lgkmcnt(3)
	v_mfma_f32_32x32x16_bf16 v[16:31], v[228:231], v[68:71], v[16:31]
	ds_read2_b64 v[228:231], v74 offset0:52 offset1:54
	v_cmp_le_i32_e64 s[6:7], 10, v250
	v_cmp_le_i32_e64 s[48:49], 11, v250
	v_exp_f32_e32 v38, v38
	v_exp_f32_e32 v39, v39
	v_cndmask_b32_e64 v36, 0, v36, s[0:1]
	v_cndmask_b32_e64 v37, 0, v37, s[4:5]
	v_add_f32_e32 v232, v232, v36
	v_add_f32_e32 v233, v233, v37
	v_cvt_pk_bf16_f32 v66, v36, v37
	v_cndmask_b32_e64 v38, 0, v38, s[6:7]
	v_cndmask_b32_e64 v39, 0, v39, s[48:49]
	v_add_f32_e32 v232, v232, v38
	v_add_f32_e32 v233, v233, v39
	v_cvt_pk_bf16_f32 v67, v38, v39
	v_cmp_le_i32_e64 s[0:1], 16, v250
	v_cmp_le_i32_e64 s[4:5], 17, v250
	v_exp_f32_e32 v40, v40
	v_exp_f32_e32 v41, v41
	v_cmp_le_i32_e64 s[6:7], 18, v250
	v_cmp_le_i32_e64 s[48:49], 19, v250
	v_exp_f32_e32 v42, v42
	v_exp_f32_e32 v43, v43
	v_cndmask_b32_e64 v40, 0, v40, s[0:1]
	v_cndmask_b32_e64 v41, 0, v41, s[4:5]
	v_add_f32_e32 v232, v232, v40
	v_add_f32_e32 v233, v233, v41
	v_cvt_pk_bf16_f32 v68, v40, v41
	s_waitcnt lgkmcnt(3)
	v_mfma_f32_32x32x16_bf16 v[0:15], v[216:219], v[64:67], v[0:15]
	v_cmp_le_i32_e64 s[0:1], 24, v250
	v_cmp_le_i32_e64 s[4:5], 25, v250
	v_exp_f32_e32 v44, v44
	v_exp_f32_e32 v45, v45
	v_cndmask_b32_e64 v42, 0, v42, s[6:7]
	v_cndmask_b32_e64 v43, 0, v43, s[48:49]
	v_add_f32_e32 v232, v232, v42
	v_add_f32_e32 v233, v233, v43
	v_cvt_pk_bf16_f32 v69, v42, v43
	s_waitcnt lgkmcnt(2)
	v_mfma_f32_32x32x16_bf16 v[16:31], v[220:223], v[64:67], v[16:31]
	v_cmp_le_i32_e64 s[6:7], 26, v250
	v_cmp_le_i32_e64 s[48:49], 27, v250
	v_exp_f32_e32 v46, v46
	v_exp_f32_e32 v47, v47
	v_cndmask_b32_e64 v44, 0, v44, s[0:1]
	v_cndmask_b32_e64 v45, 0, v45, s[4:5]
	v_add_f32_e32 v232, v232, v44
	v_add_f32_e32 v233, v233, v45
	v_cvt_pk_bf16_f32 v70, v44, v45
	v_cndmask_b32_e64 v46, 0, v46, s[6:7]
	v_cndmask_b32_e64 v47, 0, v47, s[48:49]
	v_add_f32_e32 v232, v232, v46
	v_add_f32_e32 v233, v233, v47
	v_cvt_pk_bf16_f32 v71, v46, v47
	s_nop 1
	s_waitcnt lgkmcnt(1)
	v_mfma_f32_32x32x16_bf16 v[0:15], v[224:227], v[68:71], v[0:15]
	s_waitcnt lgkmcnt(0)
	v_mfma_f32_32x32x16_bf16 v[16:31], v[228:231], v[68:71], v[16:31]
	v_add_f32_e32 v232, v232, v233
	v_add_f32_e32 v112, v112, v232
	s_branch .Lt1_join

; #define LAS __attribute__((address_space(3)))
; #define MFMA32(a, b, c) __builtin_amdgcn_mfma_f32_32x32x16_bf16((a), (b), (c), 0, 0, 0)
; __device__ __forceinline__ float ex2(float x) { return __builtin_amdgcn_exp2f(x); }
; template <int MODE>
; __device__ __forceinline__ void attn_tile(const LAS unsigned char* Kb, const LAS unsigned char* Vb, const bf16x8_t (&qf)[4], f32x16 (&oacc)[2], float& l_run,
;                                           int r, int h, int dlt0, int dlt1, bool hiw) {
;     const unsigned ulim = (MODE == 0) ? 0x80000000u : 512u;
;     float ls = 0.f;
; #pragma unroll
;     for (int mt = 0; mt < 4; ++mt) {
;         if (mt == 0) { if (hiw) __builtin_amdgcn_s_setprio(1); else __builtin_amdgcn_s_setprio(0); }
;         if (mt == 2) { if (hiw) __builtin_amdgcn_s_setprio(0); else __builtin_amdgcn_s_setprio(1); }
;         const int dl = mt < 2 ? dlt0 : dlt1;
;         f32x16 sacc = zero16();
; #pragma unroll
;         for (int ks = 0; ks < 4; ++ks) { const bf16x8_t ka = *(const LAS bf16x8_t*)(Kb + (32 * mt + r) * A_KSTR + 32 * ks + 16 * h); sacc = MFMA32(ka, qf[ks], sacc); }
; #pragma unroll
;         for (int i = 0; i < 16; ++i) {
;             float p;
;             if (MODE == 2) p = ex2(sacc[i]);
;             else if (MODE == 3) p = ex2(sacc[i] + __int_as_float(dl));
;             else { const int ci = 32 * mt + (i & 3) + 8 * (i >> 2); p = ((unsigned)(dl - ci) < ulim) ? ex2(sacc[i]) : 0.f; }
;             sacc[i] = p; ls += p;
;         }
; #pragma unroll
;         for (int s = 0; s < 2; ++s) {
;             const bf16x8_t pf = pack8(sacc, 8 * s);
; #pragma unroll
;             for (int dt = 0; dt < 2; ++dt) {
;                 const LAS unsigned char* vp = Vb + (32 * dt + r) * A_CVSTR + (32 * mt + 16 * s + 4 * h) * 2;
;                 const s16x4_t lo = *(const LAS s16x4_t*)vp, hi = *(const LAS s16x4_t*)(vp + 16);
;                 oacc[dt] = MFMA32(__builtin_shufflevector(lo, hi, 0, 1, 2, 3, 4, 5, 6, 7), pf, oacc[dt]);
;             }
;         }
;     }
;     l_run += ls;
; }
.Lt1_d3_nostage:
	v_add_f32_e32 v232, v232, v38
	v_add_f32_e32 v233, v233, v39
	v_cvt_pk_bf16_f32 v67, v38, v39
	s_waitcnt lgkmcnt(5)
	v_mfma_f32_32x32x16_bf16 v[48:63], v[208:211], v[88:91], v[48:63]
	v_exp_f32_e32 v40, v40
	v_exp_f32_e32 v41, v41
	s_waitcnt lgkmcnt(4)
	v_mfma_f32_32x32x16_bf16 v[48:63], v[212:215], v[92:95], v[48:63]
	v_exp_f32_e32 v42, v42
	v_exp_f32_e32 v43, v43
	v_add_f32_e32 v232, v232, v40
	v_add_f32_e32 v233, v233, v41
	v_cvt_pk_bf16_f32 v68, v40, v41
	s_waitcnt lgkmcnt(3)
	v_mfma_f32_32x32x16_bf16 v[0:15], v[216:219], v[64:67], v[0:15]
	ds_read2_b64 v[216:219], v73 offset0:24 offset1:26
	v_exp_f32_e32 v44, v44
	v_exp_f32_e32 v45, v45
	v_add_f32_e32 v232, v232, v42
	v_add_f32_e32 v233, v233, v43
	v_cvt_pk_bf16_f32 v69, v42, v43
	s_waitcnt lgkmcnt(3)
	v_mfma_f32_32x32x16_bf16 v[16:31], v[220:223], v[64:67], v[16:31]
	ds_read2_b64 v[220:223], v74 offset0:56 offset1:58
	v_exp_f32_e32 v46, v46
	v_exp_f32_e32 v47, v47
	v_add_f32_e32 v232, v232, v44
	v_add_f32_e32 v233, v233, v45
	v_cvt_pk_bf16_f32 v70, v44, v45
	v_add_f32_e32 v232, v232, v46
	v_add_f32_e32 v233, v233, v47
	v_cvt_pk_bf16_f32 v71, v46, v47
	v_cmp_le_i32_e64 s[0:1], 0, v250
	v_cmp_le_i32_e64 s[4:5], 1, v250
	v_exp_f32_e32 v48, v48
	v_exp_f32_e32 v49, v49
	v_cmp_le_i32_e64 s[6:7], 2, v250
	v_cmp_le_i32_e64 s[48:49], 3, v250
	v_exp_f32_e32 v50, v50
	v_exp_f32_e32 v51, v51
	v_cndmask_b32_e64 v48, 0, v48, s[0:1]
	v_cndmask_b32_e64 v49, 0, v49, s[4:5]
	v_add_f32_e32 v232, v232, v48
	v_add_f32_e32 v233, v233, v49
	v_cvt_pk_bf16_f32 v64, v48, v49
	s_waitcnt lgkmcnt(3)
	v_mfma_f32_32x32x16_bf16 v[0:15], v[224:227], v[68:71], v[0:15]
	ds_read2_b64 v[224:227], v73 offset0:28 offset1:30
	v_cmp_le_i32_e64 s[0:1], 8, v250
	v_cmp_le_i32_e64 s[4:5], 9, v250
	v_exp_f32_e32 v52, v52
	v_exp_f32_e32 v53, v53
	v_cndmask_b32_e64 v50, 0, v50, s[6:7]
	v_cndmask_b32_e64 v51, 0, v51, s[48:49]
	v_add_f32_e32 v232, v232, v50
	v_add_f32_e32 v233, v233, v51
	v_cvt_pk_bf16_f32 v65, v50, v51
	s_waitcnt lgkmcnt(3)
	v_mfma_f32_32x32x16_bf16 v[16:31], v[228:231], v[68:71], v[16:31]
	ds_read2_b64 v[228:231], v74 offset0:60 offset1:62
	v_cmp_le_i32_e64 s[6:7], 10, v250
	v_cmp_le_i32_e64 s[48:49], 11, v250
	v_exp_f32_e32 v54, v54
	v_exp_f32_e32 v55, v55
	v_cndmask_b32_e64 v52, 0, v52, s[0:1]
	v_cndmask_b32_e64 v53, 0, v53, s[4:5]
	v_add_f32_e32 v232, v232, v52
	v_add_f32_e32 v233, v233, v53
	v_cvt_pk_bf16_f32 v66, v52, v53
	v_cndmask_b32_e64 v54, 0, v54, s[6:7]
	v_cndmask_b32_e64 v55, 0, v55, s[48:49]
	v_add_f32_e32 v232, v232, v54
	v_add_f32_e32 v233, v233, v55
	v_cvt_pk_bf16_f32 v67, v54, v55
	v_cmp_le_i32_e64 s[0:1], 16, v250
	v_cmp_le_i32_e64 s[4:5], 17, v250
	v_exp_f32_e32 v56, v56
	v_exp_f32_e32 v57, v57
	v_cmp_le_i32_e64 s[6:7], 18, v250
	v_cmp_le_i32_e64 s[48:49], 19, v250
	v_exp_f32_e32 v58, v58
	v_exp_f32_e32 v59, v59
	v_cndmask_b32_e64 v56, 0, v56, s[0:1]
	v_cndmask_b32_e64 v57, 0, v57, s[4:5]
	v_add_f32_e32 v232, v232, v56
	v_add_f32_e32 v233, v233, v57
	v_cvt_pk_bf16_f32 v68, v56, v57
	s_waitcnt lgkmcnt(3)
	v_mfma_f32_32x32x16_bf16 v[0:15], v[216:219], v[64:67], v[0:15]
	v_cmp_le_i32_e64 s[0:1], 24, v250
	v_cmp_le_i32_e64 s[4:5], 25, v250
	v_exp_f32_e32 v60, v60
	v_exp_f32_e32 v61, v61
	v_cndmask_b32_e64 v58, 0, v58, s[6:7]
	v_cndmask_b32_e64 v59, 0, v59, s[48:49]
	v_add_f32_e32 v232, v232, v58
	v_add_f32_e32 v233, v233, v59
	v_cvt_pk_bf16_f32 v69, v58, v59
	s_waitcnt lgkmcnt(2)
	v_mfma_f32_32x32x16_bf16 v[16:31], v[220:223], v[64:67], v[16:31]
	v_cmp_le_i32_e64 s[6:7], 26, v250
	v_cmp_le_i32_e64 s[48:49], 27, v250
	v_exp_f32_e32 v62, v62
	v_exp_f32_e32 v63, v63
	v_cndmask_b32_e64 v60, 0, v60, s[0:1]
	v_cndmask_b32_e64 v61, 0, v61, s[4:5]
	v_add_f32_e32 v232, v232, v60
	v_add_f32_e32 v233, v233, v61
	v_cvt_pk_bf16_f32 v70, v60, v61
	v_cndmask_b32_e64 v62, 0, v62, s[6:7]
	v_cndmask_b32_e64 v63, 0, v63, s[48:49]
	v_add_f32_e32 v232, v232, v62
	v_add_f32_e32 v233, v233, v63
	v_cvt_pk_bf16_f32 v71, v62, v63
	s_nop 1
	s_waitcnt lgkmcnt(1)
	v_mfma_f32_32x32x16_bf16 v[0:15], v[224:227], v[68:71], v[0:15]
	s_waitcnt lgkmcnt(0)
	v_mfma_f32_32x32x16_bf16 v[16:31], v[228:231], v[68:71], v[16:31]
	v_add_f32_e32 v232, v232, v233
	v_add_f32_e32 v112, v112, v232
	s_branch .Lt1_join
.Lt1_e0:
	ds_read_b128 v[200:203], v72 offset:0
	ds_read_b128 v[204:207], v72 offset:32
	ds_read_b128 v[208:211], v72 offset:64
	ds_read_b128 v[212:215], v72 offset:96
	ds_read2_b64 v[216:219], v73 offset0:0 offset1:2
	ds_read2_b64 v[220:223], v74 offset0:32 offset1:34
	ds_read2_b64 v[224:227], v73 offset0:4 offset1:6
	ds_read2_b64 v[228:231], v74 offset0:36 offset1:38
	s_waitcnt lgkmcnt(7)
	v_mfma_f32_32x32x16_bf16 v[32:47], v[200:203], v[80:83], 0
	ds_read_b128 v[200:203], v72 offset:4608
	s_waitcnt lgkmcnt(7)
	v_mfma_f32_32x32x16_bf16 v[32:47], v[204:207], v[84:87], v[32:47]
	ds_read_b128 v[204:207], v72 offset:4640
	s_waitcnt lgkmcnt(7)
	v_mfma_f32_32x32x16_bf16 v[32:47], v[208:211], v[88:91], v[32:47]
	ds_read_b128 v[208:211], v72 offset:4672
	s_waitcnt lgkmcnt(7)
	v_mfma_f32_32x32x16_bf16 v[32:47], v[212:215], v[92:95], v[32:47]
	ds_read_b128 v[212:215], v72 offset:4704
	s_nop 7
	s_nop 3
	s_waitcnt lgkmcnt(3)
	v_mfma_f32_32x32x16_bf16 v[48:63], v[200:203], v[80:83], 0
	ds_read_b128 v[200:203], v72 offset:9216
	v_cmp_le_i32_e64 s[0:1], 0, v250
	v_cmp_le_i32_e64 s[4:5], 1, v250
	v_exp_f32_e32 v32, v32
	v_exp_f32_e32 v33, v33
	s_waitcnt lgkmcnt(3)
; #define LAS __attribute__((address_space(3)))
; #define MFMA32(a, b, c) __builtin_amdgcn_mfma_f32_32x32x16_bf16((a), (b), (c), 0, 0, 0)
; __device__ __forceinline__ float ex2(float x) { return __builtin_amdgcn_exp2f(x); }
; template <int MODE>
; __device__ __forceinline__ void attn_tile(const LAS unsigned char* Kb, const LAS unsigned char* Vb, const bf16x8_t (&qf)[4], f32x16 (&oacc)[2], float& l_run,
;                                           int r, int h, int dlt0, int dlt1, bool hiw) {
;     ...
; #pragma unroll
;     for (int mt = 0; mt < 4; ++mt) {
;         if (mt == 0) { if (hiw) __builtin_amdgcn_s_setprio(1); else __builtin_amdgcn_s_setprio(0); }
;         if (mt == 2) { if (hiw) __builtin_amdgcn_s_setprio(0); else __builtin_amdgcn_s_setprio(1); }
;         const int dl = mt < 2 ? dlt0 : dlt1;
;         f32x16 sacc = zero16();
; #pragma unroll
;         for (int ks = 0; ks < 4; ++ks) { const bf16x8_t ka = *(const LAS bf16x8_t*)(Kb + (32 * mt + r) * A_KSTR + 32 * ks + 16 * h); sacc = MFMA32(ka, qf[ks], sacc); }
; #pragma unroll
;         for (int i = 0; i < 16; ++i) {
;             float p;
;             if (MODE == 2) p = ex2(sacc[i]);
;             else if (MODE == 3) p = ex2(sacc[i] + __int_as_float(dl));
;             else { const int ci = 32 * mt + (i & 3) + 8 * (i >> 2); p = ((unsigned)(dl - ci) < ulim) ? ex2(sacc[i]) : 0.f; }
;             sacc[i] = p; ls += p;
;         }
; #pragma unroll
;         for (int s = 0; s < 2; ++s) {
;             const bf16x8_t pf = pack8(sacc, 8 * s);
; #pragma unroll
;             for (int dt = 0; dt < 2; ++dt) {
;                 const LAS unsigned char* vp = Vb + (32 * dt + r) * A_CVSTR + (32 * mt + 16 * s + 4 * h) * 2;
;                 const s16x4_t lo = *(const LAS s16x4_t*)vp, hi = *(const LAS s16x4_t*)(vp + 16);
;                 oacc[dt] = MFMA32(__builtin_shufflevector(lo, hi, 0, 1, 2, 3, 4, 5, 6, 7), pf, oacc[dt]);
;             }
;         }
;     }
;     l_run += ls;
	v_mfma_f32_32x32x16_bf16 v[48:63], v[204:207], v[84:87], v[48:63]
	ds_read_b128 v[204:207], v72 offset:9248
	v_cmp_le_i32_e64 s[6:7], 2, v250
	v_cmp_le_i32_e64 s[48:49], 3, v250
	v_exp_f32_e32 v34, v34
	v_exp_f32_e32 v35, v35
	v_cndmask_b32_e64 v32, v32, 0, s[0:1]
	v_cndmask_b32_e64 v33, v33, 0, s[4:5]
	v_mov_b32_e32 v232, v32
	v_mov_b32_e32 v233, v33
	v_cvt_pk_bf16_f32 v64, v32, v33
	v_cmp_le_i32_e64 s[0:1], 8, v250
	v_cmp_le_i32_e64 s[4:5], 9, v250
	v_exp_f32_e32 v36, v36
	v_exp_f32_e32 v37, v37
	v_cndmask_b32_e64 v34, v34, 0, s[6:7]
	v_cndmask_b32_e64 v35, v35, 0, s[48:49]
	v_add_f32_e32 v232, v232, v34
	v_add_f32_e32 v233, v233, v35
	v_cvt_pk_bf16_f32 v65, v34, v35
	v_cmp_le_i32_e64 s[6:7], 10, v250
	v_cmp_le_i32_e64 s[48:49], 11, v250
	v_exp_f32_e32 v38, v38
	v_exp_f32_e32 v39, v39
	v_cndmask_b32_e64 v36, v36, 0, s[0:1]
	v_cndmask_b32_e64 v37, v37, 0, s[4:5]
	v_add_f32_e32 v232, v232, v36
	v_add_f32_e32 v233, v233, v37
	v_cvt_pk_bf16_f32 v66, v36, v37
	v_cndmask_b32_e64 v38, v38, 0, s[6:7]
	v_cndmask_b32_e64 v39, v39, 0, s[48:49]
	v_add_f32_e32 v232, v232, v38
	v_add_f32_e32 v233, v233, v39
	v_cvt_pk_bf16_f32 v67, v38, v39
	s_waitcnt lgkmcnt(3)
	v_mfma_f32_32x32x16_bf16 v[48:63], v[208:211], v[88:91], v[48:63]
	ds_read_b128 v[208:211], v72 offset:9280
	v_cmp_le_i32_e64 s[0:1], 16, v250
	v_cmp_le_i32_e64 s[4:5], 17, v250
	v_exp_f32_e32 v40, v40
	v_exp_f32_e32 v41, v41
	s_waitcnt lgkmcnt(3)
	v_mfma_f32_32x32x16_bf16 v[48:63], v[212:215], v[92:95], v[48:63]
	ds_read_b128 v[212:215], v72 offset:9312
	v_cmp_le_i32_e64 s[6:7], 18, v250
	v_cmp_le_i32_e64 s[48:49], 19, v250
	v_exp_f32_e32 v42, v42
	v_exp_f32_e32 v43, v43
	v_cndmask_b32_e64 v40, v40, 0, s[0:1]
	v_cndmask_b32_e64 v41, v41, 0, s[4:5]
	v_add_f32_e32 v232, v232, v40
	v_add_f32_e32 v233, v233, v41
	v_cvt_pk_bf16_f32 v68, v40, v41
	v_mfma_f32_32x32x16_bf16 v[0:15], v[216:219], v[64:67], v[0:15]
	ds_read2_b64 v[216:219], v73 offset0:8 offset1:10
	v_cmp_le_i32_e64 s[0:1], 24, v250
	v_cmp_le_i32_e64 s[4:5], 25, v250
	v_exp_f32_e32 v44, v44
	v_exp_f32_e32 v45, v45
	v_cndmask_b32_e64 v42, v42, 0, s[6:7]
	v_cndmask_b32_e64 v43, v43, 0, s[48:49]
	v_add_f32_e32 v232, v232, v42
	v_add_f32_e32 v233, v233, v43
	v_cvt_pk_bf16_f32 v69, v42, v43
	v_mfma_f32_32x32x16_bf16 v[16:31], v[220:223], v[64:67], v[16:31]
	ds_read2_b64 v[220:223], v74 offset0:40 offset1:42
	v_cmp_le_i32_e64 s[6:7], 26, v250
	v_cmp_le_i32_e64 s[48:49], 27, v250
	v_exp_f32_e32 v46, v46
	v_exp_f32_e32 v47, v47
	v_cndmask_b32_e64 v44, v44, 0, s[0:1]
	v_cndmask_b32_e64 v45, v45, 0, s[4:5]
	v_add_f32_e32 v232, v232, v44
	v_add_f32_e32 v233, v233, v45
	v_cvt_pk_bf16_f32 v70, v44, v45
	v_cndmask_b32_e64 v46, v46, 0, s[6:7]
	v_cndmask_b32_e64 v47, v47, 0, s[48:49]
	v_add_f32_e32 v232, v232, v46
	v_add_f32_e32 v233, v233, v47
	v_cvt_pk_bf16_f32 v71, v46, v47
	s_waitcnt lgkmcnt(5)
	v_mfma_f32_32x32x16_bf16 v[32:47], v[200:203], v[80:83], 0
	ds_read_b128 v[200:203], v72 offset:13824
	v_exp_f32_e32 v48, v48
	v_exp_f32_e32 v49, v49
	s_waitcnt lgkmcnt(5)
	v_mfma_f32_32x32x16_bf16 v[32:47], v[204:207], v[84:87], v[32:47]
	ds_read_b128 v[204:207], v72 offset:13856
	v_exp_f32_e32 v50, v50
	v_exp_f32_e32 v51, v51
	v_add_f32_e32 v232, v232, v48
	v_add_f32_e32 v233, v233, v49
	v_cvt_pk_bf16_f32 v64, v48, v49
	v_mfma_f32_32x32x16_bf16 v[0:15], v[224:227], v[68:71], v[0:15]
	ds_read2_b64 v[224:227], v73 offset0:12 offset1:14
	v_exp_f32_e32 v52, v52
	v_exp_f32_e32 v53, v53
	v_add_f32_e32 v232, v232, v50
	v_add_f32_e32 v233, v233, v51
	v_cvt_pk_bf16_f32 v65, v50, v51
	v_mfma_f32_32x32x16_bf16 v[16:31], v[228:231], v[68:71], v[16:31]
	ds_read2_b64 v[228:231], v74 offset0:44 offset1:46
	v_exp_f32_e32 v54, v54
	v_exp_f32_e32 v55, v55
	v_add_f32_e32 v232, v232, v52
	v_add_f32_e32 v233, v233, v53
	v_cvt_pk_bf16_f32 v66, v52, v53
	v_add_f32_e32 v232, v232, v54
	v_add_f32_e32 v233, v233, v55
	v_cvt_pk_bf16_f32 v67, v54, v55
	s_waitcnt lgkmcnt(7)
	v_mfma_f32_32x32x16_bf16 v[32:47], v[208:211], v[88:91], v[32:47]
	ds_read_b128 v[208:211], v72 offset:13888
	v_exp_f32_e32 v56, v56
	v_exp_f32_e32 v57, v57
	s_waitcnt lgkmcnt(7)
	v_mfma_f32_32x32x16_bf16 v[32:47], v[212:215], v[92:95], v[32:47]
	ds_read_b128 v[212:215], v72 offset:13920
	v_exp_f32_e32 v58, v58
	v_exp_f32_e32 v59, v59
	v_add_f32_e32 v232, v232, v56
	v_add_f32_e32 v233, v233, v57
	v_cvt_pk_bf16_f32 v68, v56, v57
	s_waitcnt lgkmcnt(7)
	v_mfma_f32_32x32x16_bf16 v[0:15], v[216:219], v[64:67], v[0:15]
	ds_read2_b64 v[216:219], v73 offset0:16 offset1:18
	v_exp_f32_e32 v60, v60
	v_exp_f32_e32 v61, v61
	v_add_f32_e32 v232, v232, v58
	v_add_f32_e32 v233, v233, v59
	v_cvt_pk_bf16_f32 v69, v58, v59
	s_waitcnt lgkmcnt(7)
	v_mfma_f32_32x32x16_bf16 v[16:31], v[220:223], v[64:67], v[16:31]
	ds_read2_b64 v[220:223], v74 offset0:48 offset1:50
	v_exp_f32_e32 v62, v62
	v_exp_f32_e32 v63, v63
	v_add_f32_e32 v232, v232, v60
	v_add_f32_e32 v233, v233, v61
	v_cvt_pk_bf16_f32 v70, v60, v61
	v_add_f32_e32 v232, v232, v62
	v_add_f32_e32 v233, v233, v63
	v_cvt_pk_bf16_f32 v71, v62, v63
	s_waitcnt lgkmcnt(7)
	v_mfma_f32_32x32x16_bf16 v[48:63], v[200:203], v[80:83], 0
	v_exp_f32_e32 v32, v32
	v_exp_f32_e32 v33, v33
	s_waitcnt lgkmcnt(6)
	v_mfma_f32_32x32x16_bf16 v[48:63], v[204:207], v[84:87], v[48:63]
	v_exp_f32_e32 v34, v34
	v_exp_f32_e32 v35, v35
	v_add_f32_e32 v232, v232, v32
	v_add_f32_e32 v233, v233, v33
	v_cvt_pk_bf16_f32 v64, v32, v33
	s_waitcnt lgkmcnt(5)
	v_mfma_f32_32x32x16_bf16 v[0:15], v[224:227], v[68:71], v[0:15]
	ds_read2_b64 v[224:227], v73 offset0:20 offset1:22
	v_exp_f32_e32 v36, v36
	v_exp_f32_e32 v37, v37
	v_add_f32_e32 v232, v232, v34
	v_add_f32_e32 v233, v233, v35
	v_cvt_pk_bf16_f32 v65, v34, v35
	s_waitcnt lgkmcnt(5)
	v_mfma_f32_32x32x16_bf16 v[16:31], v[228:231], v[68:71], v[16:31]
	ds_read2_b64 v[228:231], v74 offset0:52 offset1:54
	v_exp_f32_e32 v38, v38
	v_exp_f32_e32 v39, v39
	v_add_f32_e32 v232, v232, v36
	v_add_f32_e32 v233, v233, v37
	v_cvt_pk_bf16_f32 v66, v36, v37
	s_cmp_eq_u32 s45, 0
	s_cbranch_scc1 .Lt1_e0_nostage
	s_waitcnt vmcnt(3)
	ds_write_b128 v251, v[96:99]
	s_waitcnt vmcnt(2)
	ds_write_b128 v251, v[100:103] offset:9216
	s_waitcnt vmcnt(1)
	ds_write2_b64 v252, v[104:105], v[106:107] offset1:1
	s_waitcnt vmcnt(0)
	ds_write2_b64 v252, v[108:109], v[110:111] offset0:16 offset1:17
	s_mov_b32 s47, 1

; #define LAS __attribute__((address_space(3)))
; #define MFMA32(a, b, c) __builtin_amdgcn_mfma_f32_32x32x16_bf16((a), (b), (c), 0, 0, 0)
; __device__ __forceinline__ float ex2(float x) { return __builtin_amdgcn_exp2f(x); }
; template <int MODE>
; __device__ __forceinline__ void attn_tile(const LAS unsigned char* Kb, const LAS unsigned char* Vb, const bf16x8_t (&qf)[4], f32x16 (&oacc)[2], float& l_run,
;                                           int r, int h, int dlt0, int dlt1, bool hiw) {
;     ...
; #pragma unroll
;     for (int mt = 0; mt < 4; ++mt) {
;         if (mt == 0) { if (hiw) __builtin_amdgcn_s_setprio(1); else __builtin_amdgcn_s_setprio(0); }
;         if (mt == 2) { if (hiw) __builtin_amdgcn_s_setprio(0); else __builtin_amdgcn_s_setprio(1); }
;         const int dl = mt < 2 ? dlt0 : dlt1;
;         f32x16 sacc = zero16();
; #pragma unroll
;         for (int ks = 0; ks < 4; ++ks) { const bf16x8_t ka = *(const LAS bf16x8_t*)(Kb + (32 * mt + r) * A_KSTR + 32 * ks + 16 * h); sacc = MFMA32(ka, qf[ks], sacc); }
; #pragma unroll
;         for (int i = 0; i < 16; ++i) {
;             float p;
;             if (MODE == 2) p = ex2(sacc[i]);
;             else if (MODE == 3) p = ex2(sacc[i] + __int_as_float(dl));
;             else { const int ci = 32 * mt + (i & 3) + 8 * (i >> 2); p = ((unsigned)(dl - ci) < ulim) ? ex2(sacc[i]) : 0.f; }
;             sacc[i] = p; ls += p;
;         }
; #pragma unroll
;         for (int s = 0; s < 2; ++s) {
;             const bf16x8_t pf = pack8(sacc, 8 * s);
; #pragma unroll
;             for (int dt = 0; dt < 2; ++dt) {
;                 const LAS unsigned char* vp = Vb + (32 * dt + r) * A_CVSTR + (32 * mt + 16 * s + 4 * h) * 2;
;                 const s16x4_t lo = *(const LAS s16x4_t*)vp, hi = *(const LAS s16x4_t*)(vp + 16);
;                 oacc[dt] = MFMA32(__builtin_shufflevector(lo, hi, 0, 1, 2, 3, 4, 5, 6, 7), pf, oacc[dt]);
;             }
;         }
;     }
;     l_run += ls;
.Lt1_e1:
	ds_read_b128 v[200:203], v72 offset:4608
	ds_read_b128 v[204:207], v72 offset:4640
	ds_read_b128 v[208:211], v72 offset:4672
	ds_read_b128 v[212:215], v72 offset:4704
	ds_read2_b64 v[216:219], v73 offset0:8 offset1:10
	ds_read2_b64 v[220:223], v74 offset0:40 offset1:42
	ds_read2_b64 v[224:227], v73 offset0:12 offset1:14
	ds_read2_b64 v[228:231], v74 offset0:44 offset1:46
	s_waitcnt lgkmcnt(7)
	v_mfma_f32_32x32x16_bf16 v[32:47], v[200:203], v[80:83], 0
	ds_read_b128 v[200:203], v72 offset:9216
	s_waitcnt lgkmcnt(7)
	v_mfma_f32_32x32x16_bf16 v[32:47], v[204:207], v[84:87], v[32:47]
	ds_read_b128 v[204:207], v72 offset:9248
	s_waitcnt lgkmcnt(7)
	v_mfma_f32_32x32x16_bf16 v[32:47], v[208:211], v[88:91], v[32:47]
	ds_read_b128 v[208:211], v72 offset:9280
	s_waitcnt lgkmcnt(7)
	v_mfma_f32_32x32x16_bf16 v[32:47], v[212:215], v[92:95], v[32:47]
	ds_read_b128 v[212:215], v72 offset:9312
	s_nop 7
	s_nop 3
	s_waitcnt lgkmcnt(3)
	v_mfma_f32_32x32x16_bf16 v[48:63], v[200:203], v[80:83], 0
	ds_read_b128 v[200:203], v72 offset:13824
	v_cmp_le_i32_e64 s[0:1], 0, v250
	v_cmp_le_i32_e64 s[4:5], 1, v250
	v_exp_f32_e32 v32, v32
	v_exp_f32_e32 v33, v33
	s_waitcnt lgkmcnt(3)
	v_mfma_f32_32x32x16_bf16 v[48:63], v[204:207], v[84:87], v[48:63]
	ds_read_b128 v[204:207], v72 offset:13856
	v_cmp_le_i32_e64 s[6:7], 2, v250
	v_cmp_le_i32_e64 s[48:49], 3, v250
	v_exp_f32_e32 v34, v34
	v_exp_f32_e32 v35, v35
	v_cndmask_b32_e64 v32, v32, 0, s[0:1]
	v_cndmask_b32_e64 v33, v33, 0, s[4:5]
	v_mov_b32_e32 v232, v32
	v_mov_b32_e32 v233, v33
	v_cvt_pk_bf16_f32 v64, v32, v33
	v_cmp_le_i32_e64 s[0:1], 8, v250
	v_cmp_le_i32_e64 s[4:5], 9, v250
	v_exp_f32_e32 v36, v36
	v_exp_f32_e32 v37, v37
	v_cndmask_b32_e64 v34, v34, 0, s[6:7]
	v_cndmask_b32_e64 v35, v35, 0, s[48:49]
	v_add_f32_e32 v232, v232, v34
	v_add_f32_e32 v233, v233, v35
	v_cvt_pk_bf16_f32 v65, v34, v35
	v_cmp_le_i32_e64 s[6:7], 10, v250
	v_cmp_le_i32_e64 s[48:49], 11, v250
	v_exp_f32_e32 v38, v38
	v_exp_f32_e32 v39, v39
	v_cndmask_b32_e64 v36, v36, 0, s[0:1]
	v_cndmask_b32_e64 v37, v37, 0, s[4:5]
	v_add_f32_e32 v232, v232, v36
	v_add_f32_e32 v233, v233, v37
	v_cvt_pk_bf16_f32 v66, v36, v37
	v_cndmask_b32_e64 v38, v38, 0, s[6:7]
	v_cndmask_b32_e64 v39, v39, 0, s[48:49]
	v_add_f32_e32 v232, v232, v38
	v_add_f32_e32 v233, v233, v39
	v_cvt_pk_bf16_f32 v67, v38, v39
	s_waitcnt lgkmcnt(3)
	v_mfma_f32_32x32x16_bf16 v[48:63], v[208:211], v[88:91], v[48:63]
	ds_read_b128 v[208:211], v72 offset:13888
	v_cmp_le_i32_e64 s[0:1], 16, v250
	v_cmp_le_i32_e64 s[4:5], 17, v250
	v_exp_f32_e32 v40, v40
	v_exp_f32_e32 v41, v41
	s_waitcnt lgkmcnt(3)
	v_mfma_f32_32x32x16_bf16 v[48:63], v[212:215], v[92:95], v[48:63]
	ds_read_b128 v[212:215], v72 offset:13920
	v_cmp_le_i32_e64 s[6:7], 18, v250
	v_cmp_le_i32_e64 s[48:49], 19, v250
	v_exp_f32_e32 v42, v42
	v_exp_f32_e32 v43, v43
	v_cndmask_b32_e64 v40, v40, 0, s[0:1]
	v_cndmask_b32_e64 v41, v41, 0, s[4:5]
	v_add_f32_e32 v232, v232, v40
	v_add_f32_e32 v233, v233, v41
	v_cvt_pk_bf16_f32 v68, v40, v41
	v_mfma_f32_32x32x16_bf16 v[0:15], v[216:219], v[64:67], v[0:15]
	ds_read2_b64 v[216:219], v73 offset0:16 offset1:18
	v_cmp_le_i32_e64 s[0:1], 24, v250
	v_cmp_le_i32_e64 s[4:5], 25, v250
	v_exp_f32_e32 v44, v44
	v_exp_f32_e32 v45, v45
	v_cndmask_b32_e64 v42, v42, 0, s[6:7]
	v_cndmask_b32_e64 v43, v43, 0, s[48:49]
	v_add_f32_e32 v232, v232, v42
	v_add_f32_e32 v233, v233, v43
	v_cvt_pk_bf16_f32 v69, v42, v43
	v_mfma_f32_32x32x16_bf16 v[16:31], v[220:223], v[64:67], v[16:31]
	ds_read2_b64 v[220:223], v74 offset0:48 offset1:50
	v_cmp_le_i32_e64 s[6:7], 26, v250
	v_cmp_le_i32_e64 s[48:49], 27, v250
	v_exp_f32_e32 v46, v46
	v_exp_f32_e32 v47, v47
	v_cndmask_b32_e64 v44, v44, 0, s[0:1]
	v_cndmask_b32_e64 v45, v45, 0, s[4:5]
	v_add_f32_e32 v232, v232, v44
	v_add_f32_e32 v233, v233, v45
	v_cvt_pk_bf16_f32 v70, v44, v45
	v_cndmask_b32_e64 v46, v46, 0, s[6:7]
	v_cndmask_b32_e64 v47, v47, 0, s[48:49]
	v_add_f32_e32 v232, v232, v46
	v_add_f32_e32 v233, v233, v47
	v_cvt_pk_bf16_f32 v71, v46, v47
	s_waitcnt lgkmcnt(5)
	v_mfma_f32_32x32x16_bf16 v[32:47], v[200:203], v[80:83], 0
	v_exp_f32_e32 v48, v48
	v_exp_f32_e32 v49, v49
	s_waitcnt lgkmcnt(4)
	v_mfma_f32_32x32x16_bf16 v[32:47], v[204:207], v[84:87], v[32:47]
	v_exp_f32_e32 v50, v50
	v_exp_f32_e32 v51, v51
	v_add_f32_e32 v232, v232, v48
	v_add_f32_e32 v233, v233, v49
	v_cvt_pk_bf16_f32 v64, v48, v49
	v_mfma_f32_32x32x16_bf16 v[0:15], v[224:227], v[68:71], v[0:15]
	ds_read2_b64 v[224:227], v73 offset0:20 offset1:22
	v_exp_f32_e32 v52, v52
	v_exp_f32_e32 v53, v53
	v_add_f32_e32 v232, v232, v50
	v_add_f32_e32 v233, v233, v51
	v_cvt_pk_bf16_f32 v65, v50, v51
	v_mfma_f32_32x32x16_bf16 v[16:31], v[228:231], v[68:71], v[16:31]
	ds_read2_b64 v[228:231], v74 offset0:52 offset1:54
	v_exp_f32_e32 v54, v54
	v_exp_f32_e32 v55, v55
	v_add_f32_e32 v232, v232, v52
	v_add_f32_e32 v233, v233, v53
	v_cvt_pk_bf16_f32 v66, v52, v53
	s_cmp_eq_u32 s45, 0
	s_cbranch_scc1 .Lt1_e1_nostage
	s_waitcnt vmcnt(3)
	ds_write_b128 v251, v[96:99]
	s_waitcnt vmcnt(2)
	ds_write_b128 v251, v[100:103] offset:9216
	s_waitcnt vmcnt(1)
	ds_write2_b64 v252, v[104:105], v[106:107] offset1:1
	s_waitcnt vmcnt(0)
	ds_write2_b64 v252, v[108:109], v[110:111] offset0:16 offset1:17
	s_mov_b32 s47, 1
; #define LAS __attribute__((address_space(3)))
; #define MFMA32(a, b, c) __builtin_amdgcn_mfma_f32_32x32x16_bf16((a), (b), (c), 0, 0, 0)
; __device__ __forceinline__ float ex2(float x) { return __builtin_amdgcn_exp2f(x); }
; template <int MODE>
; __device__ __forceinline__ void attn_tile(const LAS unsigned char* Kb, const LAS unsigned char* Vb, const bf16x8_t (&qf)[4], f32x16 (&oacc)[2], float& l_run,
;                                           int r, int h, int dlt0, int dlt1, bool hiw) {
;     ...
; #pragma unroll
;     for (int mt = 0; mt < 4; ++mt) {
;         if (mt == 0) { if (hiw) __builtin_amdgcn_s_setprio(1); else __builtin_amdgcn_s_setprio(0); }
;         if (mt == 2) { if (hiw) __builtin_amdgcn_s_setprio(0); else __builtin_amdgcn_s_setprio(1); }
;         const int dl = mt < 2 ? dlt0 : dlt1;
;         f32x16 sacc = zero16();
; #pragma unroll
;         for (int ks = 0; ks < 4; ++ks) { const bf16x8_t ka = *(const LAS bf16x8_t*)(Kb + (32 * mt + r) * A_KSTR + 32 * ks + 16 * h); sacc = MFMA32(ka, qf[ks], sacc); }
; #pragma unroll
;         for (int i = 0; i < 16; ++i) {
;             float p;
;             if (MODE == 2) p = ex2(sacc[i]);
;             else if (MODE == 3) p = ex2(sacc[i] + __int_as_float(dl));
;             else { const int ci = 32 * mt + (i & 3) + 8 * (i >> 2); p = ((unsigned)(dl - ci) < ulim) ? ex2(sacc[i]) : 0.f; }
;             sacc[i] = p; ls += p;
;         }
; #pragma unroll
;         for (int s = 0; s < 2; ++s) {
;             const bf16x8_t pf = pack8(sacc, 8 * s);
; #pragma unroll
;             for (int dt = 0; dt < 2; ++dt) {
;                 const LAS unsigned char* vp = Vb + (32 * dt + r) * A_CVSTR + (32 * mt + 16 * s + 4 * h) * 2;
;                 const s16x4_t lo = *(const LAS s16x4_t*)vp, hi = *(const LAS s16x4_t*)(vp + 16);
;                 oacc[dt] = MFMA32(__builtin_shufflevector(lo, hi, 0, 1, 2, 3, 4, 5, 6, 7), pf, oacc[dt]);
;             }
;         }
;     }
;     l_run += ls;
.Lt1_e1_nostage:
	v_add_f32_e32 v232, v232, v54
	v_add_f32_e32 v233, v233, v55
	v_cvt_pk_bf16_f32 v67, v54, v55
	s_waitcnt lgkmcnt(5)
	v_mfma_f32_32x32x16_bf16 v[32:47], v[208:211], v[88:91], v[32:47]
	v_exp_f32_e32 v56, v56
	v_exp_f32_e32 v57, v57
	s_waitcnt lgkmcnt(4)
	v_mfma_f32_32x32x16_bf16 v[32:47], v[212:215], v[92:95], v[32:47]
	v_exp_f32_e32 v58, v58
	v_exp_f32_e32 v59, v59
	v_add_f32_e32 v232, v232, v56
	v_add_f32_e32 v233, v233, v57
	v_cvt_pk_bf16_f32 v68, v56, v57
	s_waitcnt lgkmcnt(3)
	v_mfma_f32_32x32x16_bf16 v[0:15], v[216:219], v[64:67], v[0:15]
	ds_read2_b64 v[216:219], v73 offset0:24 offset1:26
	v_exp_f32_e32 v60, v60
	v_exp_f32_e32 v61, v61
	v_add_f32_e32 v232, v232, v58
	v_add_f32_e32 v233, v233, v59
	v_cvt_pk_bf16_f32 v69, v58, v59
	s_waitcnt lgkmcnt(3)
	v_mfma_f32_32x32x16_bf16 v[16:31], v[220:223], v[64:67], v[16:31]
	ds_read2_b64 v[220:223], v74 offset0:56 offset1:58
	v_exp_f32_e32 v62, v62
	v_exp_f32_e32 v63, v63
	v_add_f32_e32 v232, v232, v60
	v_add_f32_e32 v233, v233, v61
	v_cvt_pk_bf16_f32 v70, v60, v61
	v_add_f32_e32 v232, v232, v62
	v_add_f32_e32 v233, v233, v63
	v_cvt_pk_bf16_f32 v71, v62, v63
	v_exp_f32_e32 v32, v32
	v_exp_f32_e32 v33, v33
	v_exp_f32_e32 v34, v34
	v_exp_f32_e32 v35, v35
	v_add_f32_e32 v232, v232, v32
	v_add_f32_e32 v233, v233, v33
	v_cvt_pk_bf16_f32 v64, v32, v33
	s_waitcnt lgkmcnt(3)
	v_mfma_f32_32x32x16_bf16 v[0:15], v[224:227], v[68:71], v[0:15]
	ds_read2_b64 v[224:227], v73 offset0:28 offset1:30
	v_exp_f32_e32 v36, v36
	v_exp_f32_e32 v37, v37
	v_add_f32_e32 v232, v232, v34
	v_add_f32_e32 v233, v233, v35
	v_cvt_pk_bf16_f32 v65, v34, v35
	s_waitcnt lgkmcnt(3)
	v_mfma_f32_32x32x16_bf16 v[16:31], v[228:231], v[68:71], v[16:31]
	ds_read2_b64 v[228:231], v74 offset0:60 offset1:62
	v_exp_f32_e32 v38, v38
	v_exp_f32_e32 v39, v39
	v_add_f32_e32 v232, v232, v36
	v_add_f32_e32 v233, v233, v37
	v_cvt_pk_bf16_f32 v66, v36, v37
	v_add_f32_e32 v232, v232, v38
	v_add_f32_e32 v233, v233, v39
	v_cvt_pk_bf16_f32 v67, v38, v39
	v_exp_f32_e32 v40, v40
	v_exp_f32_e32 v41, v41
	v_exp_f32_e32 v42, v42
	v_exp_f32_e32 v43, v43
	v_add_f32_e32 v232, v232, v40
	v_add_f32_e32 v233, v233, v41
	v_cvt_pk_bf16_f32 v68, v40, v41
	s_waitcnt lgkmcnt(3)
	v_mfma_f32_32x32x16_bf16 v[0:15], v[216:219], v[64:67], v[0:15]
	v_exp_f32_e32 v44, v44
	v_exp_f32_e32 v45, v45
	v_add_f32_e32 v232, v232, v42
	v_add_f32_e32 v233, v233, v43
	v_cvt_pk_bf16_f32 v69, v42, v43
	s_waitcnt lgkmcnt(2)
	v_mfma_f32_32x32x16_bf16 v[16:31], v[220:223], v[64:67], v[16:31]
	v_exp_f32_e32 v46, v46
	v_exp_f32_e32 v47, v47
	v_add_f32_e32 v232, v232, v44
	v_add_f32_e32 v233, v233, v45
	v_cvt_pk_bf16_f32 v70, v44, v45
	v_add_f32_e32 v232, v232, v46
	v_add_f32_e32 v233, v233, v47
	v_cvt_pk_bf16_f32 v71, v46, v47
	s_nop 1
	s_waitcnt lgkmcnt(1)
	v_mfma_f32_32x32x16_bf16 v[0:15], v[224:227], v[68:71], v[0:15]
	s_waitcnt lgkmcnt(0)
	v_mfma_f32_32x32x16_bf16 v[16:31], v[228:231], v[68:71], v[16:31]
	v_add_f32_e32 v232, v232, v233
	v_add_f32_e32 v112, v112, v232
	s_branch .Lt1_join
.Lt1_e2:
	ds_read_b128 v[200:203], v72 offset:9216
	ds_read_b128 v[204:207], v72 offset:9248
	ds_read_b128 v[208:211], v72 offset:9280
	ds_read_b128 v[212:215], v72 offset:9312
	ds_read2_b64 v[216:219], v73 offset0:16 offset1:18
	ds_read2_b64 v[220:223], v74 offset0:48 offset1:50
	ds_read2_b64 v[224:227], v73 offset0:20 offset1:22
	ds_read2_b64 v[228:231], v74 offset0:52 offset1:54
	s_waitcnt lgkmcnt(7)
	v_mfma_f32_32x32x16_bf16 v[32:47], v[200:203], v[80:83], 0
	ds_read_b128 v[200:203], v72 offset:13824
	s_waitcnt lgkmcnt(7)
	v_mfma_f32_32x32x16_bf16 v[32:47], v[204:207], v[84:87], v[32:47]
	ds_read_b128 v[204:207], v72 offset:13856
	s_waitcnt lgkmcnt(7)
	v_mfma_f32_32x32x16_bf16 v[32:47], v[208:211], v[88:91], v[32:47]
	ds_read_b128 v[208:211], v72 offset:13888
	s_waitcnt lgkmcnt(7)
	v_mfma_f32_32x32x16_bf16 v[32:47], v[212:215], v[92:95], v[32:47]
	ds_read_b128 v[212:215], v72 offset:13920
	s_nop 7
	s_nop 3
	s_waitcnt lgkmcnt(3)
	v_mfma_f32_32x32x16_bf16 v[48:63], v[200:203], v[80:83], 0
	v_cmp_le_i32_e64 s[0:1], 0, v250
	v_cmp_le_i32_e64 s[4:5], 1, v250
	v_exp_f32_e32 v32, v32
	v_exp_f32_e32 v33, v33
	s_waitcnt lgkmcnt(2)
	v_mfma_f32_32x32x16_bf16 v[48:63], v[204:207], v[84:87], v[48:63]
	v_cmp_le_i32_e64 s[6:7], 2, v250
	v_cmp_le_i32_e64 s[48:49], 3, v250
	v_exp_f32_e32 v34, v34
	v_exp_f32_e32 v35, v35
	v_cndmask_b32_e64 v32, v32, 0, s[0:1]
	v_cndmask_b32_e64 v33, v33, 0, s[4:5]
	v_mov_b32_e32 v232, v32
	v_mov_b32_e32 v233, v33
	v_cvt_pk_bf16_f32 v64, v32, v33
	v_cmp_le_i32_e64 s[0:1], 8, v250
	v_cmp_le_i32_e64 s[4:5], 9, v250
	v_exp_f32_e32 v36, v36
	v_exp_f32_e32 v37, v37
	v_cndmask_b32_e64 v34, v34, 0, s[6:7]
	v_cndmask_b32_e64 v35, v35, 0, s[48:49]
	v_add_f32_e32 v232, v232, v34
	v_add_f32_e32 v233, v233, v35
	v_cvt_pk_bf16_f32 v65, v34, v35
	v_cmp_le_i32_e64 s[6:7], 10, v250
	v_cmp_le_i32_e64 s[48:49], 11, v250
	v_exp_f32_e32 v38, v38
	v_exp_f32_e32 v39, v39
	v_cndmask_b32_e64 v36, v36, 0, s[0:1]
	v_cndmask_b32_e64 v37, v37, 0, s[4:5]
	v_add_f32_e32 v232, v232, v36
	v_add_f32_e32 v233, v233, v37
	v_cvt_pk_bf16_f32 v66, v36, v37
	s_cmp_eq_u32 s45, 0
	s_cbranch_scc1 .Lt1_e2_nostage
	s_waitcnt vmcnt(3)
	ds_write_b128 v251, v[96:99]
	s_waitcnt vmcnt(2)
	ds_write_b128 v251, v[100:103] offset:9216
	s_waitcnt vmcnt(1)
	ds_write2_b64 v252, v[104:105], v[106:107] offset1:1
	s_waitcnt vmcnt(0)
	ds_write2_b64 v252, v[108:109], v[110:111] offset0:16 offset1:17
	s_mov_b32 s47, 1
; #define LAS __attribute__((address_space(3)))
; #define MFMA32(a, b, c) __builtin_amdgcn_mfma_f32_32x32x16_bf16((a), (b), (c), 0, 0, 0)
; __device__ __forceinline__ float ex2(float x) { return __builtin_amdgcn_exp2f(x); }
; template <int MODE>
; __device__ __forceinline__ void attn_tile(const LAS unsigned char* Kb, const LAS unsigned char* Vb, const bf16x8_t (&qf)[4], f32x16 (&oacc)[2], float& l_run,
;                                           int r, int h, int dlt0, int dlt1, bool hiw) {
;     ...
; #pragma unroll
;     for (int mt = 0; mt < 4; ++mt) {
;         if (mt == 0) { if (hiw) __builtin_amdgcn_s_setprio(1); else __builtin_amdgcn_s_setprio(0); }
;         if (mt == 2) { if (hiw) __builtin_amdgcn_s_setprio(0); else __builtin_amdgcn_s_setprio(1); }
;         const int dl = mt < 2 ? dlt0 : dlt1;
;         f32x16 sacc = zero16();
; #pragma unroll
;         for (int ks = 0; ks < 4; ++ks) { const bf16x8_t ka = *(const LAS bf16x8_t*)(Kb + (32 * mt + r) * A_KSTR + 32 * ks + 16 * h); sacc = MFMA32(ka, qf[ks], sacc); }
; #pragma unroll
;         for (int i = 0; i < 16; ++i) {
;             float p;
;             if (MODE == 2) p = ex2(sacc[i]);
;             else if (MODE == 3) p = ex2(sacc[i] + __int_as_float(dl));
;             else { const int ci = 32 * mt + (i & 3) + 8 * (i >> 2); p = ((unsigned)(dl - ci) < ulim) ? ex2(sacc[i]) : 0.f; }
;             sacc[i] = p; ls += p;
;         }
; #pragma unroll
;         for (int s = 0; s < 2; ++s) {
;             const bf16x8_t pf = pack8(sacc, 8 * s);
; #pragma unroll
;             for (int dt = 0; dt < 2; ++dt) {
;                 const LAS unsigned char* vp = Vb + (32 * dt + r) * A_CVSTR + (32 * mt + 16 * s + 4 * h) * 2;
;                 const s16x4_t lo = *(const LAS s16x4_t*)vp, hi = *(const LAS s16x4_t*)(vp + 16);
;                 oacc[dt] = MFMA32(__builtin_shufflevector(lo, hi, 0, 1, 2, 3, 4, 5, 6, 7), pf, oacc[dt]);
;             }
;         }
;     }
;     l_run += ls;
.Lt1_e2_nostage:
	v_cndmask_b32_e64 v38, v38, 0, s[6:7]
	v_cndmask_b32_e64 v39, v39, 0, s[48:49]
	v_add_f32_e32 v232, v232, v38
	v_add_f32_e32 v233, v233, v39
	v_cvt_pk_bf16_f32 v67, v38, v39
	s_waitcnt lgkmcnt(1)
	v_mfma_f32_32x32x16_bf16 v[48:63], v[208:211], v[88:91], v[48:63]
	v_cmp_le_i32_e64 s[0:1], 16, v250
	v_cmp_le_i32_e64 s[4:5], 17, v250
	v_exp_f32_e32 v40, v40
	v_exp_f32_e32 v41, v41
	s_waitcnt lgkmcnt(0)
	v_mfma_f32_32x32x16_bf16 v[48:63], v[212:215], v[92:95], v[48:63]
	v_cmp_le_i32_e64 s[6:7], 18, v250
	v_cmp_le_i32_e64 s[48:49], 19, v250
	v_exp_f32_e32 v42, v42
	v_exp_f32_e32 v43, v43
	v_cndmask_b32_e64 v40, v40, 0, s[0:1]
	v_cndmask_b32_e64 v41, v41, 0, s[4:5]
	v_add_f32_e32 v232, v232, v40
	v_add_f32_e32 v233, v233, v41
	v_cvt_pk_bf16_f32 v68, v40, v41
	v_mfma_f32_32x32x16_bf16 v[0:15], v[216:219], v[64:67], v[0:15]
	ds_read2_b64 v[216:219], v73 offset0:24 offset1:26
	v_cmp_le_i32_e64 s[0:1], 24, v250
	v_cmp_le_i32_e64 s[4:5], 25, v250
	v_exp_f32_e32 v44, v44
	v_exp_f32_e32 v45, v45
	v_cndmask_b32_e64 v42, v42, 0, s[6:7]
	v_cndmask_b32_e64 v43, v43, 0, s[48:49]
	v_add_f32_e32 v232, v232, v42
	v_add_f32_e32 v233, v233, v43
	v_cvt_pk_bf16_f32 v69, v42, v43
	v_mfma_f32_32x32x16_bf16 v[16:31], v[220:223], v[64:67], v[16:31]
	ds_read2_b64 v[220:223], v74 offset0:56 offset1:58
	v_cmp_le_i32_e64 s[6:7], 26, v250
	v_cmp_le_i32_e64 s[48:49], 27, v250
	v_exp_f32_e32 v46, v46
	v_exp_f32_e32 v47, v47
	v_cndmask_b32_e64 v44, v44, 0, s[0:1]
	v_cndmask_b32_e64 v45, v45, 0, s[4:5]
	v_add_f32_e32 v232, v232, v44
	v_add_f32_e32 v233, v233, v45
	v_cvt_pk_bf16_f32 v70, v44, v45
	v_cndmask_b32_e64 v46, v46, 0, s[6:7]
	v_cndmask_b32_e64 v47, v47, 0, s[48:49]
	v_add_f32_e32 v232, v232, v46
	v_add_f32_e32 v233, v233, v47
	v_cvt_pk_bf16_f32 v71, v46, v47
	v_exp_f32_e32 v48, v48
	v_exp_f32_e32 v49, v49
	v_exp_f32_e32 v50, v50
	v_exp_f32_e32 v51, v51
	v_add_f32_e32 v232, v232, v48
	v_add_f32_e32 v233, v233, v49
	v_cvt_pk_bf16_f32 v64, v48, v49
	v_mfma_f32_32x32x16_bf16 v[0:15], v[224:227], v[68:71], v[0:15]
	ds_read2_b64 v[224:227], v73 offset0:28 offset1:30
	v_exp_f32_e32 v52, v52
	v_exp_f32_e32 v53, v53
	v_add_f32_e32 v232, v232, v50
	v_add_f32_e32 v233, v233, v51
	v_cvt_pk_bf16_f32 v65, v50, v51
	v_mfma_f32_32x32x16_bf16 v[16:31], v[228:231], v[68:71], v[16:31]
	ds_read2_b64 v[228:231], v74 offset0:60 offset1:62
	v_exp_f32_e32 v54, v54
	v_exp_f32_e32 v55, v55
	v_add_f32_e32 v232, v232, v52
	v_add_f32_e32 v233, v233, v53
	v_cvt_pk_bf16_f32 v66, v52, v53
	v_add_f32_e32 v232, v232, v54
	v_add_f32_e32 v233, v233, v55
	v_cvt_pk_bf16_f32 v67, v54, v55
	v_exp_f32_e32 v56, v56
	v_exp_f32_e32 v57, v57
	v_exp_f32_e32 v58, v58
	v_exp_f32_e32 v59, v59
	v_add_f32_e32 v232, v232, v56
	v_add_f32_e32 v233, v233, v57
	v_cvt_pk_bf16_f32 v68, v56, v57
	s_waitcnt lgkmcnt(3)
	v_mfma_f32_32x32x16_bf16 v[0:15], v[216:219], v[64:67], v[0:15]
	v_exp_f32_e32 v60, v60
	v_exp_f32_e32 v61, v61
	v_add_f32_e32 v232, v232, v58
	v_add_f32_e32 v233, v233, v59
	v_cvt_pk_bf16_f32 v69, v58, v59
	s_waitcnt lgkmcnt(2)
	v_mfma_f32_32x32x16_bf16 v[16:31], v[220:223], v[64:67], v[16:31]
	v_exp_f32_e32 v62, v62
	v_exp_f32_e32 v63, v63
	v_add_f32_e32 v232, v232, v60
	v_add_f32_e32 v233, v233, v61
	v_cvt_pk_bf16_f32 v70, v60, v61
	v_add_f32_e32 v232, v232, v62
	v_add_f32_e32 v233, v233, v63
	v_cvt_pk_bf16_f32 v71, v62, v63
	s_nop 1
	s_waitcnt lgkmcnt(1)
	v_mfma_f32_32x32x16_bf16 v[0:15], v[224:227], v[68:71], v[0:15]
	s_waitcnt lgkmcnt(0)
	v_mfma_f32_32x32x16_bf16 v[16:31], v[228:231], v[68:71], v[16:31]
	v_add_f32_e32 v232, v232, v233
	v_add_f32_e32 v112, v112, v232
	s_branch .Lt1_join

; __device__ __forceinline__ void phase4_attn(const Args& a, LAS unsigned char* lds) {
;     ...
;                     if (i + 1 < n_all) A_STAGE(bufo ^ 1);
;                     __syncthreads();
.Lt1_stage:
	s_cmp_eq_u32 s45, 0
	s_cbranch_scc1 .Lt1_latch
	s_cmp_eq_u32 s47, 1
	s_cbranch_scc1 .Lt1_latch
	s_waitcnt vmcnt(3)
	ds_write_b128 v251, v[96:99]
	s_waitcnt vmcnt(2)
	ds_write_b128 v251, v[100:103] offset:9216
	s_waitcnt vmcnt(1)
	ds_write2_b64 v252, v[104:105], v[106:107] offset1:1
	s_waitcnt vmcnt(0)
	ds_write2_b64 v252, v[108:109], v[110:111] offset0:16 offset1:17

; #define LAS __attribute__((address_space(3)))
; __device__ __forceinline__ void phase4_attn(const Args& a, LAS unsigned char* lds) {
;     ...
;                 {
;                     const bf16_t* kc = kcmp + (size_t)bh * 128 * 64; const bf16_t* vc = vcmpT + (size_t)bh * 64 * 128;
; #pragma unroll
;                     for (int i = 0; i < 2; ++i) { const int c = tid + 512 * i;
;                         const u32x4 kv = *(const u32x4*)(kc + (size_t)c * 8);
;                         *(LAS u32x4*)(lds + A_CMPK + (c >> 3) * A_KSTR + (c & 7) * 16) = kv;
;                         const u32x4 vv = *(const u32x4*)(vc + (size_t)c * 8);
;                         LAS unsigned char* vp = lds + A_CMPV + (c >> 4) * A_CVSTR + (c & 15) * 16;
;                         *(LAS u32x2*)vp = (u32x2){vv.x, vv.y}; *(LAS u32x2*)(vp + 8) = (u32x2){vv.z, vv.w}; }
;                 }
;                 bf16x8_t qf[4];
; #pragma unroll
;                 for (int ks = 0; ks < 4; ++ks) qf[ks] = __builtin_nontemporal_load((const bf16x8_t*)(qn + (size_t)tok * 512 + head * 64 + 16 * ks + 8 * h));
;                 __syncthreads();
;                 {
;                     f32x16 s4[4];
; #pragma unroll
;                     for (int mt = 0; mt < 4; ++mt) { s4[mt] = zero16();
; #pragma unroll
;                         for (int ks = 0; ks < 4; ++ks) { const bf16x8_t ka = *(const LAS bf16x8_t*)(lds + A_CMPK + (32 * mt + r) * A_KSTR + 32 * ks + 16 * h); s4[mt] = MFMA32(ka, qf[ks], s4[mt]); } }
;                     const int clim = (pos - 31 - 64 * h) >> 4;
;                     float ls = 0.f;
; #pragma unroll
;                     for (int mt = 0; mt < 4; ++mt)
; #pragma unroll
;                         for (int i = 0; i < 16; ++i) { const int ci = 32 * mt + (i & 3) + 8 * (i >> 2);
;                             const float p = (ci <= clim) ? ex2(s4[mt][i]) : 0.f; s4[mt][i] = p; ls += p; }
;                     ls += __shfl_xor(ls, 32);
;                     const float inv = 1.f / fmaxf(ls, 1e-20f);
; #pragma unroll
;                     for (int mt = 0; mt < 4; ++mt) s4[mt] *= inv;
;                     if (t >= 16) {
;                         float oprev = 0.f;
; #pragma unroll
;                         for (int idx = 0; idx < 16; ++idx) {
;                             const int mt = idx >> 2, ap = idx & 3;
;                             const float tail = 0.5f * s4[mt][4 * ap + 3];
.LBB0_794:
	v_mov_b32_e32 v152, v184
	v_readlane_b32 s0, v254, 57
	s_waitcnt vmcnt(2)
	v_and_b32_e32 v100, 31, v152
	v_or_b32_e32 v98, s79, v100
	v_or_b32_e32 v194, s24, v98
	v_readlane_b32 s1, v254, 58
	v_or_b32_e32 v4, s39, v194
	v_ashrrev_i32_e32 v153, 31, v152
	v_mov_b64_e32 v[0:1], s[0:1]
	v_mad_i64_i32 v[0:1], s[0:1], v4, s83, v[0:1]
	global_load_dwordx3 v[112:114], v[0:1], off
	v_lshlrev_b32_e32 v0, 4, v152
	v_readlane_b32 s4, v254, 35
	v_and_b32_e32 v1, 0x70, v0
	v_and_b32_e32 v0, 0xf0, v0
	v_lshlrev_b64 v[10:11], 4, v[152:153]
	v_readlane_b32 s5, v254, 36
	v_add_u32_e32 v6, s85, v1
	v_add_u32_e32 v8, s86, v0
	v_lshl_add_u64 v[0:1], s[4:5], 0, v[10:11]
	s_nop 0
	s_barrier
	global_load_dwordx4 v[16:19], v[0:1], off
	v_add_u32_e32 v14, 0x200, v152
	v_ashrrev_i32_e32 v15, 31, v14
	v_lshlrev_b64 v[12:13], 4, v[14:15]
	v_lshl_add_u64 v[36:37], s[52:53], 0, v[10:11]
	global_load_dwordx4 v[20:23], v[36:37], off
	v_lshl_add_u64 v[36:37], s[4:5], 0, v[12:13]
	global_load_dwordx4 v[24:27], v[36:37], off
	v_lshl_add_u64 v[36:37], s[52:53], 0, v[12:13]
	global_load_dwordx4 v[28:31], v[36:37], off
	v_readlane_b32 s0, v254, 59
	v_readlane_b32 s1, v254, 60
	v_ashrrev_i32_e32 v5, 31, v4
	v_bfe_u32 v101, v152, 5, 1
	v_lshlrev_b64 v[72:73], 10, v[4:5]
	v_lshlrev_b32_e32 v118, 4, v101
	v_lshl_add_u64 v[0:1], s[0:1], 0, v[72:73]
	v_lshl_add_u64 v[4:5], v[0:1], 0, v[118:119]
	global_load_dwordx4 v[0:3], v[4:5], off nt
	global_load_dwordx4 v[74:77], v[4:5], off offset:32 nt
	global_load_dwordx4 v[68:71], v[4:5], off offset:64 nt
	global_load_dwordx4 v[64:67], v[4:5], off offset:96 nt
	v_ashrrev_i32_e32 v99, 3, v152
	v_ashrrev_i32_e32 v7, 4, v152
	v_mul_u32_u24_e32 v153, 0x90, v100
	v_add3_u32 v82, s85, v118, v153
	v_mad_u32_u24 v32, v99, s87, v6
	v_mad_u32_u24 v33, v7, s94, v8
	v_add_u32_e32 v35, 0x2100, v33
	s_waitcnt vmcnt(7)
	ds_write_b128 v32, v[16:19]
	s_waitcnt vmcnt(6)
	ds_write2_b64 v33, v[20:21], v[22:23] offset1:1
	s_waitcnt vmcnt(5)
	ds_write_b128 v32, v[24:27] offset:9216
	s_waitcnt vmcnt(4)
	ds_write2_b64 v35, v[28:29], v[30:31] offset1:1
	s_waitcnt lgkmcnt(0)
	s_barrier
	s_waitcnt vmcnt(0)
	v_mov_b32_e32 v84, v0
	v_mov_b32_e32 v85, v1
	v_mov_b32_e32 v86, v2
	v_mov_b32_e32 v87, v3
	v_lshlrev_b32_e32 v195, 2, v101
	v_lshlrev_b32_e32 v196, 3, v101
	v_mul_u32_u24_e32 v197, 0x108, v100
	v_add3_u32 v244, s86, v196, v197
	v_add_u32_e32 v245, 0x2000, v244
	v_lshlrev_b32_e32 v239, 4, v195
	v_sub_u32_e32 v236, v194, v239
	v_subrev_u32_e32 v236, 31, v236
	v_ashrrev_i32_e32 v236, 4, v236
	v_mov_b32_e32 v0, 0
	v_mov_b32_e32 v1, 0
	v_mov_b32_e32 v2, 0
	v_mov_b32_e32 v3, 0
	v_mov_b32_e32 v4, 0
	v_mov_b32_e32 v5, 0
	v_mov_b32_e32 v6, 0
	v_mov_b32_e32 v7, 0
	v_mov_b32_e32 v8, 0
	v_mov_b32_e32 v9, 0
	v_mov_b32_e32 v10, 0
	v_mov_b32_e32 v11, 0
	v_mov_b32_e32 v12, 0
	v_mov_b32_e32 v13, 0
	v_mov_b32_e32 v14, 0
	v_mov_b32_e32 v15, 0
	v_mov_b32_e32 v16, 0
	v_mov_b32_e32 v17, 0
	v_mov_b32_e32 v18, 0
	v_mov_b32_e32 v19, 0
	v_mov_b32_e32 v20, 0
	v_mov_b32_e32 v21, 0
	v_mov_b32_e32 v22, 0
	v_mov_b32_e32 v23, 0
	v_mov_b32_e32 v24, 0
	v_mov_b32_e32 v25, 0
	v_mov_b32_e32 v26, 0
	v_mov_b32_e32 v27, 0
	v_mov_b32_e32 v28, 0
	v_mov_b32_e32 v29, 0
	v_mov_b32_e32 v30, 0
	v_mov_b32_e32 v31, 0
	v_mov_b32_e32 v160, 0
	v_mov_b32_e32 v161, 0
	v_mov_b32_e32 v162, 0
	v_mov_b32_e32 v163, 0
	v_mov_b32_e32 v164, 0
	v_mov_b32_e32 v165, 0
	v_mov_b32_e32 v166, 0
	v_mov_b32_e32 v167, 0
	v_mov_b32_e32 v168, 0
	v_mov_b32_e32 v169, 0
	v_mov_b32_e32 v170, 0
	v_mov_b32_e32 v171, 0
	v_mov_b32_e32 v172, 0
	v_mov_b32_e32 v173, 0
	v_mov_b32_e32 v174, 0
	v_mov_b32_e32 v175, 0
	v_mov_b32_e32 v176, 0
	v_mov_b32_e32 v177, 0
	v_mov_b32_e32 v178, 0
	v_mov_b32_e32 v179, 0
	v_mov_b32_e32 v180, 0
	v_mov_b32_e32 v181, 0
	v_mov_b32_e32 v182, 0
	v_mov_b32_e32 v183, 0
	v_mov_b32_e32 v246, 0
	v_mov_b32_e32 v247, 0
	v_mov_b32_e32 v248, 0
	v_mov_b32_e32 v249, 0
	v_mov_b32_e32 v250, 0
	v_mov_b32_e32 v251, 0
	v_mov_b32_e32 v252, 0
	v_mov_b32_e32 v253, 0
	v_readfirstlane_b32 s7, v152
	s_bfe_u32 s7, s7, 0x10006
	s_lshl_b32 s9, s38, 1
	s_add_i32 s7, s7, s9
	s_lshr_b32 s7, s7, 4
	s_cmp_eq_u32 s7, 0
	s_cbranch_scc1 .Lc1_n1
	s_cmp_eq_u32 s7, 1
	s_cbranch_scc1 .Lc1_n2
	s_cmp_eq_u32 s7, 2
	s_cbranch_scc1 .Lc1_n3
	s_branch .Lc1_n4

; __device__ __forceinline__ void phase4_attn(const Args& a, LAS unsigned char* lds) {
;     ...
;                     ls += __shfl_xor(ls, 32);
;                     const float inv = 1.f / fmaxf(ls, 1e-20f);
; #pragma unroll
;                     for (int mt = 0; mt < 4; ++mt) s4[mt] *= inv;
;                     if (t >= 16) {
;                         float oprev = 0.f;
; #pragma unroll
;                         for (int idx = 0; idx < 16; ++idx) {
;                             const int mt = idx >> 2, ap = idx & 3;
;                             const float tail = 0.5f * s4[mt][4 * ap + 3];
;                             const float ot = __shfl_xor(tail, 32);
;                             const float inner = s4[mt][4 * ap] + s4[mt][4 * ap + 1] + s4[mt][4 * ap + 2] + tail;
;                             const float prev = h ? ot : oprev;
;                             oprev = ot;
;                             IMP[(g * 64 + ql) * A_IMPSTR + 8 * mt + 2 * ap + h] = inner + prev;
;                         }
;                     }
.Lc1_fin:
	v_add_f32_e32 v232, v232, v233
	ds_bpermute_b32 v239, v193, v232
	s_waitcnt lgkmcnt(0)
	v_add_f32_e32 v239, v232, v239
	v_max_f32_e32 v239, 0x1e3ce508, v239
	v_div_scale_f32 v240, s[44:45], v239, v239, 1.0
	v_rcp_f32_e32 v241, v240
	v_div_scale_f32 v242, vcc, 1.0, v239, 1.0
	s_nop 0
	v_fma_f32 v243, -v240, v241, 1.0
	v_fmac_f32_e32 v241, v243, v241
	v_mul_f32_e32 v243, v242, v241
	v_fma_f32 v96, -v240, v243, v242
	v_fmac_f32_e32 v243, v96, v241
	v_fma_f32 v240, -v240, v243, v242
	v_div_fmas_f32 v240, v240, v241, v243
	v_div_fixup_f32 v97, v240, v239, 1.0
	v_mul_f32_e32 v0, v0, v97
	v_mul_f32_e32 v1, v1, v97
	v_mul_f32_e32 v2, v2, v97
	v_mul_f32_e32 v3, v3, v97
	v_mul_f32_e32 v4, v4, v97
	v_mul_f32_e32 v5, v5, v97
	v_mul_f32_e32 v6, v6, v97
	v_mul_f32_e32 v7, v7, v97
	v_mul_f32_e32 v8, v8, v97
	v_mul_f32_e32 v9, v9, v97
	v_mul_f32_e32 v10, v10, v97
	v_mul_f32_e32 v11, v11, v97
	v_mul_f32_e32 v12, v12, v97
	v_mul_f32_e32 v13, v13, v97
	v_mul_f32_e32 v14, v14, v97
	v_mul_f32_e32 v15, v15, v97
	v_mul_f32_e32 v16, v16, v97
	v_mul_f32_e32 v17, v17, v97
	v_mul_f32_e32 v18, v18, v97
	v_mul_f32_e32 v19, v19, v97
	v_mul_f32_e32 v20, v20, v97
	v_mul_f32_e32 v21, v21, v97
	v_mul_f32_e32 v22, v22, v97
	v_mul_f32_e32 v23, v23, v97
	v_mul_f32_e32 v24, v24, v97
	v_mul_f32_e32 v25, v25, v97
	v_mul_f32_e32 v26, v26, v97
	v_mul_f32_e32 v27, v27, v97
	v_mul_f32_e32 v28, v28, v97
	v_mul_f32_e32 v29, v29, v97
	v_mul_f32_e32 v30, v30, v97
	v_mul_f32_e32 v31, v31, v97
	s_cmp_gt_u32 s38, 15
	s_cbranch_scc0 .Lc1_noimp
	v_cmp_ne_u32_e64 s[46:47], 0, v101
	ds_bpermute_b32 v32, v193, v176
	ds_bpermute_b32 v33, v193, v177
	ds_bpermute_b32 v34, v193, v178
	ds_bpermute_b32 v35, v193, v179
	ds_bpermute_b32 v36, v193, v180
	ds_bpermute_b32 v37, v193, v181
	ds_bpermute_b32 v38, v193, v182
	ds_bpermute_b32 v39, v193, v183
	ds_bpermute_b32 v40, v193, v246
	ds_bpermute_b32 v41, v193, v247
	ds_bpermute_b32 v42, v193, v248
	ds_bpermute_b32 v43, v193, v249
	ds_bpermute_b32 v44, v193, v250
	ds_bpermute_b32 v45, v193, v251
	ds_bpermute_b32 v46, v193, v252
	ds_bpermute_b32 v47, v193, v253
	v_lshrrev_b32_e32 v48, 7, v152
	v_lshl_or_b32 v48, v48, 6, v98
	v_mul_u32_u24_e32 v48, 0x84, v48
	v_add_u32_e32 v48, v48, v195
	v_add_u32_e32 v48, 0x19e00, v48
	s_waitcnt lgkmcnt(0)
	v_cndmask_b32_e64 v49, 0, v32, s[46:47]
	v_add_f32_e32 v49, v160, v49
	v_mul_f32_e32 v49, v49, v97
	ds_write_b32 v48, v49 offset:0
	v_cndmask_b32_e64 v50, v32, v33, s[46:47]
	v_add_f32_e32 v50, v161, v50
	v_mul_f32_e32 v50, v50, v97
	ds_write_b32 v48, v50 offset:8
	v_cndmask_b32_e64 v49, v33, v34, s[46:47]
	v_add_f32_e32 v49, v162, v49
	v_mul_f32_e32 v49, v49, v97
	ds_write_b32 v48, v49 offset:16
	v_cndmask_b32_e64 v50, v34, v35, s[46:47]
	v_add_f32_e32 v50, v163, v50
	v_mul_f32_e32 v50, v50, v97
	ds_write_b32 v48, v50 offset:24
	v_cndmask_b32_e64 v49, v35, v36, s[46:47]
	v_add_f32_e32 v49, v164, v49
	v_mul_f32_e32 v49, v49, v97
	ds_write_b32 v48, v49 offset:32
	v_cndmask_b32_e64 v50, v36, v37, s[46:47]
	v_add_f32_e32 v50, v165, v50
	v_mul_f32_e32 v50, v50, v97
	ds_write_b32 v48, v50 offset:40
	v_cndmask_b32_e64 v49, v37, v38, s[46:47]
	v_add_f32_e32 v49, v166, v49
	v_mul_f32_e32 v49, v49, v97
	ds_write_b32 v48, v49 offset:48
	v_cndmask_b32_e64 v50, v38, v39, s[46:47]
	v_add_f32_e32 v50, v167, v50
	v_mul_f32_e32 v50, v50, v97
	ds_write_b32 v48, v50 offset:56
	v_cndmask_b32_e64 v49, v39, v40, s[46:47]
	v_add_f32_e32 v49, v168, v49
	v_mul_f32_e32 v49, v49, v97
	ds_write_b32 v48, v49 offset:64
	v_cndmask_b32_e64 v50, v40, v41, s[46:47]
	v_add_f32_e32 v50, v169, v50
	v_mul_f32_e32 v50, v50, v97
	ds_write_b32 v48, v50 offset:72
	v_cndmask_b32_e64 v49, v41, v42, s[46:47]
	v_add_f32_e32 v49, v170, v49
	v_mul_f32_e32 v49, v49, v97
	ds_write_b32 v48, v49 offset:80
	v_cndmask_b32_e64 v50, v42, v43, s[46:47]
	v_add_f32_e32 v50, v171, v50
	v_mul_f32_e32 v50, v50, v97
	ds_write_b32 v48, v50 offset:88
	v_cndmask_b32_e64 v49, v43, v44, s[46:47]
	v_add_f32_e32 v49, v172, v49
	v_mul_f32_e32 v49, v49, v97
	ds_write_b32 v48, v49 offset:96
	v_cndmask_b32_e64 v50, v44, v45, s[46:47]
	v_add_f32_e32 v50, v173, v50
	v_mul_f32_e32 v50, v50, v97
	ds_write_b32 v48, v50 offset:104
	v_cndmask_b32_e64 v49, v45, v46, s[46:47]
	v_add_f32_e32 v49, v174, v49
	v_mul_f32_e32 v49, v49, v97
	ds_write_b32 v48, v49 offset:112
	v_cndmask_b32_e64 v50, v46, v47, s[46:47]
	v_add_f32_e32 v50, v175, v50
	v_mul_f32_e32 v50, v50, v97
	ds_write_b32 v48, v50 offset:120
; #define LAS __attribute__((address_space(3)))
; __device__ __forceinline__ void phase4_attn(const Args& a, LAS unsigned char* lds) {
;     ...
;                 if (t >= 16) {
;                     __syncthreads();
;                     const int qloc = tid >> 3, jg = tid & 7;
;                     unsigned bits = 0u;
;                     float xe[4]; int cnt[4];
; #pragma unroll
;                     for (int e = 0; e < 4; ++e) { const int j = 4 * jg + e; const LAS float* ip = IMP + qloc * A_IMPSTR + j;
;                         float x = (ip[0] + ip[64 * A_IMPSTR]) + (ip[128 * A_IMPSTR] + ip[192 * A_IMPSTR]);
;                         if (j == 0 || j == t || j == t - 1) x = 1e9f;
;                         if (j > t) x = -INFINITY;
;                         xe[e] = x; cnt[e] = 0; }
; #pragma unroll 4
;                     for (int i = 0; i < 32; ++i) { const LAS float* ip = IMP + qloc * A_IMPSTR + i;
;                         float vi = (ip[0] + ip[64 * A_IMPSTR]) + (ip[128 * A_IMPSTR] + ip[192 * A_IMPSTR]);
;                         if (i == 0 || i == t || i == t - 1) vi = 1e9f;
;                         if (i > t) vi = -INFINITY;
; #pragma unroll
;                         for (int e = 0; e < 4; ++e) cnt[e] += (vi > xe[e] || (vi == xe[e] && i < 4 * jg + e)) ? 1 : 0; }
; #pragma unroll
;                     for (int e = 0; e < 4; ++e) if (cnt[e] < 16 && xe[e] > -INFINITY) bits |= 1u << (4 * jg + e);
;                     bits |= __shfl_xor(bits, 1); bits |= __shfl_xor(bits, 2); bits |= __shfl_xor(bits, 4);
;                     if (jg == 0) SELM[qloc] = bits;
;                     __syncthreads();
;                 }
;                 const unsigned selw = (t >= 16) ? SELM[ql] : ((2u << t) - 1u);
; #pragma unroll
;                 for (int ks = 0; ks < 4; ++ks) qf[ks] = __builtin_nontemporal_load((const bf16x8_t*)(qr + (size_t)tok * 512 + head * 64 + 16 * ks + 8 * h));
;                 const int kt_lo = t >= 8 ? t - 8 : 0, wlo = kt_lo >> 1, n_sel = (t >> 1) + 1, n_all = n_sel + ((t >> 1) - wlo + 1);
.Lc1_noimp:
	s_waitcnt lgkmcnt(0)
	v_mov_b32_e32 v198, s30
	s_and_b64 vcc, exec, s[2:3]
	s_cbranch_vccnz .LBB0_804
	s_movk_i32 s0, 0x84
	v_mul_lo_u32 v50, v99, s0
	v_readlane_b32 s0, v254, 28
	v_and_b32_e32 v33, 7, v152
	s_nop 0
	v_add_u32_e32 v46, s0, v50
	v_lshl_add_u32 v32, v33, 4, v46
	v_add_u32_e32 v40, 0x2100, v32
	v_add_u32_e32 v36, 0x4200, v32
	v_add_u32_e32 v38, 0x6300, v32
	s_barrier
	ds_read2_b32 v[34:35], v32 offset1:1
	ds_read2_b32 v[36:37], v36 offset1:1
	ds_read2_b32 v[38:39], v38 offset1:1
	ds_read2_b32 v[40:41], v40 offset1:1
	v_lshlrev_b32_e32 v32, 2, v33
	s_waitcnt lgkmcnt(3)
	v_mov_b32_e32 v42, v34
	s_waitcnt lgkmcnt(2)
	v_mov_b32_e32 v43, v36
	s_waitcnt lgkmcnt(1)
	v_mov_b32_e32 v45, v38
	s_waitcnt lgkmcnt(0)
	v_mov_b32_e32 v44, v40
	v_cmp_eq_u32_e32 vcc, 0, v33
	v_cmp_eq_u32_e64 s[0:1], s38, v32
	v_pk_add_f32 v[42:43], v[42:43], v[44:45]
	s_or_b64 s[2:3], vcc, s[0:1]
	v_cmp_eq_u32_e64 s[0:1], s80, v32
	v_add_f32_e32 v34, v42, v43
	s_or_b64 s[0:1], s[2:3], s[0:1]
	v_cndmask_b32_e64 v33, v34, v190, s[0:1]
	v_cmp_ge_u32_e64 s[0:1], s38, v32
	v_mov_b32_e32 v36, v35
	v_mov_b32_e32 v38, v41
	v_cndmask_b32_e64 v34, v191, v33, s[0:1]
	v_or_b32_e32 v33, 1, v32
	v_pk_add_f32 v[36:37], v[36:37], v[38:39]
	v_cmp_eq_u32_e64 s[0:1], s38, v33
	v_cmp_eq_u32_e64 s[2:3], s80, v33
	v_add_f32_e32 v35, v36, v37
	s_or_b64 s[0:1], s[0:1], s[2:3]
	v_or_b32_e32 v38, 2, v32
	v_cndmask_b32_e64 v33, v35, v190, s[0:1]
	v_lshl_add_u32 v35, v38, 2, v46
	v_add_u32_e32 v36, 0x2100, v35
	v_add_u32_e32 v37, 0x4200, v35
	v_add_u32_e32 v39, 0x6300, v35
	ds_read2_b32 v[40:41], v35 offset1:1
	ds_read2_b32 v[44:45], v36 offset1:1
	ds_read2_b32 v[46:47], v37 offset1:1
	ds_read2_b32 v[48:49], v39 offset1:1
	v_cmp_gt_u32_e64 s[0:1], s38, v32
	v_or_b32_e32 v42, 3, v32
	s_waitcnt lgkmcnt(2)
	v_pk_add_f32 v[40:41], v[40:41], v[44:45]
	v_cndmask_b32_e64 v36, v191, v33, s[0:1]
	s_waitcnt lgkmcnt(0)
	v_pk_add_f32 v[44:45], v[46:47], v[48:49]
	v_cmp_eq_u32_e64 s[0:1], s38, v38
	v_cmp_eq_u32_e64 s[4:5], s80, v38
	v_pk_add_f32 v[40:41], v[40:41], v[44:45]
	v_cmp_eq_u32_e64 s[2:3], s38, v42
	v_cmp_eq_u32_e64 s[6:7], s80, v42
	s_or_b64 s[0:1], s[0:1], s[4:5]
	v_cndmask_b32_e64 v37, v40, v190, s[0:1]
	s_or_b64 s[0:1], s[2:3], s[6:7]
	v_cndmask_b32_e64 v33, v41, v190, s[0:1]
	v_cmp_ge_u32_e64 s[0:1], s38, v42
	s_mov_b32 s30, 0
	s_mov_b32 s42, 1
	v_cndmask_b32_e64 v33, v191, v33, s[0:1]
	v_cmp_ge_u32_e64 s[0:1], s38, v38
	v_mov_b32_e32 v35, v32
	s_mov_b32 s43, s38
	v_cndmask_b32_e64 v40, v191, v37, s[0:1]
	s_mov_b32 s44, s80
	v_mov_b32_e32 v37, v34
	v_mov_b32_e32 v39, v36
	v_mov_b32_e32 v41, v38
	v_mov_b32_e32 v44, v40
	v_mov_b32_e32 v43, v40
	v_mov_b32_e32 v45, v42
	v_mov_b32_e32 v46, v33
	v_mov_b32_e32 v47, v33
	v_add_u32_e32 v48, 0, v50
	v_mov_b32_e32 v49, 0
	v_mov_b32_e32 v50, 0
	v_mov_b32_e32 v51, 0
	v_mov_b32_e32 v52, 0
	v_mov_b32_e32 v53, 0
	v_mov_b32_e32 v54, 0
	v_mov_b32_e32 v55, 0
	v_mov_b32_e32 v56, 0
	s_mov_b32 s45, 0

; #define LAS __attribute__((address_space(3)))
; #define MFMA32(a, b, c) __builtin_amdgcn_mfma_f32_32x32x16_bf16((a), (b), (c), 0, 0, 0)
; __device__ __forceinline__ float ex2(float x) { return __builtin_amdgcn_exp2f(x); }
; template <int MODE>
; __device__ __forceinline__ void attn_tile(const LAS unsigned char* Kb, const LAS unsigned char* Vb, const bf16x8_t (&qf)[4], f32x16 (&oacc)[2], float& l_run,
;                                           int r, int h, int dlt0, int dlt1, bool hiw) {
;     ...
; #pragma unroll
;     for (int mt = 0; mt < 4; ++mt) {
;         if (mt == 0) { if (hiw) __builtin_amdgcn_s_setprio(1); else __builtin_amdgcn_s_setprio(0); }
;         if (mt == 2) { if (hiw) __builtin_amdgcn_s_setprio(0); else __builtin_amdgcn_s_setprio(1); }
;         const int dl = mt < 2 ? dlt0 : dlt1;
;         f32x16 sacc = zero16();
; #pragma unroll
;         for (int ks = 0; ks < 4; ++ks) { const bf16x8_t ka = *(const LAS bf16x8_t*)(Kb + (32 * mt + r) * A_KSTR + 32 * ks + 16 * h); sacc = MFMA32(ka, qf[ks], sacc); }
; #pragma unroll
;         for (int i = 0; i < 16; ++i) {
;             float p;
;             if (MODE == 2) p = ex2(sacc[i]);
;             else if (MODE == 3) p = ex2(sacc[i] + __int_as_float(dl));
;             else { const int ci = 32 * mt + (i & 3) + 8 * (i >> 2); p = ((unsigned)(dl - ci) < ulim) ? ex2(sacc[i]) : 0.f; }
;             sacc[i] = p; ls += p;
;         }
; #pragma unroll
;         for (int s = 0; s < 2; ++s) {
;             const bf16x8_t pf = pack8(sacc, 8 * s);
; #pragma unroll
;             for (int dt = 0; dt < 2; ++dt) {
;                 const LAS unsigned char* vp = Vb + (32 * dt + r) * A_CVSTR + (32 * mt + 16 * s + 4 * h) * 2;
;                 const s16x4_t lo = *(const LAS s16x4_t*)vp, hi = *(const LAS s16x4_t*)(vp + 16);
;                 oacc[dt] = MFMA32(__builtin_shufflevector(lo, hi, 0, 1, 2, 3, 4, 5, 6, 7), pf, oacc[dt]);
;             }
;         }
;     }
;     l_run += ls;
.Lt2_bias:
	ds_read_b128 v[200:203], v72 offset:0
	ds_read_b128 v[204:207], v72 offset:32
	ds_read_b128 v[208:211], v72 offset:64
	ds_read_b128 v[212:215], v72 offset:96
	ds_read2_b64 v[216:219], v73 offset0:0 offset1:2
	ds_read2_b64 v[220:223], v74 offset0:32 offset1:34
	ds_read2_b64 v[224:227], v73 offset0:4 offset1:6
	ds_read2_b64 v[228:231], v74 offset0:36 offset1:38
	v_bfe_i32 v236, v198, s49, 1
	s_add_i32 s49, s49, 1
	v_bfe_i32 v237, v198, s49, 1
	s_waitcnt lgkmcnt(7)
	v_mfma_f32_32x32x16_bf16 v[32:47], v[200:203], v[80:83], 0
	ds_read_b128 v[200:203], v72 offset:4608
	s_waitcnt lgkmcnt(7)
	v_mfma_f32_32x32x16_bf16 v[32:47], v[204:207], v[84:87], v[32:47]
	ds_read_b128 v[204:207], v72 offset:4640
	s_waitcnt lgkmcnt(7)
	v_mfma_f32_32x32x16_bf16 v[32:47], v[208:211], v[88:91], v[32:47]
	ds_read_b128 v[208:211], v72 offset:4672
	s_waitcnt lgkmcnt(7)
	v_mfma_f32_32x32x16_bf16 v[32:47], v[212:215], v[92:95], v[32:47]
	ds_read_b128 v[212:215], v72 offset:4704
	s_nop 7
	s_nop 3
	s_waitcnt lgkmcnt(3)
	v_mfma_f32_32x32x16_bf16 v[48:63], v[200:203], v[80:83], 0
	ds_read_b128 v[200:203], v72 offset:9216
	v_exp_f32_e32 v32, v32
	v_exp_f32_e32 v33, v33
	s_waitcnt lgkmcnt(3)
	v_mfma_f32_32x32x16_bf16 v[48:63], v[204:207], v[84:87], v[48:63]
	ds_read_b128 v[204:207], v72 offset:9248
	v_exp_f32_e32 v34, v34
	v_exp_f32_e32 v35, v35
	v_mov_b32_e32 v232, v32
	v_mov_b32_e32 v233, v33
	v_cvt_pk_bf16_f32 v64, v32, v33
	v_and_b32_e32 v64, v236, v64
	v_exp_f32_e32 v36, v36
	v_exp_f32_e32 v37, v37
	v_add_f32_e32 v232, v232, v34
	v_add_f32_e32 v233, v233, v35
	v_cvt_pk_bf16_f32 v65, v34, v35
	v_and_b32_e32 v65, v236, v65
	v_exp_f32_e32 v38, v38
	v_exp_f32_e32 v39, v39
	v_add_f32_e32 v232, v232, v36
	v_add_f32_e32 v233, v233, v37
	v_cvt_pk_bf16_f32 v66, v36, v37
	v_and_b32_e32 v66, v236, v66
	v_add_f32_e32 v232, v232, v38
	v_add_f32_e32 v233, v233, v39
	v_cvt_pk_bf16_f32 v67, v38, v39
	v_and_b32_e32 v67, v236, v67
	s_waitcnt lgkmcnt(3)
	v_mfma_f32_32x32x16_bf16 v[48:63], v[208:211], v[88:91], v[48:63]
	ds_read_b128 v[208:211], v72 offset:9280
	v_exp_f32_e32 v40, v40
	v_exp_f32_e32 v41, v41
	s_waitcnt lgkmcnt(3)
	v_mfma_f32_32x32x16_bf16 v[48:63], v[212:215], v[92:95], v[48:63]
	ds_read_b128 v[212:215], v72 offset:9312
	v_exp_f32_e32 v42, v42
	v_exp_f32_e32 v43, v43
	v_add_f32_e32 v232, v232, v40
	v_add_f32_e32 v233, v233, v41
	v_cvt_pk_bf16_f32 v68, v40, v41
	v_and_b32_e32 v68, v236, v68
	v_mfma_f32_32x32x16_bf16 v[0:15], v[216:219], v[64:67], v[0:15]
	ds_read2_b64 v[216:219], v73 offset0:8 offset1:10
	v_exp_f32_e32 v44, v44
	v_exp_f32_e32 v45, v45
	v_add_f32_e32 v232, v232, v42
	v_add_f32_e32 v233, v233, v43
	v_cvt_pk_bf16_f32 v69, v42, v43
	v_and_b32_e32 v69, v236, v69
	v_mfma_f32_32x32x16_bf16 v[16:31], v[220:223], v[64:67], v[16:31]
	ds_read2_b64 v[220:223], v74 offset0:40 offset1:42
	v_exp_f32_e32 v46, v46
	v_exp_f32_e32 v47, v47
	v_add_f32_e32 v232, v232, v44
	v_add_f32_e32 v233, v233, v45
	v_cvt_pk_bf16_f32 v70, v44, v45
	v_and_b32_e32 v70, v236, v70
	v_add_f32_e32 v232, v232, v46
	v_add_f32_e32 v233, v233, v47
	v_cvt_pk_bf16_f32 v71, v46, v47
	v_and_b32_e32 v71, v236, v71
	s_waitcnt lgkmcnt(5)
	v_mfma_f32_32x32x16_bf16 v[32:47], v[200:203], v[80:83], 0
	ds_read_b128 v[200:203], v72 offset:13824
	v_exp_f32_e32 v48, v48
	v_exp_f32_e32 v49, v49
	s_waitcnt lgkmcnt(5)
	v_mfma_f32_32x32x16_bf16 v[32:47], v[204:207], v[84:87], v[32:47]
	ds_read_b128 v[204:207], v72 offset:13856
	v_exp_f32_e32 v50, v50
	v_exp_f32_e32 v51, v51
	v_add_f32_e32 v232, v232, v48
	v_add_f32_e32 v233, v233, v49
	v_cvt_pk_bf16_f32 v64, v48, v49
	v_and_b32_e32 v64, v236, v64
	v_mfma_f32_32x32x16_bf16 v[0:15], v[224:227], v[68:71], v[0:15]
	ds_read2_b64 v[224:227], v73 offset0:12 offset1:14
	v_exp_f32_e32 v52, v52
	v_exp_f32_e32 v53, v53
	v_add_f32_e32 v232, v232, v50
	v_add_f32_e32 v233, v233, v51
	v_cvt_pk_bf16_f32 v65, v50, v51
	v_and_b32_e32 v65, v236, v65
	v_mfma_f32_32x32x16_bf16 v[16:31], v[228:231], v[68:71], v[16:31]
	ds_read2_b64 v[228:231], v74 offset0:44 offset1:46
	v_exp_f32_e32 v54, v54
	v_exp_f32_e32 v55, v55
	v_add_f32_e32 v232, v232, v52
	v_add_f32_e32 v233, v233, v53
	v_cvt_pk_bf16_f32 v66, v52, v53
	v_and_b32_e32 v66, v236, v66
	v_add_f32_e32 v232, v232, v54
	v_add_f32_e32 v233, v233, v55
	v_cvt_pk_bf16_f32 v67, v54, v55
	v_and_b32_e32 v67, v236, v67
	s_waitcnt lgkmcnt(7)
	v_mfma_f32_32x32x16_bf16 v[32:47], v[208:211], v[88:91], v[32:47]
	ds_read_b128 v[208:211], v72 offset:13888
	v_exp_f32_e32 v56, v56
	v_exp_f32_e32 v57, v57
	s_waitcnt lgkmcnt(7)
	v_mfma_f32_32x32x16_bf16 v[32:47], v[212:215], v[92:95], v[32:47]
	ds_read_b128 v[212:215], v72 offset:13920
	v_exp_f32_e32 v58, v58
	v_exp_f32_e32 v59, v59
	v_add_f32_e32 v232, v232, v56
	v_add_f32_e32 v233, v233, v57
	v_cvt_pk_bf16_f32 v68, v56, v57
	v_and_b32_e32 v68, v236, v68
	s_waitcnt lgkmcnt(7)
	v_mfma_f32_32x32x16_bf16 v[0:15], v[216:219], v[64:67], v[0:15]
	ds_read2_b64 v[216:219], v73 offset0:16 offset1:18
	v_exp_f32_e32 v60, v60
	v_exp_f32_e32 v61, v61
	v_add_f32_e32 v232, v232, v58
	v_add_f32_e32 v233, v233, v59
	v_cvt_pk_bf16_f32 v69, v58, v59
	v_and_b32_e32 v69, v236, v69
	s_waitcnt lgkmcnt(7)
	v_mfma_f32_32x32x16_bf16 v[16:31], v[220:223], v[64:67], v[16:31]
	ds_read2_b64 v[220:223], v74 offset0:48 offset1:50
	v_exp_f32_e32 v62, v62
	v_exp_f32_e32 v63, v63
	v_add_f32_e32 v232, v232, v60
	v_add_f32_e32 v233, v233, v61
	v_cvt_pk_bf16_f32 v70, v60, v61
	v_and_b32_e32 v70, v236, v70
	v_add_f32_e32 v232, v232, v62
	v_add_f32_e32 v233, v233, v63
	v_cvt_pk_bf16_f32 v71, v62, v63
	v_and_b32_e32 v71, v236, v71
	s_waitcnt lgkmcnt(7)
	v_mfma_f32_32x32x16_bf16 v[48:63], v[200:203], v[80:83], 0
	v_exp_f32_e32 v32, v32
	v_exp_f32_e32 v33, v33
	s_waitcnt lgkmcnt(6)
	v_mfma_f32_32x32x16_bf16 v[48:63], v[204:207], v[84:87], v[48:63]
	v_exp_f32_e32 v34, v34
	v_exp_f32_e32 v35, v35
	v_mov_b32_e32 v234, v32
	v_mov_b32_e32 v235, v33
	v_cvt_pk_bf16_f32 v64, v32, v33
	v_and_b32_e32 v64, v237, v64
	s_waitcnt lgkmcnt(5)
	v_mfma_f32_32x32x16_bf16 v[0:15], v[224:227], v[68:71], v[0:15]
	ds_read2_b64 v[224:227], v73 offset0:20 offset1:22
	v_exp_f32_e32 v36, v36
	v_exp_f32_e32 v37, v37
	v_add_f32_e32 v234, v234, v34
	v_add_f32_e32 v235, v235, v35
	v_cvt_pk_bf16_f32 v65, v34, v35
	v_and_b32_e32 v65, v237, v65
	s_waitcnt lgkmcnt(5)
	v_mfma_f32_32x32x16_bf16 v[16:31], v[228:231], v[68:71], v[16:31]
	ds_read2_b64 v[228:231], v74 offset0:52 offset1:54
	v_exp_f32_e32 v38, v38
	v_exp_f32_e32 v39, v39
	v_add_f32_e32 v234, v234, v36
	v_add_f32_e32 v235, v235, v37
	v_cvt_pk_bf16_f32 v66, v36, v37
	v_and_b32_e32 v66, v237, v66
	s_cmp_eq_u32 s45, 0
	s_cbranch_scc1 .Lt2_bias_nostage
	s_waitcnt vmcnt(3)
	ds_write_b128 v251, v[96:99]
	s_waitcnt vmcnt(2)
	ds_write_b128 v251, v[100:103] offset:9216
	s_waitcnt vmcnt(1)
	ds_write2_b64 v252, v[104:105], v[106:107] offset1:1
	s_waitcnt vmcnt(0)
	ds_write2_b64 v252, v[108:109], v[110:111] offset0:16 offset1:17
	s_mov_b32 s47, 1
